# k-loop load stages: m0 wait states filled with the stage's own ds_reads; every m0 write now at least one instruction ahead of its LDS-DMA load (hazard fix)
# baseline (speedup 1.0000x reference)
; #define PG8_STAGE(bufoff, gbase, voff) do { _Pragma("unroll") for (int _i = 0; _i < 2; ++_i) \
;         __builtin_amdgcn_global_load_lds((const unsigned*)((const char*)(gbase) + (voff)[_i]), (PG8_LAS unsigned*)(lds + (bufoff) + ldsw + _i * 8192), 16, 0, 0); } while (0)
; #define PG8_LDA(dst, b, h) do { _Pragma("unroll") for (int m = 0; m < 4; ++m) _Pragma("unroll") for (int k = 0; k < 2; ++k) dst[m][k] = *(const PG8_LAS bf16x8*)(lds + PG8_SA(b, h) + aoff + m * 2048 + k * 1024); } while (0)
; #define PG8_LDB(dst, b, h) do { _Pragma("unroll") for (int n = 0; n < 2; ++n) _Pragma("unroll") for (int k = 0; k < 2; ++k) dst[n][k] = *(const PG8_LAS bf16x8*)(lds + PG8_SB(b, h) + boff + n * 2048 + k * 1024); } while (0)
; #define PG8_MMA(ai, bj, At, Bt) do { __builtin_amdgcn_s_setprio(1); _Pragma("unroll") for (int m = 0; m < 4; ++m) _Pragma("unroll") for (int n = 0; n < 2; ++n) _Pragma("unroll") for (int k = 0; k < 2; ++k) \
;         acc[ai][bj][m][n] = __builtin_amdgcn_mfma_f32_16x16x32_bf16(Bt[n][k], At[m][k], acc[ai][bj][m][n], 0, 0, 0); __builtin_amdgcn_s_setprio(0); } while (0)
; #define PG8_WAIT_V(n) asm volatile("s_waitcnt vmcnt(" #n ")" ::: "memory")
; #define PG8_WAIT_L(n) asm volatile("s_waitcnt lgkmcnt(" #n ")" ::: "memory")
; template <class Epi, class Sched, bool ALIGN_EPI = false, bool SP2 = false>
; __device__ __forceinline__ void gemm_phase(PG8_LAS unsigned char* lds, const Gemm g, const Sched& S, const Epi& E) {
;     ...
;             const bool last = (t == nt - 2);
;             const char* a1 = cA + (size_t)(t + 1) * kstep;
;             const char* a2 = last ? nA : cA + (size_t)(t + 2) * kstep; const char* b2 = last ? nB : cB + (size_t)(t + 2) * kstep;
;             const char* a3 = a2 + kstep; const char* b3 = b2 + kstep;
;             if (last && has_next) S.a_ready(nxt);
;             if constexpr (SP2) {
;             PG8_LDB(B0, 0, 0); PG8_LDB(B1, 0, 1); PG8_SCHED; PG8_LDA(At, 0, 0); PG8_STAGE(PG8_SA(1, 1), a1 + hstep, voffA);
;             PG8_WAIT_V(8); PG8_WAIT_L(0); PG8_BAR; PG8_MMA(0, 0, At, B0); PG8_MMA(0, 1, At, B1); PG8_BAR; PG8_SCHED;
;             PG8_LDA(At, 0, 1); PG8_STAGE(PG8_SB(0, 0), b2, voffB); PG8_STAGE(PG8_SB(0, 1), b2 + hstep, voffB); PG8_STAGE(PG8_SA(0, 0), a2, voffA);
;             PG8_WAIT_V(8); PG8_WAIT_L(0); PG8_BAR; PG8_MMA(1, 0, At, B0); PG8_MMA(1, 1, At, B1); PG8_BAR; PG8_SCHED;
.LBB0_218:
	ds_read_b128 v[148:151], v157
	ds_read_b128 v[166:169], v157 offset:1024
	ds_read_b128 v[172:175], v157 offset:2048
	ds_read_b128 v[176:179], v157 offset:3072
	ds_read_b128 v[180:183], v158
	ds_read_b128 v[184:187], v158 offset:1024
	ds_read_b128 v[188:191], v158 offset:2048
	ds_read_b128 v[196:199], v158 offset:3072
	s_add_u32 s6, s52, 0xfffc0080
	s_addc_u32 s7, s53, -1
	s_cmp_eq_u32 s72, 12
	s_cselect_b32 s57, s4, s7
	s_cselect_b32 s56, s41, s6
	s_cselect_b32 s55, s39, s33
	s_cselect_b32 s54, s78, s79
	s_add_i32 m0, s37, 0xc000
	ds_read_b128 v[200:203], v159
	ds_read_b128 v[204:207], v159 offset:1024
	ds_read_b128 v[208:211], v159 offset:2048
	ds_read_b128 v[212:215], v159 offset:3072
	ds_read_b128 v[216:219], v159 offset:4096
	ds_read_b128 v[220:223], v159 offset:5120
	ds_read_b128 v[224:227], v159 offset:6144
	global_load_lds_dwordx4 v140, s[52:53]
	s_add_i32 m0, s37, 0xe000
	ds_read_b128 v[228:231], v159 offset:7168
	global_load_lds_dwordx4 v142, s[52:53]
	s_waitcnt vmcnt(8)
	s_waitcnt lgkmcnt(0)
	s_barrier
	s_waitcnt lgkmcnt(0)
	v_mfma_f32_16x16x32_bf16 v[124:127], v[148:151], v[200:203], v[124:127]
	v_mfma_f32_16x16x32_bf16 v[116:119], v[172:175], v[200:203], v[116:119]
	v_mfma_f32_16x16x32_bf16 v[108:111], v[148:151], v[208:211], v[108:111]
	v_mfma_f32_16x16x32_bf16 v[100:103], v[172:175], v[208:211], v[100:103]
	v_mfma_f32_16x16x32_bf16 v[92:95], v[148:151], v[216:219], v[92:95]
	v_mfma_f32_16x16x32_bf16 v[84:87], v[172:175], v[216:219], v[84:87]
	v_mfma_f32_16x16x32_bf16 v[76:79], v[148:151], v[224:227], v[76:79]
	v_mfma_f32_16x16x32_bf16 v[68:71], v[172:175], v[224:227], v[68:71]
	v_mfma_f32_16x16x32_bf16 v[124:127], v[166:169], v[204:207], v[124:127]
	v_mfma_f32_16x16x32_bf16 v[116:119], v[176:179], v[204:207], v[116:119]
	v_mfma_f32_16x16x32_bf16 v[108:111], v[166:169], v[212:215], v[108:111]
	v_mfma_f32_16x16x32_bf16 v[100:103], v[176:179], v[212:215], v[100:103]
	v_mfma_f32_16x16x32_bf16 v[92:95], v[166:169], v[220:223], v[92:95]
	v_mfma_f32_16x16x32_bf16 v[84:87], v[176:179], v[220:223], v[84:87]
	v_mfma_f32_16x16x32_bf16 v[76:79], v[166:169], v[228:231], v[76:79]
	v_mfma_f32_16x16x32_bf16 v[68:71], v[176:179], v[228:231], v[68:71]
	v_mfma_f32_16x16x32_bf16 v[120:123], v[180:183], v[200:203], v[120:123]
	v_mfma_f32_16x16x32_bf16 v[112:115], v[188:191], v[200:203], v[112:115]
	v_mfma_f32_16x16x32_bf16 v[104:107], v[180:183], v[208:211], v[104:107]
	v_mfma_f32_16x16x32_bf16 v[96:99], v[188:191], v[208:211], v[96:99]
	v_mfma_f32_16x16x32_bf16 v[88:91], v[180:183], v[216:219], v[88:91]
	v_mfma_f32_16x16x32_bf16 v[80:83], v[188:191], v[216:219], v[80:83]
	v_mfma_f32_16x16x32_bf16 v[72:75], v[180:183], v[224:227], v[72:75]
	v_mfma_f32_16x16x32_bf16 v[64:67], v[188:191], v[224:227], v[64:67]
	v_mfma_f32_16x16x32_bf16 v[120:123], v[184:187], v[204:207], v[120:123]
	v_mfma_f32_16x16x32_bf16 v[112:115], v[196:199], v[204:207], v[112:115]
	v_mfma_f32_16x16x32_bf16 v[104:107], v[184:187], v[212:215], v[104:107]
	v_mfma_f32_16x16x32_bf16 v[96:99], v[196:199], v[212:215], v[96:99]
	v_mfma_f32_16x16x32_bf16 v[88:91], v[184:187], v[220:223], v[88:91]
	v_mfma_f32_16x16x32_bf16 v[80:83], v[196:199], v[220:223], v[80:83]
	v_mfma_f32_16x16x32_bf16 v[72:75], v[184:187], v[228:231], v[72:75]
	v_mfma_f32_16x16x32_bf16 v[64:67], v[196:199], v[228:231], v[64:67]
	s_barrier
	s_add_i32 s6, s69, s36
	s_mov_b32 m0, s6
	ds_read_b128 v[200:203], v159 offset:16384
	ds_read_b128 v[204:207], v159 offset:17408
	ds_read_b128 v[208:211], v159 offset:18432
	ds_read_b128 v[212:215], v159 offset:19456
	ds_read_b128 v[216:219], v159 offset:20480
	global_load_lds_dwordx4 v136, s[54:55]
	s_add_i32 m0, s6, 0x2000
	s_add_u32 s6, s54, 0x40000
	s_addc_u32 s7, s55, 0
	s_add_i32 s73, s74, s36
	global_load_lds_dwordx4 v132, s[54:55]
	s_mov_b32 m0, s73
	s_nop 0
	global_load_lds_dwordx4 v136, s[6:7]
	s_add_i32 m0, s73, 0x2000
	ds_read_b128 v[228:231], v159 offset:23552
	global_load_lds_dwordx4 v132, s[6:7]
	s_mov_b32 m0, s37
	ds_read_b128 v[224:227], v159 offset:22528
	global_load_lds_dwordx4 v138, s[56:57]
	s_mov_b32 m0, s59
	ds_read_b128 v[220:223], v159 offset:21504
	global_load_lds_dwordx4 v134, s[56:57]
	s_waitcnt vmcnt(8)
	s_waitcnt lgkmcnt(0)
	s_barrier
	s_waitcnt lgkmcnt(0)
	v_mfma_f32_16x16x32_bf16 v[60:63], v[148:151], v[200:203], v[60:63]
	v_mfma_f32_16x16x32_bf16 v[52:55], v[172:175], v[200:203], v[52:55]
	v_mfma_f32_16x16x32_bf16 v[44:47], v[148:151], v[208:211], v[44:47]
	v_mfma_f32_16x16x32_bf16 v[36:39], v[172:175], v[208:211], v[36:39]
	v_mfma_f32_16x16x32_bf16 v[28:31], v[148:151], v[216:219], v[28:31]
	v_mfma_f32_16x16x32_bf16 v[20:23], v[172:175], v[216:219], v[20:23]
	v_mfma_f32_16x16x32_bf16 v[12:15], v[148:151], v[224:227], v[12:15]
	v_mfma_f32_16x16x32_bf16 v[4:7], v[172:175], v[224:227], v[4:7]
	v_mfma_f32_16x16x32_bf16 v[60:63], v[166:169], v[204:207], v[60:63]
	v_mfma_f32_16x16x32_bf16 v[52:55], v[176:179], v[204:207], v[52:55]
	v_mfma_f32_16x16x32_bf16 v[44:47], v[166:169], v[212:215], v[44:47]
	v_mfma_f32_16x16x32_bf16 v[36:39], v[176:179], v[212:215], v[36:39]
	v_mfma_f32_16x16x32_bf16 v[28:31], v[166:169], v[220:223], v[28:31]
	v_mfma_f32_16x16x32_bf16 v[20:23], v[176:179], v[220:223], v[20:23]
	v_mfma_f32_16x16x32_bf16 v[12:15], v[166:169], v[228:231], v[12:15]
	v_mfma_f32_16x16x32_bf16 v[4:7], v[176:179], v[228:231], v[4:7]
	v_mfma_f32_16x16x32_bf16 v[56:59], v[180:183], v[200:203], v[56:59]
	v_mfma_f32_16x16x32_bf16 v[48:51], v[188:191], v[200:203], v[48:51]
	v_mfma_f32_16x16x32_bf16 v[40:43], v[180:183], v[208:211], v[40:43]
	v_mfma_f32_16x16x32_bf16 v[32:35], v[188:191], v[208:211], v[32:35]
	v_mfma_f32_16x16x32_bf16 v[24:27], v[180:183], v[216:219], v[24:27]
	v_mfma_f32_16x16x32_bf16 v[16:19], v[188:191], v[216:219], v[16:19]
	v_mfma_f32_16x16x32_bf16 v[8:11], v[180:183], v[224:227], v[8:11]
	v_mfma_f32_16x16x32_bf16 v[0:3], v[188:191], v[224:227], v[0:3]
	v_mfma_f32_16x16x32_bf16 v[56:59], v[184:187], v[204:207], v[56:59]
	v_mfma_f32_16x16x32_bf16 v[48:51], v[196:199], v[204:207], v[48:51]
	v_mfma_f32_16x16x32_bf16 v[40:43], v[184:187], v[212:215], v[40:43]
	v_mfma_f32_16x16x32_bf16 v[32:35], v[196:199], v[212:215], v[32:35]
	v_mfma_f32_16x16x32_bf16 v[24:27], v[184:187], v[220:223], v[24:27]
	v_mfma_f32_16x16x32_bf16 v[16:19], v[196:199], v[220:223], v[16:19]
	v_mfma_f32_16x16x32_bf16 v[8:11], v[184:187], v[228:231], v[8:11]
	v_mfma_f32_16x16x32_bf16 v[0:3], v[196:199], v[228:231], v[0:3]
	s_barrier
; #define PG8_STAGE(bufoff, gbase, voff) do { _Pragma("unroll") for (int _i = 0; _i < 2; ++_i) \
;         __builtin_amdgcn_global_load_lds((const unsigned*)((const char*)(gbase) + (voff)[_i]), (PG8_LAS unsigned*)(lds + (bufoff) + ldsw + _i * 8192), 16, 0, 0); } while (0)
; #define PG8_LDA(dst, b, h) do { _Pragma("unroll") for (int m = 0; m < 4; ++m) _Pragma("unroll") for (int k = 0; k < 2; ++k) dst[m][k] = *(const PG8_LAS bf16x8*)(lds + PG8_SA(b, h) + aoff + m * 2048 + k * 1024); } while (0)
; #define PG8_LDB(dst, b, h) do { _Pragma("unroll") for (int n = 0; n < 2; ++n) _Pragma("unroll") for (int k = 0; k < 2; ++k) dst[n][k] = *(const PG8_LAS bf16x8*)(lds + PG8_SB(b, h) + boff + n * 2048 + k * 1024); } while (0)
; #define PG8_MMA(ai, bj, At, Bt) do { __builtin_amdgcn_s_setprio(1); _Pragma("unroll") for (int m = 0; m < 4; ++m) _Pragma("unroll") for (int n = 0; n < 2; ++n) _Pragma("unroll") for (int k = 0; k < 2; ++k) \
;         acc[ai][bj][m][n] = __builtin_amdgcn_mfma_f32_16x16x32_bf16(Bt[n][k], At[m][k], acc[ai][bj][m][n], 0, 0, 0); __builtin_amdgcn_s_setprio(0); } while (0)
; #define PG8_WAIT_V(n) asm volatile("s_waitcnt vmcnt(" #n ")" ::: "memory")
; #define PG8_WAIT_L(n) asm volatile("s_waitcnt lgkmcnt(" #n ")" ::: "memory")
; #define PG8_BAR __builtin_amdgcn_s_barrier()
; #define PG8_SCHED __builtin_amdgcn_sched_barrier(0)
; template <class Epi, class Sched, bool ALIGN_EPI = false, bool SP2 = false>
; __device__ __forceinline__ void gemm_phase(PG8_LAS unsigned char* lds, const Gemm g, const Sched& S, const Epi& E) {
;     ...
;             PG8_LDB(B0, 1, 0); PG8_LDB(B1, 1, 1); PG8_SCHED; PG8_LDA(At, 1, 0); PG8_STAGE(PG8_SA(0, 1), a2 + hstep, voffA);
;             PG8_WAIT_V(8); PG8_WAIT_L(0); PG8_BAR; PG8_MMA(0, 0, At, B0); PG8_MMA(0, 1, At, B1); PG8_BAR; PG8_SCHED;
;             PG8_LDA(At, 1, 1); PG8_STAGE(PG8_SB(1, 0), b3, voffB); PG8_STAGE(PG8_SB(1, 1), b3 + hstep, voffB); PG8_STAGE(PG8_SA(1, 0), a3, voffA);
;             PG8_WAIT_V(8); PG8_WAIT_L(0); PG8_BAR; PG8_MMA(1, 0, At, B0); PG8_MMA(1, 1, At, B1); PG8_BAR; PG8_SCHED;
	s_add_i32 s73, 0, 0x18000
	v_add_u32_e32 v161, s73, v154
	s_add_i32 s80, 0, 0x1c000
	ds_read_b128 v[148:151], v161
	ds_read_b128 v[166:169], v161 offset:1024
	ds_read_b128 v[172:175], v161 offset:2048
	ds_read_b128 v[176:179], v161 offset:3072
	v_add_u32_e32 v161, s80, v154
	ds_read_b128 v[180:183], v161
	ds_read_b128 v[184:187], v161 offset:1024
	ds_read_b128 v[188:191], v161 offset:2048
	ds_read_b128 v[196:199], v161 offset:3072
	s_add_u32 s6, s56, 0x40000
	s_addc_u32 s7, s57, 0
	s_mov_b32 m0, s60
	ds_read_b128 v[200:203], v159 offset:32768
	ds_read_b128 v[204:207], v159 offset:33792
	ds_read_b128 v[208:211], v159 offset:34816
	ds_read_b128 v[212:215], v159 offset:35840
	ds_read_b128 v[216:219], v159 offset:36864
	ds_read_b128 v[220:223], v159 offset:37888
	ds_read_b128 v[224:227], v159 offset:38912
	global_load_lds_dwordx4 v138, s[6:7]
	s_mov_b32 m0, s61
	ds_read_b128 v[228:231], v159 offset:39936
	global_load_lds_dwordx4 v134, s[6:7]
	s_waitcnt vmcnt(8)
	s_waitcnt lgkmcnt(0)
	s_barrier
	s_waitcnt lgkmcnt(0)
	v_mfma_f32_16x16x32_bf16 v[124:127], v[148:151], v[200:203], v[124:127]
	v_mfma_f32_16x16x32_bf16 v[116:119], v[172:175], v[200:203], v[116:119]
	v_mfma_f32_16x16x32_bf16 v[108:111], v[148:151], v[208:211], v[108:111]
	v_mfma_f32_16x16x32_bf16 v[100:103], v[172:175], v[208:211], v[100:103]
	v_mfma_f32_16x16x32_bf16 v[92:95], v[148:151], v[216:219], v[92:95]
	v_mfma_f32_16x16x32_bf16 v[84:87], v[172:175], v[216:219], v[84:87]
	v_mfma_f32_16x16x32_bf16 v[76:79], v[148:151], v[224:227], v[76:79]
	v_mfma_f32_16x16x32_bf16 v[68:71], v[172:175], v[224:227], v[68:71]
	v_mfma_f32_16x16x32_bf16 v[124:127], v[166:169], v[204:207], v[124:127]
	v_mfma_f32_16x16x32_bf16 v[116:119], v[176:179], v[204:207], v[116:119]
	v_mfma_f32_16x16x32_bf16 v[108:111], v[166:169], v[212:215], v[108:111]
	v_mfma_f32_16x16x32_bf16 v[100:103], v[176:179], v[212:215], v[100:103]
	v_mfma_f32_16x16x32_bf16 v[92:95], v[166:169], v[220:223], v[92:95]
	v_mfma_f32_16x16x32_bf16 v[84:87], v[176:179], v[220:223], v[84:87]
	v_mfma_f32_16x16x32_bf16 v[76:79], v[166:169], v[228:231], v[76:79]
	v_mfma_f32_16x16x32_bf16 v[68:71], v[176:179], v[228:231], v[68:71]
	v_mfma_f32_16x16x32_bf16 v[120:123], v[180:183], v[200:203], v[120:123]
	v_mfma_f32_16x16x32_bf16 v[112:115], v[188:191], v[200:203], v[112:115]
	v_mfma_f32_16x16x32_bf16 v[104:107], v[180:183], v[208:211], v[104:107]
	v_mfma_f32_16x16x32_bf16 v[96:99], v[188:191], v[208:211], v[96:99]
	v_mfma_f32_16x16x32_bf16 v[88:91], v[180:183], v[216:219], v[88:91]
	v_mfma_f32_16x16x32_bf16 v[80:83], v[188:191], v[216:219], v[80:83]
	v_mfma_f32_16x16x32_bf16 v[72:75], v[180:183], v[224:227], v[72:75]
	v_mfma_f32_16x16x32_bf16 v[64:67], v[188:191], v[224:227], v[64:67]
	v_mfma_f32_16x16x32_bf16 v[120:123], v[184:187], v[204:207], v[120:123]
	v_mfma_f32_16x16x32_bf16 v[112:115], v[196:199], v[204:207], v[112:115]
	v_mfma_f32_16x16x32_bf16 v[104:107], v[184:187], v[212:215], v[104:107]
	v_mfma_f32_16x16x32_bf16 v[96:99], v[196:199], v[212:215], v[96:99]
	v_mfma_f32_16x16x32_bf16 v[88:91], v[184:187], v[220:223], v[88:91]
	v_mfma_f32_16x16x32_bf16 v[80:83], v[196:199], v[220:223], v[80:83]
	v_mfma_f32_16x16x32_bf16 v[72:75], v[184:187], v[228:231], v[72:75]
	v_mfma_f32_16x16x32_bf16 v[64:67], v[196:199], v[228:231], v[64:67]
	s_barrier
	s_add_i32 s6, s73, s36
	s_add_u32 s98, s54, 0x80
	s_addc_u32 s99, s55, 0
	s_add_u32 s100, s56, 0x80
	s_addc_u32 s101, s57, 0
	s_mov_b32 m0, s6
	ds_read_b128 v[200:203], v159 offset:49152
	ds_read_b128 v[204:207], v159 offset:50176
	ds_read_b128 v[208:211], v159 offset:51200
	ds_read_b128 v[212:215], v159 offset:52224
	global_load_lds_dwordx4 v136, s[98:99]
	s_add_i32 m0, s6, 0x2000
	s_add_u32 s6, s54, 0x40080
	s_addc_u32 s7, s55, 0
	s_add_i32 s54, s80, s36
	global_load_lds_dwordx4 v132, s[98:99]
	s_mov_b32 m0, s54
	ds_read_b128 v[228:231], v159 offset:56320
	global_load_lds_dwordx4 v136, s[6:7]
	s_add_i32 m0, s54, 0x2000
	ds_read_b128 v[224:227], v159 offset:55296
	global_load_lds_dwordx4 v132, s[6:7]
	s_mov_b32 m0, s67
	ds_read_b128 v[220:223], v159 offset:54272
	global_load_lds_dwordx4 v138, s[100:101]
	s_mov_b32 m0, s68
	ds_read_b128 v[216:219], v159 offset:53248
	global_load_lds_dwordx4 v134, s[100:101]
	s_waitcnt vmcnt(8)
	s_waitcnt lgkmcnt(0)
	s_barrier
	s_waitcnt lgkmcnt(0)
	v_mfma_f32_16x16x32_bf16 v[60:63], v[148:151], v[200:203], v[60:63]
	v_mfma_f32_16x16x32_bf16 v[52:55], v[172:175], v[200:203], v[52:55]
	v_mfma_f32_16x16x32_bf16 v[44:47], v[148:151], v[208:211], v[44:47]
	v_mfma_f32_16x16x32_bf16 v[36:39], v[172:175], v[208:211], v[36:39]
	v_mfma_f32_16x16x32_bf16 v[28:31], v[148:151], v[216:219], v[28:31]
	v_mfma_f32_16x16x32_bf16 v[20:23], v[172:175], v[216:219], v[20:23]
	v_mfma_f32_16x16x32_bf16 v[12:15], v[148:151], v[224:227], v[12:15]
	v_mfma_f32_16x16x32_bf16 v[4:7], v[172:175], v[224:227], v[4:7]
	v_mfma_f32_16x16x32_bf16 v[60:63], v[166:169], v[204:207], v[60:63]
	v_mfma_f32_16x16x32_bf16 v[52:55], v[176:179], v[204:207], v[52:55]
	v_mfma_f32_16x16x32_bf16 v[44:47], v[166:169], v[212:215], v[44:47]
	v_mfma_f32_16x16x32_bf16 v[36:39], v[176:179], v[212:215], v[36:39]
	v_mfma_f32_16x16x32_bf16 v[28:31], v[166:169], v[220:223], v[28:31]
	v_mfma_f32_16x16x32_bf16 v[20:23], v[176:179], v[220:223], v[20:23]
	v_mfma_f32_16x16x32_bf16 v[12:15], v[166:169], v[228:231], v[12:15]
	v_mfma_f32_16x16x32_bf16 v[4:7], v[176:179], v[228:231], v[4:7]
	v_mfma_f32_16x16x32_bf16 v[56:59], v[180:183], v[200:203], v[56:59]
	v_mfma_f32_16x16x32_bf16 v[48:51], v[188:191], v[200:203], v[48:51]
	v_mfma_f32_16x16x32_bf16 v[40:43], v[180:183], v[208:211], v[40:43]
	v_mfma_f32_16x16x32_bf16 v[32:35], v[188:191], v[208:211], v[32:35]
	v_mfma_f32_16x16x32_bf16 v[24:27], v[180:183], v[216:219], v[24:27]
	v_mfma_f32_16x16x32_bf16 v[16:19], v[188:191], v[216:219], v[16:19]
	v_mfma_f32_16x16x32_bf16 v[8:11], v[180:183], v[224:227], v[8:11]
	v_mfma_f32_16x16x32_bf16 v[0:3], v[188:191], v[224:227], v[0:3]
	v_mfma_f32_16x16x32_bf16 v[56:59], v[184:187], v[204:207], v[56:59]
	v_mfma_f32_16x16x32_bf16 v[48:51], v[196:199], v[204:207], v[48:51]
	v_mfma_f32_16x16x32_bf16 v[40:43], v[184:187], v[212:215], v[40:43]
	v_mfma_f32_16x16x32_bf16 v[32:35], v[196:199], v[212:215], v[32:35]
	v_mfma_f32_16x16x32_bf16 v[24:27], v[184:187], v[220:223], v[24:27]
	v_mfma_f32_16x16x32_bf16 v[16:19], v[196:199], v[220:223], v[16:19]
	v_mfma_f32_16x16x32_bf16 v[8:11], v[184:187], v[228:231], v[8:11]
	v_mfma_f32_16x16x32_bf16 v[0:3], v[196:199], v[228:231], v[0:3]
	s_barrier
	s_add_i32 s72, s72, 2
	s_add_u32 s52, s52, 0x100
	s_addc_u32 s53, s53, 0
	s_add_u32 s79, s79, 0x100
	s_addc_u32 s33, s33, 0
	s_cmp_gt_u32 s72, 13
	s_cbranch_scc0 .LBB0_218
	s_and_b64 vcc, exec, s[34:35]
	s_cbranch_vccz .LBB0_221
	s_barrier

; #define PG8_STAGE(bufoff, gbase, voff) do { _Pragma("unroll") for (int _i = 0; _i < 2; ++_i) \
;         __builtin_amdgcn_global_load_lds((const unsigned*)((const char*)(gbase) + (voff)[_i]), (PG8_LAS unsigned*)(lds + (bufoff) + ldsw + _i * 8192), 16, 0, 0); } while (0)
; #define PG8_LDA(dst, b, h) do { _Pragma("unroll") for (int m = 0; m < 4; ++m) _Pragma("unroll") for (int k = 0; k < 2; ++k) dst[m][k] = *(const PG8_LAS bf16x8*)(lds + PG8_SA(b, h) + aoff + m * 2048 + k * 1024); } while (0)
; #define PG8_LDB(dst, b, h) do { _Pragma("unroll") for (int n = 0; n < 2; ++n) _Pragma("unroll") for (int k = 0; k < 2; ++k) dst[n][k] = *(const PG8_LAS bf16x8*)(lds + PG8_SB(b, h) + boff + n * 2048 + k * 1024); } while (0)
; #define PG8_MMA(ai, bj, At, Bt) do { __builtin_amdgcn_s_setprio(1); _Pragma("unroll") for (int m = 0; m < 4; ++m) _Pragma("unroll") for (int n = 0; n < 2; ++n) _Pragma("unroll") for (int k = 0; k < 2; ++k) \
;         acc[ai][bj][m][n] = __builtin_amdgcn_mfma_f32_16x16x32_bf16(Bt[n][k], At[m][k], acc[ai][bj][m][n], 0, 0, 0); __builtin_amdgcn_s_setprio(0); } while (0)
; #define PG8_WAIT_V(n) asm volatile("s_waitcnt vmcnt(" #n ")" ::: "memory")
; #define PG8_WAIT_L(n) asm volatile("s_waitcnt lgkmcnt(" #n ")" ::: "memory")
; template <class Epi, class Sched, bool ALIGN_EPI = false, bool SP2 = false>
; __device__ __forceinline__ void gemm_phase(PG8_LAS unsigned char* lds, const Gemm g, const Sched& S, const Epi& E) {
;     ...
;             const bool last = (t == nt - 2);
;             const char* a1 = cA + (size_t)(t + 1) * kstep;
;             const char* a2 = last ? nA : cA + (size_t)(t + 2) * kstep; const char* b2 = last ? nB : cB + (size_t)(t + 2) * kstep;
;             const char* a3 = a2 + kstep; const char* b3 = b2 + kstep;
;             if (last && has_next) S.a_ready(nxt);
;             if constexpr (SP2) {
;             PG8_LDB(B0, 0, 0); PG8_LDB(B1, 0, 1); PG8_SCHED; PG8_LDA(At, 0, 0); PG8_STAGE(PG8_SA(1, 1), a1 + hstep, voffA);
;             PG8_WAIT_V(8); PG8_WAIT_L(0); PG8_BAR; PG8_MMA(0, 0, At, B0); PG8_MMA(0, 1, At, B1); PG8_BAR; PG8_SCHED;
;             PG8_LDA(At, 0, 1); PG8_STAGE(PG8_SB(0, 0), b2, voffB); PG8_STAGE(PG8_SB(0, 1), b2 + hstep, voffB); PG8_STAGE(PG8_SA(0, 0), a2, voffA);
;             PG8_WAIT_V(8); PG8_WAIT_L(0); PG8_BAR; PG8_MMA(1, 0, At, B0); PG8_MMA(1, 1, At, B1); PG8_BAR; PG8_SCHED;
.LBB0_323:
	ds_read_b128 v[148:151], v156
	ds_read_b128 v[166:169], v156 offset:1024
	ds_read_b128 v[172:175], v156 offset:2048
	ds_read_b128 v[176:179], v156 offset:3072
	ds_read_b128 v[180:183], v157
	ds_read_b128 v[184:187], v157 offset:1024
	ds_read_b128 v[188:191], v157 offset:2048
	ds_read_b128 v[196:199], v157 offset:3072
	s_add_u32 s56, s54, 0x100
	s_addc_u32 s57, s55, 0
	s_cmp_eq_u32 s69, 40
	s_cselect_b32 s61, s51, s57
	s_cselect_b32 s60, s50, s56
	s_cselect_b32 s59, s53, s33
	s_cselect_b32 s58, s52, s4
	s_add_i32 m0, s37, 0xc000
	ds_read_b128 v[200:203], v158
	ds_read_b128 v[204:207], v158 offset:1024
	ds_read_b128 v[208:211], v158 offset:2048
	ds_read_b128 v[212:215], v158 offset:3072
	ds_read_b128 v[216:219], v158 offset:4096
	ds_read_b128 v[220:223], v158 offset:5120
	ds_read_b128 v[224:227], v158 offset:6144
	global_load_lds_dwordx4 v140, s[54:55]
	s_add_i32 m0, s37, 0xe000
	ds_read_b128 v[228:231], v158 offset:7168
	global_load_lds_dwordx4 v142, s[54:55]
	s_waitcnt vmcnt(8)
	s_waitcnt lgkmcnt(0)
	s_barrier
	s_waitcnt lgkmcnt(0)
	v_mfma_f32_16x16x32_bf16 v[124:127], v[148:151], v[200:203], v[124:127]
	v_mfma_f32_16x16x32_bf16 v[120:123], v[172:175], v[200:203], v[120:123]
	v_mfma_f32_16x16x32_bf16 v[108:111], v[148:151], v[208:211], v[108:111]
	v_mfma_f32_16x16x32_bf16 v[104:107], v[172:175], v[208:211], v[104:107]
	v_mfma_f32_16x16x32_bf16 v[92:95], v[148:151], v[216:219], v[92:95]
	v_mfma_f32_16x16x32_bf16 v[88:91], v[172:175], v[216:219], v[88:91]
	v_mfma_f32_16x16x32_bf16 v[76:79], v[148:151], v[224:227], v[76:79]
	v_mfma_f32_16x16x32_bf16 v[72:75], v[172:175], v[224:227], v[72:75]
	v_mfma_f32_16x16x32_bf16 v[124:127], v[166:169], v[204:207], v[124:127]
	v_mfma_f32_16x16x32_bf16 v[120:123], v[176:179], v[204:207], v[120:123]
	v_mfma_f32_16x16x32_bf16 v[108:111], v[166:169], v[212:215], v[108:111]
	v_mfma_f32_16x16x32_bf16 v[104:107], v[176:179], v[212:215], v[104:107]
	v_mfma_f32_16x16x32_bf16 v[92:95], v[166:169], v[220:223], v[92:95]
	v_mfma_f32_16x16x32_bf16 v[88:91], v[176:179], v[220:223], v[88:91]
	v_mfma_f32_16x16x32_bf16 v[76:79], v[166:169], v[228:231], v[76:79]
	v_mfma_f32_16x16x32_bf16 v[72:75], v[176:179], v[228:231], v[72:75]
	v_mfma_f32_16x16x32_bf16 v[116:119], v[180:183], v[200:203], v[116:119]
	v_mfma_f32_16x16x32_bf16 v[112:115], v[188:191], v[200:203], v[112:115]
	v_mfma_f32_16x16x32_bf16 v[100:103], v[180:183], v[208:211], v[100:103]
	v_mfma_f32_16x16x32_bf16 v[96:99], v[188:191], v[208:211], v[96:99]
	v_mfma_f32_16x16x32_bf16 v[84:87], v[180:183], v[216:219], v[84:87]
	v_mfma_f32_16x16x32_bf16 v[80:83], v[188:191], v[216:219], v[80:83]
	v_mfma_f32_16x16x32_bf16 v[68:71], v[180:183], v[224:227], v[68:71]
	v_mfma_f32_16x16x32_bf16 v[64:67], v[188:191], v[224:227], v[64:67]
	v_mfma_f32_16x16x32_bf16 v[116:119], v[184:187], v[204:207], v[116:119]
	v_mfma_f32_16x16x32_bf16 v[112:115], v[196:199], v[204:207], v[112:115]
	v_mfma_f32_16x16x32_bf16 v[100:103], v[184:187], v[212:215], v[100:103]
	v_mfma_f32_16x16x32_bf16 v[96:99], v[196:199], v[212:215], v[96:99]
	v_mfma_f32_16x16x32_bf16 v[84:87], v[184:187], v[220:223], v[84:87]
	v_mfma_f32_16x16x32_bf16 v[80:83], v[196:199], v[220:223], v[80:83]
	v_mfma_f32_16x16x32_bf16 v[68:71], v[184:187], v[228:231], v[68:71]
	v_mfma_f32_16x16x32_bf16 v[64:67], v[196:199], v[228:231], v[64:67]
	s_barrier
	s_add_i32 s6, s74, s36
	s_mov_b32 m0, s6
	ds_read_b128 v[200:203], v158 offset:16384
	ds_read_b128 v[204:207], v158 offset:17408
	ds_read_b128 v[208:211], v158 offset:18432
	ds_read_b128 v[212:215], v158 offset:19456
	ds_read_b128 v[216:219], v158 offset:20480
	global_load_lds_dwordx4 v134, s[58:59]
	s_add_i32 m0, s6, 0x2000
	s_add_u32 s54, s58, 0xb0000
	s_addc_u32 s55, s59, 0
	s_add_i32 s6, s75, s36
	global_load_lds_dwordx4 v138, s[58:59]
	s_mov_b32 m0, s6
	s_nop 0
	global_load_lds_dwordx4 v134, s[54:55]
	s_add_i32 m0, s6, 0x2000
	ds_read_b128 v[228:231], v158 offset:23552
	global_load_lds_dwordx4 v138, s[54:55]
	s_mov_b32 m0, s37
	ds_read_b128 v[224:227], v158 offset:22528
	global_load_lds_dwordx4 v132, s[60:61]
	s_mov_b32 m0, s30
	ds_read_b128 v[220:223], v158 offset:21504
	global_load_lds_dwordx4 v136, s[60:61]
	s_waitcnt vmcnt(8)
	s_waitcnt lgkmcnt(0)
	s_barrier
	s_waitcnt lgkmcnt(0)
	v_mfma_f32_16x16x32_bf16 v[60:63], v[148:151], v[200:203], v[60:63]
	v_mfma_f32_16x16x32_bf16 v[56:59], v[172:175], v[200:203], v[56:59]
	v_mfma_f32_16x16x32_bf16 v[44:47], v[148:151], v[208:211], v[44:47]
	v_mfma_f32_16x16x32_bf16 v[40:43], v[172:175], v[208:211], v[40:43]
	v_mfma_f32_16x16x32_bf16 v[28:31], v[148:151], v[216:219], v[28:31]
	v_mfma_f32_16x16x32_bf16 v[24:27], v[172:175], v[216:219], v[24:27]
	v_mfma_f32_16x16x32_bf16 v[12:15], v[148:151], v[224:227], v[12:15]
	v_mfma_f32_16x16x32_bf16 v[8:11], v[172:175], v[224:227], v[8:11]
	v_mfma_f32_16x16x32_bf16 v[60:63], v[166:169], v[204:207], v[60:63]
	v_mfma_f32_16x16x32_bf16 v[56:59], v[176:179], v[204:207], v[56:59]
	v_mfma_f32_16x16x32_bf16 v[44:47], v[166:169], v[212:215], v[44:47]
	v_mfma_f32_16x16x32_bf16 v[40:43], v[176:179], v[212:215], v[40:43]
	v_mfma_f32_16x16x32_bf16 v[28:31], v[166:169], v[220:223], v[28:31]
	v_mfma_f32_16x16x32_bf16 v[24:27], v[176:179], v[220:223], v[24:27]
	v_mfma_f32_16x16x32_bf16 v[12:15], v[166:169], v[228:231], v[12:15]
	v_mfma_f32_16x16x32_bf16 v[8:11], v[176:179], v[228:231], v[8:11]
	v_mfma_f32_16x16x32_bf16 v[52:55], v[180:183], v[200:203], v[52:55]
	v_mfma_f32_16x16x32_bf16 v[48:51], v[188:191], v[200:203], v[48:51]
	v_mfma_f32_16x16x32_bf16 v[36:39], v[180:183], v[208:211], v[36:39]
	v_mfma_f32_16x16x32_bf16 v[32:35], v[188:191], v[208:211], v[32:35]
	v_mfma_f32_16x16x32_bf16 v[20:23], v[180:183], v[216:219], v[20:23]
	v_mfma_f32_16x16x32_bf16 v[16:19], v[188:191], v[216:219], v[16:19]
	v_mfma_f32_16x16x32_bf16 v[4:7], v[180:183], v[224:227], v[4:7]
	v_mfma_f32_16x16x32_bf16 v[0:3], v[188:191], v[224:227], v[0:3]
	v_mfma_f32_16x16x32_bf16 v[52:55], v[184:187], v[204:207], v[52:55]
	v_mfma_f32_16x16x32_bf16 v[48:51], v[196:199], v[204:207], v[48:51]
	v_mfma_f32_16x16x32_bf16 v[36:39], v[184:187], v[212:215], v[36:39]
	v_mfma_f32_16x16x32_bf16 v[32:35], v[196:199], v[212:215], v[32:35]
	v_mfma_f32_16x16x32_bf16 v[20:23], v[184:187], v[220:223], v[20:23]
	v_mfma_f32_16x16x32_bf16 v[16:19], v[196:199], v[220:223], v[16:19]
	v_mfma_f32_16x16x32_bf16 v[4:7], v[184:187], v[228:231], v[4:7]
	v_mfma_f32_16x16x32_bf16 v[0:3], v[196:199], v[228:231], v[0:3]
	s_barrier
; #define PG8_STAGE(bufoff, gbase, voff) do { _Pragma("unroll") for (int _i = 0; _i < 2; ++_i) \
;         __builtin_amdgcn_global_load_lds((const unsigned*)((const char*)(gbase) + (voff)[_i]), (PG8_LAS unsigned*)(lds + (bufoff) + ldsw + _i * 8192), 16, 0, 0); } while (0)
; #define PG8_LDA(dst, b, h) do { _Pragma("unroll") for (int m = 0; m < 4; ++m) _Pragma("unroll") for (int k = 0; k < 2; ++k) dst[m][k] = *(const PG8_LAS bf16x8*)(lds + PG8_SA(b, h) + aoff + m * 2048 + k * 1024); } while (0)
; #define PG8_LDB(dst, b, h) do { _Pragma("unroll") for (int n = 0; n < 2; ++n) _Pragma("unroll") for (int k = 0; k < 2; ++k) dst[n][k] = *(const PG8_LAS bf16x8*)(lds + PG8_SB(b, h) + boff + n * 2048 + k * 1024); } while (0)
; #define PG8_MMA(ai, bj, At, Bt) do { __builtin_amdgcn_s_setprio(1); _Pragma("unroll") for (int m = 0; m < 4; ++m) _Pragma("unroll") for (int n = 0; n < 2; ++n) _Pragma("unroll") for (int k = 0; k < 2; ++k) \
;         acc[ai][bj][m][n] = __builtin_amdgcn_mfma_f32_16x16x32_bf16(Bt[n][k], At[m][k], acc[ai][bj][m][n], 0, 0, 0); __builtin_amdgcn_s_setprio(0); } while (0)
; #define PG8_WAIT_V(n) asm volatile("s_waitcnt vmcnt(" #n ")" ::: "memory")
; #define PG8_WAIT_L(n) asm volatile("s_waitcnt lgkmcnt(" #n ")" ::: "memory")
; #define PG8_BAR __builtin_amdgcn_s_barrier()
; #define PG8_SCHED __builtin_amdgcn_sched_barrier(0)
; template <class Epi, class Sched, bool ALIGN_EPI = false, bool SP2 = false>
; __device__ __forceinline__ void gemm_phase(PG8_LAS unsigned char* lds, const Gemm g, const Sched& S, const Epi& E) {
;     ...
;             PG8_LDB(B0, 1, 0); PG8_LDB(B1, 1, 1); PG8_SCHED; PG8_LDA(At, 1, 0); PG8_STAGE(PG8_SA(0, 1), a2 + hstep, voffA);
;             PG8_WAIT_V(8); PG8_WAIT_L(0); PG8_BAR; PG8_MMA(0, 0, At, B0); PG8_MMA(0, 1, At, B1); PG8_BAR; PG8_SCHED;
;             PG8_LDA(At, 1, 1); PG8_STAGE(PG8_SB(1, 0), b3, voffB); PG8_STAGE(PG8_SB(1, 1), b3 + hstep, voffB); PG8_STAGE(PG8_SA(1, 0), a3, voffA);
;             PG8_WAIT_V(8); PG8_WAIT_L(0); PG8_BAR; PG8_MMA(1, 0, At, B0); PG8_MMA(1, 1, At, B1); PG8_BAR; PG8_SCHED;
	s_add_i32 s6, 0, 0x18000
	v_add_u32_e32 v161, s6, v154
	s_add_i32 s7, 0, 0x1c000
	ds_read_b128 v[148:151], v161
	ds_read_b128 v[166:169], v161 offset:1024
	ds_read_b128 v[172:175], v161 offset:2048
	ds_read_b128 v[176:179], v161 offset:3072
	v_add_u32_e32 v161, s7, v154
	ds_read_b128 v[180:183], v161
	ds_read_b128 v[184:187], v161 offset:1024
	ds_read_b128 v[188:191], v161 offset:2048
	ds_read_b128 v[196:199], v161 offset:3072
	s_add_u32 s54, s60, 0xb0000
	s_addc_u32 s55, s61, 0
	s_mov_b32 m0, s31
	ds_read_b128 v[200:203], v158 offset:32768
	ds_read_b128 v[204:207], v158 offset:33792
	ds_read_b128 v[208:211], v158 offset:34816
	ds_read_b128 v[212:215], v158 offset:35840
	ds_read_b128 v[216:219], v158 offset:36864
	ds_read_b128 v[220:223], v158 offset:37888
	ds_read_b128 v[224:227], v158 offset:38912
	global_load_lds_dwordx4 v132, s[54:55]
	s_mov_b32 m0, s76
	ds_read_b128 v[228:231], v158 offset:39936
	global_load_lds_dwordx4 v136, s[54:55]
	s_waitcnt vmcnt(8)
	s_waitcnt lgkmcnt(0)
	s_barrier
	s_waitcnt lgkmcnt(0)
	v_mfma_f32_16x16x32_bf16 v[124:127], v[148:151], v[200:203], v[124:127]
	v_mfma_f32_16x16x32_bf16 v[120:123], v[172:175], v[200:203], v[120:123]
	v_mfma_f32_16x16x32_bf16 v[108:111], v[148:151], v[208:211], v[108:111]
	v_mfma_f32_16x16x32_bf16 v[104:107], v[172:175], v[208:211], v[104:107]
	v_mfma_f32_16x16x32_bf16 v[92:95], v[148:151], v[216:219], v[92:95]
	v_mfma_f32_16x16x32_bf16 v[88:91], v[172:175], v[216:219], v[88:91]
	v_mfma_f32_16x16x32_bf16 v[76:79], v[148:151], v[224:227], v[76:79]
	v_mfma_f32_16x16x32_bf16 v[72:75], v[172:175], v[224:227], v[72:75]
	v_mfma_f32_16x16x32_bf16 v[124:127], v[166:169], v[204:207], v[124:127]
	v_mfma_f32_16x16x32_bf16 v[120:123], v[176:179], v[204:207], v[120:123]
	v_mfma_f32_16x16x32_bf16 v[108:111], v[166:169], v[212:215], v[108:111]
	v_mfma_f32_16x16x32_bf16 v[104:107], v[176:179], v[212:215], v[104:107]
	v_mfma_f32_16x16x32_bf16 v[92:95], v[166:169], v[220:223], v[92:95]
	v_mfma_f32_16x16x32_bf16 v[88:91], v[176:179], v[220:223], v[88:91]
	v_mfma_f32_16x16x32_bf16 v[76:79], v[166:169], v[228:231], v[76:79]
	v_mfma_f32_16x16x32_bf16 v[72:75], v[176:179], v[228:231], v[72:75]
	v_mfma_f32_16x16x32_bf16 v[116:119], v[180:183], v[200:203], v[116:119]
	v_mfma_f32_16x16x32_bf16 v[112:115], v[188:191], v[200:203], v[112:115]
	v_mfma_f32_16x16x32_bf16 v[100:103], v[180:183], v[208:211], v[100:103]
	v_mfma_f32_16x16x32_bf16 v[96:99], v[188:191], v[208:211], v[96:99]
	v_mfma_f32_16x16x32_bf16 v[84:87], v[180:183], v[216:219], v[84:87]
	v_mfma_f32_16x16x32_bf16 v[80:83], v[188:191], v[216:219], v[80:83]
	v_mfma_f32_16x16x32_bf16 v[68:71], v[180:183], v[224:227], v[68:71]
	v_mfma_f32_16x16x32_bf16 v[64:67], v[188:191], v[224:227], v[64:67]
	v_mfma_f32_16x16x32_bf16 v[116:119], v[184:187], v[204:207], v[116:119]
	v_mfma_f32_16x16x32_bf16 v[112:115], v[196:199], v[204:207], v[112:115]
	v_mfma_f32_16x16x32_bf16 v[100:103], v[184:187], v[212:215], v[100:103]
	v_mfma_f32_16x16x32_bf16 v[96:99], v[196:199], v[212:215], v[96:99]
	v_mfma_f32_16x16x32_bf16 v[84:87], v[184:187], v[220:223], v[84:87]
	v_mfma_f32_16x16x32_bf16 v[80:83], v[196:199], v[220:223], v[80:83]
	v_mfma_f32_16x16x32_bf16 v[68:71], v[184:187], v[228:231], v[68:71]
	v_mfma_f32_16x16x32_bf16 v[64:67], v[196:199], v[228:231], v[64:67]
	s_barrier
	s_add_i32 s6, s6, s36
	s_add_u32 s98, s58, 0x80
	s_addc_u32 s99, s59, 0
	s_add_u32 s100, s60, 0x80
	s_addc_u32 s101, s61, 0
	s_mov_b32 m0, s6
	ds_read_b128 v[200:203], v158 offset:49152
	ds_read_b128 v[204:207], v158 offset:50176
	ds_read_b128 v[208:211], v158 offset:51200
	ds_read_b128 v[212:215], v158 offset:52224
	global_load_lds_dwordx4 v134, s[98:99]
	s_add_i32 m0, s6, 0x2000
	s_add_u32 s54, s58, 0xb0080
	s_addc_u32 s55, s59, 0
	s_add_i32 s6, s7, s36
	global_load_lds_dwordx4 v138, s[98:99]
	s_mov_b32 m0, s6
	ds_read_b128 v[228:231], v158 offset:56320
	global_load_lds_dwordx4 v134, s[54:55]
	s_add_i32 m0, s6, 0x2000
	ds_read_b128 v[224:227], v158 offset:55296
	global_load_lds_dwordx4 v138, s[54:55]
	s_mov_b32 m0, s78
	ds_read_b128 v[220:223], v158 offset:54272
	global_load_lds_dwordx4 v132, s[100:101]
	s_mov_b32 m0, s79
	ds_read_b128 v[216:219], v158 offset:53248
	global_load_lds_dwordx4 v136, s[100:101]
	s_waitcnt vmcnt(8)
	s_waitcnt lgkmcnt(0)
	s_barrier
	s_waitcnt lgkmcnt(0)
	v_mfma_f32_16x16x32_bf16 v[60:63], v[148:151], v[200:203], v[60:63]
	v_mfma_f32_16x16x32_bf16 v[56:59], v[172:175], v[200:203], v[56:59]
	v_mfma_f32_16x16x32_bf16 v[44:47], v[148:151], v[208:211], v[44:47]
	v_mfma_f32_16x16x32_bf16 v[40:43], v[172:175], v[208:211], v[40:43]
	v_mfma_f32_16x16x32_bf16 v[28:31], v[148:151], v[216:219], v[28:31]
	v_mfma_f32_16x16x32_bf16 v[24:27], v[172:175], v[216:219], v[24:27]
	v_mfma_f32_16x16x32_bf16 v[12:15], v[148:151], v[224:227], v[12:15]
	v_mfma_f32_16x16x32_bf16 v[8:11], v[172:175], v[224:227], v[8:11]
	v_mfma_f32_16x16x32_bf16 v[60:63], v[166:169], v[204:207], v[60:63]
	v_mfma_f32_16x16x32_bf16 v[56:59], v[176:179], v[204:207], v[56:59]
	v_mfma_f32_16x16x32_bf16 v[44:47], v[166:169], v[212:215], v[44:47]
	v_mfma_f32_16x16x32_bf16 v[40:43], v[176:179], v[212:215], v[40:43]
	v_mfma_f32_16x16x32_bf16 v[28:31], v[166:169], v[220:223], v[28:31]
	v_mfma_f32_16x16x32_bf16 v[24:27], v[176:179], v[220:223], v[24:27]
	v_mfma_f32_16x16x32_bf16 v[12:15], v[166:169], v[228:231], v[12:15]
	v_mfma_f32_16x16x32_bf16 v[8:11], v[176:179], v[228:231], v[8:11]
	v_mfma_f32_16x16x32_bf16 v[52:55], v[180:183], v[200:203], v[52:55]
	v_mfma_f32_16x16x32_bf16 v[48:51], v[188:191], v[200:203], v[48:51]
	v_mfma_f32_16x16x32_bf16 v[36:39], v[180:183], v[208:211], v[36:39]
	v_mfma_f32_16x16x32_bf16 v[32:35], v[188:191], v[208:211], v[32:35]
	v_mfma_f32_16x16x32_bf16 v[20:23], v[180:183], v[216:219], v[20:23]
	v_mfma_f32_16x16x32_bf16 v[16:19], v[188:191], v[216:219], v[16:19]
	v_mfma_f32_16x16x32_bf16 v[4:7], v[180:183], v[224:227], v[4:7]
	v_mfma_f32_16x16x32_bf16 v[0:3], v[188:191], v[224:227], v[0:3]
	v_mfma_f32_16x16x32_bf16 v[52:55], v[184:187], v[204:207], v[52:55]
	v_mfma_f32_16x16x32_bf16 v[48:51], v[196:199], v[204:207], v[48:51]
	v_mfma_f32_16x16x32_bf16 v[36:39], v[184:187], v[212:215], v[36:39]
	v_mfma_f32_16x16x32_bf16 v[32:35], v[196:199], v[212:215], v[32:35]
	v_mfma_f32_16x16x32_bf16 v[20:23], v[184:187], v[220:223], v[20:23]
	v_mfma_f32_16x16x32_bf16 v[16:19], v[196:199], v[220:223], v[16:19]
	v_mfma_f32_16x16x32_bf16 v[4:7], v[184:187], v[228:231], v[4:7]
	v_mfma_f32_16x16x32_bf16 v[0:3], v[196:199], v[228:231], v[0:3]
	s_barrier
	s_add_i32 s69, s69, 2
	s_add_u32 s4, s4, 0x100
	s_addc_u32 s33, s33, 0
	s_cmp_gt_u32 s69, 41
	s_mov_b64 s[54:55], s[56:57]
	s_cbranch_scc0 .LBB0_323
	s_and_b64 vcc, exec, s[40:41]
	s_cbranch_vccz .LBB0_326
	s_barrier

; #define PG8_STAGE(bufoff, gbase, voff) do { _Pragma("unroll") for (int _i = 0; _i < 2; ++_i) \
;         __builtin_amdgcn_global_load_lds((const unsigned*)((const char*)(gbase) + (voff)[_i]), (PG8_LAS unsigned*)(lds + (bufoff) + ldsw + _i * 8192), 16, 0, 0); } while (0)
; #define PG8_LDA(dst, b, h) do { _Pragma("unroll") for (int m = 0; m < 4; ++m) _Pragma("unroll") for (int k = 0; k < 2; ++k) dst[m][k] = *(const PG8_LAS bf16x8*)(lds + PG8_SA(b, h) + aoff + m * 2048 + k * 1024); } while (0)
; #define PG8_LDB(dst, b, h) do { _Pragma("unroll") for (int n = 0; n < 2; ++n) _Pragma("unroll") for (int k = 0; k < 2; ++k) dst[n][k] = *(const PG8_LAS bf16x8*)(lds + PG8_SB(b, h) + boff + n * 2048 + k * 1024); } while (0)
; #define PG8_MMA(ai, bj, At, Bt) do { __builtin_amdgcn_s_setprio(1); _Pragma("unroll") for (int m = 0; m < 4; ++m) _Pragma("unroll") for (int n = 0; n < 2; ++n) _Pragma("unroll") for (int k = 0; k < 2; ++k) \
;         acc[ai][bj][m][n] = __builtin_amdgcn_mfma_f32_16x16x32_bf16(Bt[n][k], At[m][k], acc[ai][bj][m][n], 0, 0, 0); __builtin_amdgcn_s_setprio(0); } while (0)
; #define PG8_WAIT_V(n) asm volatile("s_waitcnt vmcnt(" #n ")" ::: "memory")
; #define PG8_WAIT_L(n) asm volatile("s_waitcnt lgkmcnt(" #n ")" ::: "memory")
; template <class Epi, class Sched, bool ALIGN_EPI = false, bool SP2 = false>
; __device__ __forceinline__ void gemm_phase(PG8_LAS unsigned char* lds, const Gemm g, const Sched& S, const Epi& E) {
;     ...
;             const bool last = (t == nt - 2);
;             const char* a1 = cA + (size_t)(t + 1) * kstep;
;             const char* a2 = last ? nA : cA + (size_t)(t + 2) * kstep; const char* b2 = last ? nB : cB + (size_t)(t + 2) * kstep;
;             const char* a3 = a2 + kstep; const char* b3 = b2 + kstep;
;             if (last && has_next) S.a_ready(nxt);
;             if constexpr (SP2) {
;             PG8_LDB(B0, 0, 0); PG8_LDB(B1, 0, 1); PG8_SCHED; PG8_LDA(At, 0, 0); PG8_STAGE(PG8_SA(1, 1), a1 + hstep, voffA);
;             PG8_WAIT_V(8); PG8_WAIT_L(0); PG8_BAR; PG8_MMA(0, 0, At, B0); PG8_MMA(0, 1, At, B1); PG8_BAR; PG8_SCHED;
;             PG8_LDA(At, 0, 1); PG8_STAGE(PG8_SB(0, 0), b2, voffB); PG8_STAGE(PG8_SB(0, 1), b2 + hstep, voffB); PG8_STAGE(PG8_SA(0, 0), a2, voffA);
;             PG8_WAIT_V(8); PG8_WAIT_L(0); PG8_BAR; PG8_MMA(1, 0, At, B0); PG8_MMA(1, 1, At, B1); PG8_BAR; PG8_SCHED;
.LBB0_463:
	ds_read_b128 v[152:155], v172
	ds_read_b128 v[156:159], v172 offset:1024
	ds_read_b128 v[166:169], v172 offset:2048
	ds_read_b128 v[176:179], v172 offset:3072
	ds_read_b128 v[180:183], v173
	ds_read_b128 v[184:187], v173 offset:1024
	ds_read_b128 v[188:191], v173 offset:2048
	ds_read_b128 v[196:199], v173 offset:3072
	s_add_u32 s6, s60, 0xfffc0080
	s_addc_u32 s7, s61, -1
	s_cmp_eq_u32 s72, 12
	s_cselect_b32 s81, s49, s7
	s_cselect_b32 s80, s55, s6
	s_cselect_b32 s79, s53, s33
	s_cselect_b32 s78, vcc_lo, vcc_hi
	s_add_i32 m0, s31, 0xc000
	ds_read_b128 v[200:203], v174
	ds_read_b128 v[204:207], v174 offset:1024
	ds_read_b128 v[208:211], v174 offset:2048
	ds_read_b128 v[212:215], v174 offset:3072
	ds_read_b128 v[216:219], v174 offset:4096
	ds_read_b128 v[220:223], v174 offset:5120
	ds_read_b128 v[224:227], v174 offset:6144
	global_load_lds_dwordx4 v144, s[60:61]
	s_add_i32 m0, s31, 0xe000
	ds_read_b128 v[228:231], v174 offset:7168
	global_load_lds_dwordx4 v146, s[60:61]
	s_waitcnt vmcnt(8)
	s_waitcnt lgkmcnt(0)
	s_barrier
	s_waitcnt lgkmcnt(0)
	v_mfma_f32_16x16x32_bf16 v[124:127], v[152:155], v[200:203], v[124:127]
	v_mfma_f32_16x16x32_bf16 v[120:123], v[166:169], v[200:203], v[120:123]
	v_mfma_f32_16x16x32_bf16 v[108:111], v[152:155], v[208:211], v[108:111]
	v_mfma_f32_16x16x32_bf16 v[104:107], v[166:169], v[208:211], v[104:107]
	v_mfma_f32_16x16x32_bf16 v[92:95], v[152:155], v[216:219], v[92:95]
	v_mfma_f32_16x16x32_bf16 v[88:91], v[166:169], v[216:219], v[88:91]
	v_mfma_f32_16x16x32_bf16 v[76:79], v[152:155], v[224:227], v[76:79]
	v_mfma_f32_16x16x32_bf16 v[72:75], v[166:169], v[224:227], v[72:75]
	v_mfma_f32_16x16x32_bf16 v[124:127], v[156:159], v[204:207], v[124:127]
	v_mfma_f32_16x16x32_bf16 v[120:123], v[176:179], v[204:207], v[120:123]
	v_mfma_f32_16x16x32_bf16 v[108:111], v[156:159], v[212:215], v[108:111]
	v_mfma_f32_16x16x32_bf16 v[104:107], v[176:179], v[212:215], v[104:107]
	v_mfma_f32_16x16x32_bf16 v[92:95], v[156:159], v[220:223], v[92:95]
	v_mfma_f32_16x16x32_bf16 v[88:91], v[176:179], v[220:223], v[88:91]
	v_mfma_f32_16x16x32_bf16 v[76:79], v[156:159], v[228:231], v[76:79]
	v_mfma_f32_16x16x32_bf16 v[72:75], v[176:179], v[228:231], v[72:75]
	v_mfma_f32_16x16x32_bf16 v[116:119], v[180:183], v[200:203], v[116:119]
	v_mfma_f32_16x16x32_bf16 v[112:115], v[188:191], v[200:203], v[112:115]
	v_mfma_f32_16x16x32_bf16 v[100:103], v[180:183], v[208:211], v[100:103]
	v_mfma_f32_16x16x32_bf16 v[96:99], v[188:191], v[208:211], v[96:99]
	v_mfma_f32_16x16x32_bf16 v[84:87], v[180:183], v[216:219], v[84:87]
	v_mfma_f32_16x16x32_bf16 v[80:83], v[188:191], v[216:219], v[80:83]
	v_mfma_f32_16x16x32_bf16 v[68:71], v[180:183], v[224:227], v[68:71]
	v_mfma_f32_16x16x32_bf16 v[64:67], v[188:191], v[224:227], v[64:67]
	v_mfma_f32_16x16x32_bf16 v[116:119], v[184:187], v[204:207], v[116:119]
	v_mfma_f32_16x16x32_bf16 v[112:115], v[196:199], v[204:207], v[112:115]
	v_mfma_f32_16x16x32_bf16 v[100:103], v[184:187], v[212:215], v[100:103]
	v_mfma_f32_16x16x32_bf16 v[96:99], v[196:199], v[212:215], v[96:99]
	v_mfma_f32_16x16x32_bf16 v[84:87], v[184:187], v[220:223], v[84:87]
	v_mfma_f32_16x16x32_bf16 v[80:83], v[196:199], v[220:223], v[80:83]
	v_mfma_f32_16x16x32_bf16 v[68:71], v[184:187], v[228:231], v[68:71]
	v_mfma_f32_16x16x32_bf16 v[64:67], v[196:199], v[228:231], v[64:67]
	s_barrier
	s_add_i32 s6, s69, s30
	s_mov_b32 m0, s6
	ds_read_b128 v[200:203], v174 offset:16384
	ds_read_b128 v[204:207], v174 offset:17408
	ds_read_b128 v[208:211], v174 offset:18432
	ds_read_b128 v[212:215], v174 offset:19456
	ds_read_b128 v[216:219], v174 offset:20480
	global_load_lds_dwordx4 v134, s[78:79]
	s_add_i32 m0, s6, 0x2000
	s_add_u32 s6, s78, 0x40000
	s_addc_u32 s7, s79, 0
	s_add_i32 s73, s74, s30
	global_load_lds_dwordx4 v138, s[78:79]
	s_mov_b32 m0, s73
	s_nop 0
	global_load_lds_dwordx4 v134, s[6:7]
	s_add_i32 m0, s73, 0x2000
	ds_read_b128 v[228:231], v174 offset:23552
	global_load_lds_dwordx4 v138, s[6:7]
	s_mov_b32 m0, s31
	ds_read_b128 v[224:227], v174 offset:22528
	global_load_lds_dwordx4 v132, s[80:81]
	s_mov_b32 m0, s36
	ds_read_b128 v[220:223], v174 offset:21504
	global_load_lds_dwordx4 v136, s[80:81]
	s_waitcnt vmcnt(8)
	s_waitcnt lgkmcnt(0)
	s_barrier
	s_waitcnt lgkmcnt(0)
	v_mfma_f32_16x16x32_bf16 v[60:63], v[152:155], v[200:203], v[60:63]
	v_mfma_f32_16x16x32_bf16 v[56:59], v[166:169], v[200:203], v[56:59]
	v_mfma_f32_16x16x32_bf16 v[44:47], v[152:155], v[208:211], v[44:47]
	v_mfma_f32_16x16x32_bf16 v[40:43], v[166:169], v[208:211], v[40:43]
	v_mfma_f32_16x16x32_bf16 v[28:31], v[152:155], v[216:219], v[28:31]
	v_mfma_f32_16x16x32_bf16 v[24:27], v[166:169], v[216:219], v[24:27]
	v_mfma_f32_16x16x32_bf16 v[12:15], v[152:155], v[224:227], v[12:15]
	v_mfma_f32_16x16x32_bf16 v[8:11], v[166:169], v[224:227], v[8:11]
	v_mfma_f32_16x16x32_bf16 v[60:63], v[156:159], v[204:207], v[60:63]
	v_mfma_f32_16x16x32_bf16 v[56:59], v[176:179], v[204:207], v[56:59]
	v_mfma_f32_16x16x32_bf16 v[44:47], v[156:159], v[212:215], v[44:47]
	v_mfma_f32_16x16x32_bf16 v[40:43], v[176:179], v[212:215], v[40:43]
	v_mfma_f32_16x16x32_bf16 v[28:31], v[156:159], v[220:223], v[28:31]
	v_mfma_f32_16x16x32_bf16 v[24:27], v[176:179], v[220:223], v[24:27]
	v_mfma_f32_16x16x32_bf16 v[12:15], v[156:159], v[228:231], v[12:15]
	v_mfma_f32_16x16x32_bf16 v[8:11], v[176:179], v[228:231], v[8:11]
	v_mfma_f32_16x16x32_bf16 v[52:55], v[180:183], v[200:203], v[52:55]
	v_mfma_f32_16x16x32_bf16 v[48:51], v[188:191], v[200:203], v[48:51]
	v_mfma_f32_16x16x32_bf16 v[36:39], v[180:183], v[208:211], v[36:39]
	v_mfma_f32_16x16x32_bf16 v[32:35], v[188:191], v[208:211], v[32:35]
	v_mfma_f32_16x16x32_bf16 v[20:23], v[180:183], v[216:219], v[20:23]
	v_mfma_f32_16x16x32_bf16 v[16:19], v[188:191], v[216:219], v[16:19]
	v_mfma_f32_16x16x32_bf16 v[4:7], v[180:183], v[224:227], v[4:7]
	v_mfma_f32_16x16x32_bf16 v[0:3], v[188:191], v[224:227], v[0:3]
	v_mfma_f32_16x16x32_bf16 v[52:55], v[184:187], v[204:207], v[52:55]
	v_mfma_f32_16x16x32_bf16 v[48:51], v[196:199], v[204:207], v[48:51]
	v_mfma_f32_16x16x32_bf16 v[36:39], v[184:187], v[212:215], v[36:39]
	v_mfma_f32_16x16x32_bf16 v[32:35], v[196:199], v[212:215], v[32:35]
	v_mfma_f32_16x16x32_bf16 v[20:23], v[184:187], v[220:223], v[20:23]
	v_mfma_f32_16x16x32_bf16 v[16:19], v[196:199], v[220:223], v[16:19]
	v_mfma_f32_16x16x32_bf16 v[4:7], v[184:187], v[228:231], v[4:7]
	v_mfma_f32_16x16x32_bf16 v[0:3], v[196:199], v[228:231], v[0:3]
	s_barrier
; #define PG8_STAGE(bufoff, gbase, voff) do { _Pragma("unroll") for (int _i = 0; _i < 2; ++_i) \
;         __builtin_amdgcn_global_load_lds((const unsigned*)((const char*)(gbase) + (voff)[_i]), (PG8_LAS unsigned*)(lds + (bufoff) + ldsw + _i * 8192), 16, 0, 0); } while (0)
; #define PG8_LDA(dst, b, h) do { _Pragma("unroll") for (int m = 0; m < 4; ++m) _Pragma("unroll") for (int k = 0; k < 2; ++k) dst[m][k] = *(const PG8_LAS bf16x8*)(lds + PG8_SA(b, h) + aoff + m * 2048 + k * 1024); } while (0)
; #define PG8_LDB(dst, b, h) do { _Pragma("unroll") for (int n = 0; n < 2; ++n) _Pragma("unroll") for (int k = 0; k < 2; ++k) dst[n][k] = *(const PG8_LAS bf16x8*)(lds + PG8_SB(b, h) + boff + n * 2048 + k * 1024); } while (0)
; #define PG8_MMA(ai, bj, At, Bt) do { __builtin_amdgcn_s_setprio(1); _Pragma("unroll") for (int m = 0; m < 4; ++m) _Pragma("unroll") for (int n = 0; n < 2; ++n) _Pragma("unroll") for (int k = 0; k < 2; ++k) \
;         acc[ai][bj][m][n] = __builtin_amdgcn_mfma_f32_16x16x32_bf16(Bt[n][k], At[m][k], acc[ai][bj][m][n], 0, 0, 0); __builtin_amdgcn_s_setprio(0); } while (0)
; #define PG8_WAIT_V(n) asm volatile("s_waitcnt vmcnt(" #n ")" ::: "memory")
; #define PG8_WAIT_L(n) asm volatile("s_waitcnt lgkmcnt(" #n ")" ::: "memory")
; #define PG8_BAR __builtin_amdgcn_s_barrier()
; #define PG8_SCHED __builtin_amdgcn_sched_barrier(0)
; template <class Epi, class Sched, bool ALIGN_EPI = false, bool SP2 = false>
; __device__ __forceinline__ void gemm_phase(PG8_LAS unsigned char* lds, const Gemm g, const Sched& S, const Epi& E) {
;     ...
;             PG8_LDB(B0, 1, 0); PG8_LDB(B1, 1, 1); PG8_SCHED; PG8_LDA(At, 1, 0); PG8_STAGE(PG8_SA(0, 1), a2 + hstep, voffA);
;             PG8_WAIT_V(8); PG8_WAIT_L(0); PG8_BAR; PG8_MMA(0, 0, At, B0); PG8_MMA(0, 1, At, B1); PG8_BAR; PG8_SCHED;
;             PG8_LDA(At, 1, 1); PG8_STAGE(PG8_SB(1, 0), b3, voffB); PG8_STAGE(PG8_SB(1, 1), b3 + hstep, voffB); PG8_STAGE(PG8_SA(1, 0), a3, voffA);
;             PG8_WAIT_V(8); PG8_WAIT_L(0); PG8_BAR; PG8_MMA(1, 0, At, B0); PG8_MMA(1, 1, At, B1); PG8_BAR; PG8_SCHED;
	s_add_i32 s73, 0, 0x18000
	v_add_u32_e32 v175, s73, v143
	s_add_i32 s82, 0, 0x1c000
	ds_read_b128 v[152:155], v175
	ds_read_b128 v[156:159], v175 offset:1024
	ds_read_b128 v[166:169], v175 offset:2048
	ds_read_b128 v[176:179], v175 offset:3072
	v_add_u32_e32 v175, s82, v143
	ds_read_b128 v[180:183], v175
	ds_read_b128 v[184:187], v175 offset:1024
	ds_read_b128 v[188:191], v175 offset:2048
	ds_read_b128 v[196:199], v175 offset:3072
	s_add_u32 s6, s80, 0x40000
	s_addc_u32 s7, s81, 0
	s_mov_b32 m0, s37
	ds_read_b128 v[200:203], v174 offset:32768
	ds_read_b128 v[204:207], v174 offset:33792
	ds_read_b128 v[208:211], v174 offset:34816
	ds_read_b128 v[212:215], v174 offset:35840
	ds_read_b128 v[216:219], v174 offset:36864
	ds_read_b128 v[220:223], v174 offset:37888
	ds_read_b128 v[224:227], v174 offset:38912
	global_load_lds_dwordx4 v132, s[6:7]
	s_mov_b32 m0, s42
	ds_read_b128 v[228:231], v174 offset:39936
	global_load_lds_dwordx4 v136, s[6:7]
	s_waitcnt vmcnt(8)
	s_waitcnt lgkmcnt(0)
	s_barrier
	s_waitcnt lgkmcnt(0)
	v_mfma_f32_16x16x32_bf16 v[124:127], v[152:155], v[200:203], v[124:127]
	v_mfma_f32_16x16x32_bf16 v[120:123], v[166:169], v[200:203], v[120:123]
	v_mfma_f32_16x16x32_bf16 v[108:111], v[152:155], v[208:211], v[108:111]
	v_mfma_f32_16x16x32_bf16 v[104:107], v[166:169], v[208:211], v[104:107]
	v_mfma_f32_16x16x32_bf16 v[92:95], v[152:155], v[216:219], v[92:95]
	v_mfma_f32_16x16x32_bf16 v[88:91], v[166:169], v[216:219], v[88:91]
	v_mfma_f32_16x16x32_bf16 v[76:79], v[152:155], v[224:227], v[76:79]
	v_mfma_f32_16x16x32_bf16 v[72:75], v[166:169], v[224:227], v[72:75]
	v_mfma_f32_16x16x32_bf16 v[124:127], v[156:159], v[204:207], v[124:127]
	v_mfma_f32_16x16x32_bf16 v[120:123], v[176:179], v[204:207], v[120:123]
	v_mfma_f32_16x16x32_bf16 v[108:111], v[156:159], v[212:215], v[108:111]
	v_mfma_f32_16x16x32_bf16 v[104:107], v[176:179], v[212:215], v[104:107]
	v_mfma_f32_16x16x32_bf16 v[92:95], v[156:159], v[220:223], v[92:95]
	v_mfma_f32_16x16x32_bf16 v[88:91], v[176:179], v[220:223], v[88:91]
	v_mfma_f32_16x16x32_bf16 v[76:79], v[156:159], v[228:231], v[76:79]
	v_mfma_f32_16x16x32_bf16 v[72:75], v[176:179], v[228:231], v[72:75]
	v_mfma_f32_16x16x32_bf16 v[116:119], v[180:183], v[200:203], v[116:119]
	v_mfma_f32_16x16x32_bf16 v[112:115], v[188:191], v[200:203], v[112:115]
	v_mfma_f32_16x16x32_bf16 v[100:103], v[180:183], v[208:211], v[100:103]
	v_mfma_f32_16x16x32_bf16 v[96:99], v[188:191], v[208:211], v[96:99]
	v_mfma_f32_16x16x32_bf16 v[84:87], v[180:183], v[216:219], v[84:87]
	v_mfma_f32_16x16x32_bf16 v[80:83], v[188:191], v[216:219], v[80:83]
	v_mfma_f32_16x16x32_bf16 v[68:71], v[180:183], v[224:227], v[68:71]
	v_mfma_f32_16x16x32_bf16 v[64:67], v[188:191], v[224:227], v[64:67]
	v_mfma_f32_16x16x32_bf16 v[116:119], v[184:187], v[204:207], v[116:119]
	v_mfma_f32_16x16x32_bf16 v[112:115], v[196:199], v[204:207], v[112:115]
	v_mfma_f32_16x16x32_bf16 v[100:103], v[184:187], v[212:215], v[100:103]
	v_mfma_f32_16x16x32_bf16 v[96:99], v[196:199], v[212:215], v[96:99]
	v_mfma_f32_16x16x32_bf16 v[84:87], v[184:187], v[220:223], v[84:87]
	v_mfma_f32_16x16x32_bf16 v[80:83], v[196:199], v[220:223], v[80:83]
	v_mfma_f32_16x16x32_bf16 v[68:71], v[184:187], v[228:231], v[68:71]
	v_mfma_f32_16x16x32_bf16 v[64:67], v[196:199], v[228:231], v[64:67]
	s_barrier
	s_add_i32 s6, s73, s30
	s_add_u32 s98, s78, 0x80
	s_addc_u32 s99, s79, 0
	s_add_u32 s100, s80, 0x80
	s_addc_u32 s101, s81, 0
	s_mov_b32 m0, s6
	ds_read_b128 v[200:203], v174 offset:49152
	ds_read_b128 v[204:207], v174 offset:50176
	ds_read_b128 v[208:211], v174 offset:51200
	ds_read_b128 v[212:215], v174 offset:52224
	global_load_lds_dwordx4 v134, s[98:99]
	s_add_i32 m0, s6, 0x2000
	s_add_u32 s6, s78, 0x40080
	s_addc_u32 s7, s79, 0
	s_add_i32 s73, s82, s30
	global_load_lds_dwordx4 v138, s[98:99]
	s_mov_b32 m0, s73
	ds_read_b128 v[228:231], v174 offset:56320
	global_load_lds_dwordx4 v134, s[6:7]
	s_add_i32 m0, s73, 0x2000
	ds_read_b128 v[224:227], v174 offset:55296
	global_load_lds_dwordx4 v138, s[6:7]
	s_mov_b32 m0, s67
	ds_read_b128 v[220:223], v174 offset:54272
	global_load_lds_dwordx4 v132, s[100:101]
	s_mov_b32 m0, s68
	ds_read_b128 v[216:219], v174 offset:53248
	global_load_lds_dwordx4 v136, s[100:101]
	s_waitcnt vmcnt(8)
	s_waitcnt lgkmcnt(0)
	s_barrier
	s_waitcnt lgkmcnt(0)
	v_mfma_f32_16x16x32_bf16 v[60:63], v[152:155], v[200:203], v[60:63]
	v_mfma_f32_16x16x32_bf16 v[56:59], v[166:169], v[200:203], v[56:59]
	v_mfma_f32_16x16x32_bf16 v[44:47], v[152:155], v[208:211], v[44:47]
	v_mfma_f32_16x16x32_bf16 v[40:43], v[166:169], v[208:211], v[40:43]
	v_mfma_f32_16x16x32_bf16 v[28:31], v[152:155], v[216:219], v[28:31]
	v_mfma_f32_16x16x32_bf16 v[24:27], v[166:169], v[216:219], v[24:27]
	v_mfma_f32_16x16x32_bf16 v[12:15], v[152:155], v[224:227], v[12:15]
	v_mfma_f32_16x16x32_bf16 v[8:11], v[166:169], v[224:227], v[8:11]
	v_mfma_f32_16x16x32_bf16 v[60:63], v[156:159], v[204:207], v[60:63]
	v_mfma_f32_16x16x32_bf16 v[56:59], v[176:179], v[204:207], v[56:59]
	v_mfma_f32_16x16x32_bf16 v[44:47], v[156:159], v[212:215], v[44:47]
	v_mfma_f32_16x16x32_bf16 v[40:43], v[176:179], v[212:215], v[40:43]
	v_mfma_f32_16x16x32_bf16 v[28:31], v[156:159], v[220:223], v[28:31]
	v_mfma_f32_16x16x32_bf16 v[24:27], v[176:179], v[220:223], v[24:27]
	v_mfma_f32_16x16x32_bf16 v[12:15], v[156:159], v[228:231], v[12:15]
	v_mfma_f32_16x16x32_bf16 v[8:11], v[176:179], v[228:231], v[8:11]
	v_mfma_f32_16x16x32_bf16 v[52:55], v[180:183], v[200:203], v[52:55]
	v_mfma_f32_16x16x32_bf16 v[48:51], v[188:191], v[200:203], v[48:51]
	v_mfma_f32_16x16x32_bf16 v[36:39], v[180:183], v[208:211], v[36:39]
	v_mfma_f32_16x16x32_bf16 v[32:35], v[188:191], v[208:211], v[32:35]
	v_mfma_f32_16x16x32_bf16 v[20:23], v[180:183], v[216:219], v[20:23]
	v_mfma_f32_16x16x32_bf16 v[16:19], v[188:191], v[216:219], v[16:19]
	v_mfma_f32_16x16x32_bf16 v[4:7], v[180:183], v[224:227], v[4:7]
	v_mfma_f32_16x16x32_bf16 v[0:3], v[188:191], v[224:227], v[0:3]
	v_mfma_f32_16x16x32_bf16 v[52:55], v[184:187], v[204:207], v[52:55]
	v_mfma_f32_16x16x32_bf16 v[48:51], v[196:199], v[204:207], v[48:51]
	v_mfma_f32_16x16x32_bf16 v[36:39], v[184:187], v[212:215], v[36:39]
	v_mfma_f32_16x16x32_bf16 v[32:35], v[196:199], v[212:215], v[32:35]
	v_mfma_f32_16x16x32_bf16 v[20:23], v[184:187], v[220:223], v[20:23]
	v_mfma_f32_16x16x32_bf16 v[16:19], v[196:199], v[220:223], v[16:19]
	v_mfma_f32_16x16x32_bf16 v[4:7], v[184:187], v[228:231], v[4:7]
	v_mfma_f32_16x16x32_bf16 v[0:3], v[196:199], v[228:231], v[0:3]
	s_barrier
	s_add_i32 s72, s72, 2
	s_add_u32 s60, s60, 0x100
	s_addc_u32 s61, s61, 0
	s_add_u32 vcc_hi, vcc_hi, 0x100
	s_addc_u32 s33, s33, 0
	s_cmp_gt_u32 s72, 13
	s_cbranch_scc0 .LBB0_463
	s_and_b64 vcc, exec, s[50:51]
	s_cbranch_vccz .LBB0_466
	s_barrier

; #define PG8_STAGE(bufoff, gbase, voff) do { _Pragma("unroll") for (int _i = 0; _i < 2; ++_i) \
;         __builtin_amdgcn_global_load_lds((const unsigned*)((const char*)(gbase) + (voff)[_i]), (PG8_LAS unsigned*)(lds + (bufoff) + ldsw + _i * 8192), 16, 0, 0); } while (0)
; #define PG8_LDA(dst, b, h) do { _Pragma("unroll") for (int m = 0; m < 4; ++m) _Pragma("unroll") for (int k = 0; k < 2; ++k) dst[m][k] = *(const PG8_LAS bf16x8*)(lds + PG8_SA(b, h) + aoff + m * 2048 + k * 1024); } while (0)
; #define PG8_LDB(dst, b, h) do { _Pragma("unroll") for (int n = 0; n < 2; ++n) _Pragma("unroll") for (int k = 0; k < 2; ++k) dst[n][k] = *(const PG8_LAS bf16x8*)(lds + PG8_SB(b, h) + boff + n * 2048 + k * 1024); } while (0)
; #define PG8_MMA(ai, bj, At, Bt) do { __builtin_amdgcn_s_setprio(1); _Pragma("unroll") for (int m = 0; m < 4; ++m) _Pragma("unroll") for (int n = 0; n < 2; ++n) _Pragma("unroll") for (int k = 0; k < 2; ++k) \
;         acc[ai][bj][m][n] = __builtin_amdgcn_mfma_f32_16x16x32_bf16(Bt[n][k], At[m][k], acc[ai][bj][m][n], 0, 0, 0); __builtin_amdgcn_s_setprio(0); } while (0)
; #define PG8_WAIT_V(n) asm volatile("s_waitcnt vmcnt(" #n ")" ::: "memory")
; #define PG8_WAIT_L(n) asm volatile("s_waitcnt lgkmcnt(" #n ")" ::: "memory")
; #define PG8_BAR __builtin_amdgcn_s_barrier()
; #define PG8_SCHED __builtin_amdgcn_sched_barrier(0)
; template <class Epi, class Sched, bool ALIGN_EPI = false, bool SP2 = false>
; __device__ __forceinline__ void gemm_phase(PG8_LAS unsigned char* lds, const Gemm g, const Sched& S, const Epi& E) {
;     ...
;             const char* a1 = cA + (size_t)(t + 1) * kstep;
;             const char* a2 = last ? nA : cA + (size_t)(t + 2) * kstep; const char* b2 = last ? nB : cB + (size_t)(t + 2) * kstep;
;             const char* a3 = a2 + kstep; const char* b3 = b2 + kstep;
;     ...
;             PG8_LDB(B0, 0, 0); PG8_LDB(B1, 0, 1); PG8_SCHED; PG8_LDA(At, 0, 0); PG8_STAGE(PG8_SA(1, 1), a1 + hstep, voffA);
;             PG8_WAIT_V(8); PG8_WAIT_L(0); PG8_BAR; PG8_MMA(0, 0, At, B0); PG8_MMA(0, 1, At, B1); PG8_BAR; PG8_SCHED;
;             PG8_LDA(At, 0, 1); PG8_STAGE(PG8_SB(0, 0), b2, voffB); PG8_STAGE(PG8_SB(0, 1), b2 + hstep, voffB); PG8_STAGE(PG8_SA(0, 0), a2, voffA);
;             PG8_WAIT_V(8); PG8_WAIT_L(0); PG8_BAR; PG8_MMA(1, 0, At, B0); PG8_MMA(1, 1, At, B1); PG8_BAR; PG8_SCHED;
.LBB0_777:
	ds_read_b128 v[144:147], v158
	ds_read_b128 v[168:171], v158 offset:1024
	ds_read_b128 v[172:175], v158 offset:2048
	ds_read_b128 v[176:179], v158 offset:3072
	ds_read_b128 v[180:183], v159
	ds_read_b128 v[184:187], v159 offset:1024
	ds_read_b128 v[188:191], v159 offset:2048
	ds_read_b128 v[196:199], v159 offset:3072
	s_add_u32 s60, s58, 0x100
	s_addc_u32 s61, s59, 0
	s_cmp_eq_u32 s72, 8
	s_cselect_b32 s81, s49, s61
	s_cselect_b32 s80, s48, s60
	s_cselect_b32 s79, s57, vcc_lo
	s_cselect_b32 s78, s56, s33
	s_add_i32 m0, s76, 0xc000
	ds_read_b128 v[200:203], v163
	ds_read_b128 v[204:207], v163 offset:1024
	ds_read_b128 v[208:211], v163 offset:2048
	ds_read_b128 v[212:215], v163 offset:3072
	ds_read_b128 v[216:219], v163 offset:4096
	ds_read_b128 v[220:223], v163 offset:5120
	ds_read_b128 v[224:227], v163 offset:6144
	global_load_lds_dwordx4 v136, s[58:59]
	s_add_i32 m0, s76, 0xe000
	ds_read_b128 v[228:231], v163 offset:7168
	global_load_lds_dwordx4 v138, s[58:59]
	s_waitcnt vmcnt(8)
	s_waitcnt lgkmcnt(0)
	s_barrier
	s_waitcnt lgkmcnt(0)
	v_mfma_f32_16x16x32_bf16 v[124:127], v[144:147], v[200:203], v[124:127]
	v_mfma_f32_16x16x32_bf16 v[120:123], v[172:175], v[200:203], v[120:123]
	v_mfma_f32_16x16x32_bf16 v[108:111], v[144:147], v[208:211], v[108:111]
	v_mfma_f32_16x16x32_bf16 v[104:107], v[172:175], v[208:211], v[104:107]
	v_mfma_f32_16x16x32_bf16 v[92:95], v[144:147], v[216:219], v[92:95]
	v_mfma_f32_16x16x32_bf16 v[88:91], v[172:175], v[216:219], v[88:91]
	v_mfma_f32_16x16x32_bf16 v[76:79], v[144:147], v[224:227], v[76:79]
	v_mfma_f32_16x16x32_bf16 v[72:75], v[172:175], v[224:227], v[72:75]
	v_mfma_f32_16x16x32_bf16 v[124:127], v[168:171], v[204:207], v[124:127]
	v_mfma_f32_16x16x32_bf16 v[120:123], v[176:179], v[204:207], v[120:123]
	v_mfma_f32_16x16x32_bf16 v[108:111], v[168:171], v[212:215], v[108:111]
	v_mfma_f32_16x16x32_bf16 v[104:107], v[176:179], v[212:215], v[104:107]
	v_mfma_f32_16x16x32_bf16 v[92:95], v[168:171], v[220:223], v[92:95]
	v_mfma_f32_16x16x32_bf16 v[88:91], v[176:179], v[220:223], v[88:91]
	v_mfma_f32_16x16x32_bf16 v[76:79], v[168:171], v[228:231], v[76:79]
	v_mfma_f32_16x16x32_bf16 v[72:75], v[176:179], v[228:231], v[72:75]
	v_mfma_f32_16x16x32_bf16 v[116:119], v[180:183], v[200:203], v[116:119]
	v_mfma_f32_16x16x32_bf16 v[112:115], v[188:191], v[200:203], v[112:115]
	v_mfma_f32_16x16x32_bf16 v[100:103], v[180:183], v[208:211], v[100:103]
	v_mfma_f32_16x16x32_bf16 v[96:99], v[188:191], v[208:211], v[96:99]
	v_mfma_f32_16x16x32_bf16 v[84:87], v[180:183], v[216:219], v[84:87]
	v_mfma_f32_16x16x32_bf16 v[80:83], v[188:191], v[216:219], v[80:83]
	v_mfma_f32_16x16x32_bf16 v[68:71], v[180:183], v[224:227], v[68:71]
	v_mfma_f32_16x16x32_bf16 v[64:67], v[188:191], v[224:227], v[64:67]
	v_mfma_f32_16x16x32_bf16 v[116:119], v[184:187], v[204:207], v[116:119]
	v_mfma_f32_16x16x32_bf16 v[112:115], v[196:199], v[204:207], v[112:115]
	v_mfma_f32_16x16x32_bf16 v[100:103], v[184:187], v[212:215], v[100:103]
	v_mfma_f32_16x16x32_bf16 v[96:99], v[196:199], v[212:215], v[96:99]
	v_mfma_f32_16x16x32_bf16 v[84:87], v[184:187], v[220:223], v[84:87]
	v_mfma_f32_16x16x32_bf16 v[80:83], v[196:199], v[220:223], v[80:83]
	v_mfma_f32_16x16x32_bf16 v[68:71], v[184:187], v[228:231], v[68:71]
	v_mfma_f32_16x16x32_bf16 v[64:67], v[196:199], v[228:231], v[64:67]
	s_barrier
	s_add_i32 s6, s26, s67
	s_mov_b32 m0, s6
	ds_read_b128 v[200:203], v163 offset:16384
	ds_read_b128 v[204:207], v163 offset:17408
	ds_read_b128 v[208:211], v163 offset:18432
	ds_read_b128 v[212:215], v163 offset:19456
	ds_read_b128 v[216:219], v163 offset:20480
	global_load_lds_dwordx4 v130, s[78:79]
	s_add_i32 m0, s6, 0x2000
	s_add_u32 s6, s78, 0x30000
	s_addc_u32 s7, s79, 0
	s_add_i32 s58, s74, s67
	global_load_lds_dwordx4 v134, s[78:79]
	s_mov_b32 m0, s58
	s_nop 0
	global_load_lds_dwordx4 v130, s[6:7]
	s_add_i32 m0, s58, 0x2000
	ds_read_b128 v[228:231], v163 offset:23552
	global_load_lds_dwordx4 v134, s[6:7]
	s_mov_b32 m0, s76
	ds_read_b128 v[224:227], v163 offset:22528
	global_load_lds_dwordx4 v128, s[80:81]
	s_mov_b32 m0, s77
	ds_read_b128 v[220:223], v163 offset:21504
	global_load_lds_dwordx4 v132, s[80:81]
	s_waitcnt vmcnt(8)
	s_waitcnt lgkmcnt(0)
	s_barrier
	s_waitcnt lgkmcnt(0)
	v_mfma_f32_16x16x32_bf16 v[60:63], v[144:147], v[200:203], v[60:63]
	v_mfma_f32_16x16x32_bf16 v[56:59], v[172:175], v[200:203], v[56:59]
	v_mfma_f32_16x16x32_bf16 v[44:47], v[144:147], v[208:211], v[44:47]
	v_mfma_f32_16x16x32_bf16 v[40:43], v[172:175], v[208:211], v[40:43]
	v_mfma_f32_16x16x32_bf16 v[28:31], v[144:147], v[216:219], v[28:31]
	v_mfma_f32_16x16x32_bf16 v[24:27], v[172:175], v[216:219], v[24:27]
	v_mfma_f32_16x16x32_bf16 v[12:15], v[144:147], v[224:227], v[12:15]
	v_mfma_f32_16x16x32_bf16 v[8:11], v[172:175], v[224:227], v[8:11]
	v_mfma_f32_16x16x32_bf16 v[60:63], v[168:171], v[204:207], v[60:63]
	v_mfma_f32_16x16x32_bf16 v[56:59], v[176:179], v[204:207], v[56:59]
	v_mfma_f32_16x16x32_bf16 v[44:47], v[168:171], v[212:215], v[44:47]
	v_mfma_f32_16x16x32_bf16 v[40:43], v[176:179], v[212:215], v[40:43]
	v_mfma_f32_16x16x32_bf16 v[28:31], v[168:171], v[220:223], v[28:31]
	v_mfma_f32_16x16x32_bf16 v[24:27], v[176:179], v[220:223], v[24:27]
	v_mfma_f32_16x16x32_bf16 v[12:15], v[168:171], v[228:231], v[12:15]
	v_mfma_f32_16x16x32_bf16 v[8:11], v[176:179], v[228:231], v[8:11]
	v_mfma_f32_16x16x32_bf16 v[52:55], v[180:183], v[200:203], v[52:55]
	v_mfma_f32_16x16x32_bf16 v[48:51], v[188:191], v[200:203], v[48:51]
	v_mfma_f32_16x16x32_bf16 v[36:39], v[180:183], v[208:211], v[36:39]
	v_mfma_f32_16x16x32_bf16 v[32:35], v[188:191], v[208:211], v[32:35]
	v_mfma_f32_16x16x32_bf16 v[20:23], v[180:183], v[216:219], v[20:23]
	v_mfma_f32_16x16x32_bf16 v[16:19], v[188:191], v[216:219], v[16:19]
	v_mfma_f32_16x16x32_bf16 v[4:7], v[180:183], v[224:227], v[4:7]
	v_mfma_f32_16x16x32_bf16 v[0:3], v[188:191], v[224:227], v[0:3]
	v_mfma_f32_16x16x32_bf16 v[52:55], v[184:187], v[204:207], v[52:55]
	v_mfma_f32_16x16x32_bf16 v[48:51], v[196:199], v[204:207], v[48:51]
	v_mfma_f32_16x16x32_bf16 v[36:39], v[184:187], v[212:215], v[36:39]
	v_mfma_f32_16x16x32_bf16 v[32:35], v[196:199], v[212:215], v[32:35]
	v_mfma_f32_16x16x32_bf16 v[20:23], v[184:187], v[220:223], v[20:23]
	v_mfma_f32_16x16x32_bf16 v[16:19], v[196:199], v[220:223], v[16:19]
	v_mfma_f32_16x16x32_bf16 v[4:7], v[184:187], v[228:231], v[4:7]
	v_mfma_f32_16x16x32_bf16 v[0:3], v[196:199], v[228:231], v[0:3]
	s_barrier
; #define PG8_STAGE(bufoff, gbase, voff) do { _Pragma("unroll") for (int _i = 0; _i < 2; ++_i) \
;         __builtin_amdgcn_global_load_lds((const unsigned*)((const char*)(gbase) + (voff)[_i]), (PG8_LAS unsigned*)(lds + (bufoff) + ldsw + _i * 8192), 16, 0, 0); } while (0)
; #define PG8_LDA(dst, b, h) do { _Pragma("unroll") for (int m = 0; m < 4; ++m) _Pragma("unroll") for (int k = 0; k < 2; ++k) dst[m][k] = *(const PG8_LAS bf16x8*)(lds + PG8_SA(b, h) + aoff + m * 2048 + k * 1024); } while (0)
; #define PG8_LDB(dst, b, h) do { _Pragma("unroll") for (int n = 0; n < 2; ++n) _Pragma("unroll") for (int k = 0; k < 2; ++k) dst[n][k] = *(const PG8_LAS bf16x8*)(lds + PG8_SB(b, h) + boff + n * 2048 + k * 1024); } while (0)
; #define PG8_MMA(ai, bj, At, Bt) do { __builtin_amdgcn_s_setprio(1); _Pragma("unroll") for (int m = 0; m < 4; ++m) _Pragma("unroll") for (int n = 0; n < 2; ++n) _Pragma("unroll") for (int k = 0; k < 2; ++k) \
;         acc[ai][bj][m][n] = __builtin_amdgcn_mfma_f32_16x16x32_bf16(Bt[n][k], At[m][k], acc[ai][bj][m][n], 0, 0, 0); __builtin_amdgcn_s_setprio(0); } while (0)
; #define PG8_WAIT_V(n) asm volatile("s_waitcnt vmcnt(" #n ")" ::: "memory")
; #define PG8_WAIT_L(n) asm volatile("s_waitcnt lgkmcnt(" #n ")" ::: "memory")
; #define PG8_BAR __builtin_amdgcn_s_barrier()
; #define PG8_SCHED __builtin_amdgcn_sched_barrier(0)
; template <class Epi, class Sched, bool ALIGN_EPI = false, bool SP2 = false>
; __device__ __forceinline__ void gemm_phase(PG8_LAS unsigned char* lds, const Gemm g, const Sched& S, const Epi& E) {
;     ...
;             PG8_LDB(B0, 1, 0); PG8_LDB(B1, 1, 1); PG8_SCHED; PG8_LDA(At, 1, 0); PG8_STAGE(PG8_SA(0, 1), a2 + hstep, voffA);
;             PG8_WAIT_V(8); PG8_WAIT_L(0); PG8_BAR; PG8_MMA(0, 0, At, B0); PG8_MMA(0, 1, At, B1); PG8_BAR; PG8_SCHED;
;             PG8_LDA(At, 1, 1); PG8_STAGE(PG8_SB(1, 0), b3, voffB); PG8_STAGE(PG8_SB(1, 1), b3 + hstep, voffB); PG8_STAGE(PG8_SA(1, 0), a3, voffA);
;             PG8_WAIT_V(8); PG8_WAIT_L(0); PG8_BAR; PG8_MMA(1, 0, At, B0); PG8_MMA(1, 1, At, B1); PG8_BAR; PG8_SCHED;
	s_add_i32 s58, 0, 0x18000
	v_add_u32_e32 v167, s58, v156
	s_add_i32 s59, 0, 0x1c000
	ds_read_b128 v[144:147], v167
	ds_read_b128 v[168:171], v167 offset:1024
	ds_read_b128 v[172:175], v167 offset:2048
	ds_read_b128 v[176:179], v167 offset:3072
	v_add_u32_e32 v167, s59, v156
	ds_read_b128 v[180:183], v167
	ds_read_b128 v[184:187], v167 offset:1024
	ds_read_b128 v[188:191], v167 offset:2048
	ds_read_b128 v[196:199], v167 offset:3072
	s_add_u32 s6, s80, 0x30000
	s_addc_u32 s7, s81, 0
	s_mov_b32 m0, s36
	ds_read_b128 v[200:203], v163 offset:32768
	ds_read_b128 v[204:207], v163 offset:33792
	ds_read_b128 v[208:211], v163 offset:34816
	ds_read_b128 v[212:215], v163 offset:35840
	ds_read_b128 v[216:219], v163 offset:36864
	ds_read_b128 v[220:223], v163 offset:37888
	ds_read_b128 v[224:227], v163 offset:38912
	global_load_lds_dwordx4 v128, s[6:7]
	s_mov_b32 m0, s37
	ds_read_b128 v[228:231], v163 offset:39936
	global_load_lds_dwordx4 v132, s[6:7]
	s_waitcnt vmcnt(8)
	s_waitcnt lgkmcnt(0)
	s_barrier
	s_waitcnt lgkmcnt(0)
	v_mfma_f32_16x16x32_bf16 v[124:127], v[144:147], v[200:203], v[124:127]
	v_mfma_f32_16x16x32_bf16 v[120:123], v[172:175], v[200:203], v[120:123]
	v_mfma_f32_16x16x32_bf16 v[108:111], v[144:147], v[208:211], v[108:111]
	v_mfma_f32_16x16x32_bf16 v[104:107], v[172:175], v[208:211], v[104:107]
	v_mfma_f32_16x16x32_bf16 v[92:95], v[144:147], v[216:219], v[92:95]
	v_mfma_f32_16x16x32_bf16 v[88:91], v[172:175], v[216:219], v[88:91]
	v_mfma_f32_16x16x32_bf16 v[76:79], v[144:147], v[224:227], v[76:79]
	v_mfma_f32_16x16x32_bf16 v[72:75], v[172:175], v[224:227], v[72:75]
	v_mfma_f32_16x16x32_bf16 v[124:127], v[168:171], v[204:207], v[124:127]
	v_mfma_f32_16x16x32_bf16 v[120:123], v[176:179], v[204:207], v[120:123]
	v_mfma_f32_16x16x32_bf16 v[108:111], v[168:171], v[212:215], v[108:111]
	v_mfma_f32_16x16x32_bf16 v[104:107], v[176:179], v[212:215], v[104:107]
	v_mfma_f32_16x16x32_bf16 v[92:95], v[168:171], v[220:223], v[92:95]
	v_mfma_f32_16x16x32_bf16 v[88:91], v[176:179], v[220:223], v[88:91]
	v_mfma_f32_16x16x32_bf16 v[76:79], v[168:171], v[228:231], v[76:79]
	v_mfma_f32_16x16x32_bf16 v[72:75], v[176:179], v[228:231], v[72:75]
	v_mfma_f32_16x16x32_bf16 v[116:119], v[180:183], v[200:203], v[116:119]
	v_mfma_f32_16x16x32_bf16 v[112:115], v[188:191], v[200:203], v[112:115]
	v_mfma_f32_16x16x32_bf16 v[100:103], v[180:183], v[208:211], v[100:103]
	v_mfma_f32_16x16x32_bf16 v[96:99], v[188:191], v[208:211], v[96:99]
	v_mfma_f32_16x16x32_bf16 v[84:87], v[180:183], v[216:219], v[84:87]
	v_mfma_f32_16x16x32_bf16 v[80:83], v[188:191], v[216:219], v[80:83]
	v_mfma_f32_16x16x32_bf16 v[68:71], v[180:183], v[224:227], v[68:71]
	v_mfma_f32_16x16x32_bf16 v[64:67], v[188:191], v[224:227], v[64:67]
	v_mfma_f32_16x16x32_bf16 v[116:119], v[184:187], v[204:207], v[116:119]
	v_mfma_f32_16x16x32_bf16 v[112:115], v[196:199], v[204:207], v[112:115]
	v_mfma_f32_16x16x32_bf16 v[100:103], v[184:187], v[212:215], v[100:103]
	v_mfma_f32_16x16x32_bf16 v[96:99], v[196:199], v[212:215], v[96:99]
	v_mfma_f32_16x16x32_bf16 v[84:87], v[184:187], v[220:223], v[84:87]
	v_mfma_f32_16x16x32_bf16 v[80:83], v[196:199], v[220:223], v[80:83]
	v_mfma_f32_16x16x32_bf16 v[68:71], v[184:187], v[228:231], v[68:71]
	v_mfma_f32_16x16x32_bf16 v[64:67], v[196:199], v[228:231], v[64:67]
	s_barrier
	s_add_i32 s6, s58, s67
	s_add_u32 s98, s78, 0x80
	s_addc_u32 s99, s79, 0
	s_add_u32 s100, s80, 0x80
	s_addc_u32 s101, s81, 0
	s_mov_b32 m0, s6
	ds_read_b128 v[200:203], v163 offset:49152
	ds_read_b128 v[204:207], v163 offset:50176
	ds_read_b128 v[208:211], v163 offset:51200
	ds_read_b128 v[212:215], v163 offset:52224
	global_load_lds_dwordx4 v130, s[98:99]
	s_add_i32 m0, s6, 0x2000
	s_add_u32 s6, s78, 0x30080
	s_addc_u32 s7, s79, 0
	s_add_i32 s58, s59, s67
	global_load_lds_dwordx4 v134, s[98:99]
	s_mov_b32 m0, s58
	ds_read_b128 v[228:231], v163 offset:56320
	global_load_lds_dwordx4 v130, s[6:7]
	s_add_i32 m0, s58, 0x2000
	ds_read_b128 v[224:227], v163 offset:55296
	global_load_lds_dwordx4 v134, s[6:7]
	s_mov_b32 m0, s31
	ds_read_b128 v[220:223], v163 offset:54272
	global_load_lds_dwordx4 v128, s[100:101]
	s_mov_b32 m0, s4
	ds_read_b128 v[216:219], v163 offset:53248
	global_load_lds_dwordx4 v132, s[100:101]
	s_waitcnt vmcnt(8)
	s_waitcnt lgkmcnt(0)
	s_barrier
	s_waitcnt lgkmcnt(0)
	v_mfma_f32_16x16x32_bf16 v[60:63], v[144:147], v[200:203], v[60:63]
	v_mfma_f32_16x16x32_bf16 v[56:59], v[172:175], v[200:203], v[56:59]
	v_mfma_f32_16x16x32_bf16 v[44:47], v[144:147], v[208:211], v[44:47]
	v_mfma_f32_16x16x32_bf16 v[40:43], v[172:175], v[208:211], v[40:43]
	v_mfma_f32_16x16x32_bf16 v[28:31], v[144:147], v[216:219], v[28:31]
	v_mfma_f32_16x16x32_bf16 v[24:27], v[172:175], v[216:219], v[24:27]
	v_mfma_f32_16x16x32_bf16 v[12:15], v[144:147], v[224:227], v[12:15]
	v_mfma_f32_16x16x32_bf16 v[8:11], v[172:175], v[224:227], v[8:11]
	v_mfma_f32_16x16x32_bf16 v[60:63], v[168:171], v[204:207], v[60:63]
	v_mfma_f32_16x16x32_bf16 v[56:59], v[176:179], v[204:207], v[56:59]
	v_mfma_f32_16x16x32_bf16 v[44:47], v[168:171], v[212:215], v[44:47]
	v_mfma_f32_16x16x32_bf16 v[40:43], v[176:179], v[212:215], v[40:43]
	v_mfma_f32_16x16x32_bf16 v[28:31], v[168:171], v[220:223], v[28:31]
	v_mfma_f32_16x16x32_bf16 v[24:27], v[176:179], v[220:223], v[24:27]
	v_mfma_f32_16x16x32_bf16 v[12:15], v[168:171], v[228:231], v[12:15]
	v_mfma_f32_16x16x32_bf16 v[8:11], v[176:179], v[228:231], v[8:11]
	v_mfma_f32_16x16x32_bf16 v[52:55], v[180:183], v[200:203], v[52:55]
	v_mfma_f32_16x16x32_bf16 v[48:51], v[188:191], v[200:203], v[48:51]
	v_mfma_f32_16x16x32_bf16 v[36:39], v[180:183], v[208:211], v[36:39]
	v_mfma_f32_16x16x32_bf16 v[32:35], v[188:191], v[208:211], v[32:35]
	v_mfma_f32_16x16x32_bf16 v[20:23], v[180:183], v[216:219], v[20:23]
	v_mfma_f32_16x16x32_bf16 v[16:19], v[188:191], v[216:219], v[16:19]
	v_mfma_f32_16x16x32_bf16 v[4:7], v[180:183], v[224:227], v[4:7]
	v_mfma_f32_16x16x32_bf16 v[0:3], v[188:191], v[224:227], v[0:3]
	v_mfma_f32_16x16x32_bf16 v[52:55], v[184:187], v[204:207], v[52:55]
	v_mfma_f32_16x16x32_bf16 v[48:51], v[196:199], v[204:207], v[48:51]
	v_mfma_f32_16x16x32_bf16 v[36:39], v[184:187], v[212:215], v[36:39]
	v_mfma_f32_16x16x32_bf16 v[32:35], v[196:199], v[212:215], v[32:35]
	v_mfma_f32_16x16x32_bf16 v[20:23], v[184:187], v[220:223], v[20:23]
	v_mfma_f32_16x16x32_bf16 v[16:19], v[196:199], v[220:223], v[16:19]
	v_mfma_f32_16x16x32_bf16 v[4:7], v[184:187], v[228:231], v[4:7]
	v_mfma_f32_16x16x32_bf16 v[0:3], v[196:199], v[228:231], v[0:3]
	s_barrier
	s_add_i32 s72, s72, 2
	s_add_u32 s33, s33, 0x100
	s_addc_u32 vcc_lo, vcc_lo, 0
	s_cmp_gt_u32 s72, 9
	s_mov_b64 s[58:59], s[60:61]
	s_cbranch_scc0 .LBB0_777
	s_and_b64 vcc, exec, s[54:55]
	s_cbranch_vccz .LBB0_780
	s_barrier

; #define PG8_STAGE(bufoff, gbase, voff) do { _Pragma("unroll") for (int _i = 0; _i < 2; ++_i) \
;         __builtin_amdgcn_global_load_lds((const unsigned*)((const char*)(gbase) + (voff)[_i]), (PG8_LAS unsigned*)(lds + (bufoff) + ldsw + _i * 8192), 16, 0, 0); } while (0)
; #define PG8_LDA(dst, b, h) do { _Pragma("unroll") for (int m = 0; m < 4; ++m) _Pragma("unroll") for (int k = 0; k < 2; ++k) dst[m][k] = *(const PG8_LAS bf16x8*)(lds + PG8_SA(b, h) + aoff + m * 2048 + k * 1024); } while (0)
; #define PG8_LDB(dst, b, h) do { _Pragma("unroll") for (int n = 0; n < 2; ++n) _Pragma("unroll") for (int k = 0; k < 2; ++k) dst[n][k] = *(const PG8_LAS bf16x8*)(lds + PG8_SB(b, h) + boff + n * 2048 + k * 1024); } while (0)
; #define PG8_MMA(ai, bj, At, Bt) do { __builtin_amdgcn_s_setprio(1); _Pragma("unroll") for (int m = 0; m < 4; ++m) _Pragma("unroll") for (int n = 0; n < 2; ++n) _Pragma("unroll") for (int k = 0; k < 2; ++k) \
;         acc[ai][bj][m][n] = __builtin_amdgcn_mfma_f32_16x16x32_bf16(Bt[n][k], At[m][k], acc[ai][bj][m][n], 0, 0, 0); __builtin_amdgcn_s_setprio(0); } while (0)
; #define PG8_WAIT_V(n) asm volatile("s_waitcnt vmcnt(" #n ")" ::: "memory")
; #define PG8_WAIT_L(n) asm volatile("s_waitcnt lgkmcnt(" #n ")" ::: "memory")
; #define PG8_BAR __builtin_amdgcn_s_barrier()
; #define PG8_SCHED __builtin_amdgcn_sched_barrier(0)
; template <class Epi, class Sched, bool ALIGN_EPI = false, bool SP2 = false>
; __device__ __forceinline__ void gemm_phase(PG8_LAS unsigned char* lds, const Gemm g, const Sched& S, const Epi& E) {
;     ...
;             const char* a1 = cA + (size_t)(t + 1) * kstep;
;             const char* a2 = last ? nA : cA + (size_t)(t + 2) * kstep; const char* b2 = last ? nB : cB + (size_t)(t + 2) * kstep;
;             const char* a3 = a2 + kstep; const char* b3 = b2 + kstep;
;     ...
;             PG8_LDB(B0, 0, 0); PG8_LDB(B1, 0, 1); PG8_SCHED; PG8_LDA(At, 0, 0); PG8_STAGE(PG8_SA(1, 1), a1 + hstep, voffA);
;             PG8_WAIT_V(8); PG8_WAIT_L(0); PG8_BAR; PG8_MMA(0, 0, At, B0); PG8_MMA(0, 1, At, B1); PG8_BAR; PG8_SCHED;
;             PG8_LDA(At, 0, 1); PG8_STAGE(PG8_SB(0, 0), b2, voffB); PG8_STAGE(PG8_SB(0, 1), b2 + hstep, voffB); PG8_STAGE(PG8_SA(0, 0), a2, voffA);
;             PG8_WAIT_V(8); PG8_WAIT_L(0); PG8_BAR; PG8_MMA(1, 0, At, B0); PG8_MMA(1, 1, At, B1); PG8_BAR; PG8_SCHED;
.LBB0_901:
	ds_read_b128 v[144:147], v159
	ds_read_b128 v[168:171], v159 offset:1024
	ds_read_b128 v[172:175], v159 offset:2048
	ds_read_b128 v[176:179], v159 offset:3072
	ds_read_b128 v[180:183], v163
	ds_read_b128 v[184:187], v163 offset:1024
	ds_read_b128 v[188:191], v163 offset:2048
	ds_read_b128 v[196:199], v163 offset:3072
	s_add_u32 s6, s56, 0xfffc0080
	s_addc_u32 s7, s57, -1
	s_cmp_eq_u32 s72, 12
	s_cselect_b32 s61, s49, s7
	s_cselect_b32 s60, s76, s6
	s_cselect_b32 s59, s41, s33
	s_cselect_b32 s58, s77, s78
	s_add_i32 m0, s30, 0xc000
	ds_read_b128 v[200:203], v166
	ds_read_b128 v[204:207], v166 offset:1024
	ds_read_b128 v[208:211], v166 offset:2048
	ds_read_b128 v[212:215], v166 offset:3072
	ds_read_b128 v[216:219], v166 offset:4096
	ds_read_b128 v[220:223], v166 offset:5120
	ds_read_b128 v[224:227], v166 offset:6144
	global_load_lds_dwordx4 v136, s[56:57]
	s_add_i32 m0, s30, 0xe000
	ds_read_b128 v[228:231], v166 offset:7168
	global_load_lds_dwordx4 v138, s[56:57]
	s_waitcnt vmcnt(8)
	s_waitcnt lgkmcnt(0)
	s_barrier
	s_waitcnt lgkmcnt(0)
	v_mfma_f32_16x16x32_bf16 v[124:127], v[144:147], v[200:203], v[124:127]
	v_mfma_f32_16x16x32_bf16 v[116:119], v[172:175], v[200:203], v[116:119]
	v_mfma_f32_16x16x32_bf16 v[108:111], v[144:147], v[208:211], v[108:111]
	v_mfma_f32_16x16x32_bf16 v[100:103], v[172:175], v[208:211], v[100:103]
	v_mfma_f32_16x16x32_bf16 v[92:95], v[144:147], v[216:219], v[92:95]
	v_mfma_f32_16x16x32_bf16 v[84:87], v[172:175], v[216:219], v[84:87]
	v_mfma_f32_16x16x32_bf16 v[76:79], v[144:147], v[224:227], v[76:79]
	v_mfma_f32_16x16x32_bf16 v[68:71], v[172:175], v[224:227], v[68:71]
	v_mfma_f32_16x16x32_bf16 v[124:127], v[168:171], v[204:207], v[124:127]
	v_mfma_f32_16x16x32_bf16 v[116:119], v[176:179], v[204:207], v[116:119]
	v_mfma_f32_16x16x32_bf16 v[108:111], v[168:171], v[212:215], v[108:111]
	v_mfma_f32_16x16x32_bf16 v[100:103], v[176:179], v[212:215], v[100:103]
	v_mfma_f32_16x16x32_bf16 v[92:95], v[168:171], v[220:223], v[92:95]
	v_mfma_f32_16x16x32_bf16 v[84:87], v[176:179], v[220:223], v[84:87]
	v_mfma_f32_16x16x32_bf16 v[76:79], v[168:171], v[228:231], v[76:79]
	v_mfma_f32_16x16x32_bf16 v[68:71], v[176:179], v[228:231], v[68:71]
	v_mfma_f32_16x16x32_bf16 v[120:123], v[180:183], v[200:203], v[120:123]
	v_mfma_f32_16x16x32_bf16 v[112:115], v[188:191], v[200:203], v[112:115]
	v_mfma_f32_16x16x32_bf16 v[104:107], v[180:183], v[208:211], v[104:107]
	v_mfma_f32_16x16x32_bf16 v[96:99], v[188:191], v[208:211], v[96:99]
	v_mfma_f32_16x16x32_bf16 v[88:91], v[180:183], v[216:219], v[88:91]
	v_mfma_f32_16x16x32_bf16 v[80:83], v[188:191], v[216:219], v[80:83]
	v_mfma_f32_16x16x32_bf16 v[72:75], v[180:183], v[224:227], v[72:75]
	v_mfma_f32_16x16x32_bf16 v[64:67], v[188:191], v[224:227], v[64:67]
	v_mfma_f32_16x16x32_bf16 v[120:123], v[184:187], v[204:207], v[120:123]
	v_mfma_f32_16x16x32_bf16 v[112:115], v[196:199], v[204:207], v[112:115]
	v_mfma_f32_16x16x32_bf16 v[104:107], v[184:187], v[212:215], v[104:107]
	v_mfma_f32_16x16x32_bf16 v[96:99], v[196:199], v[212:215], v[96:99]
	v_mfma_f32_16x16x32_bf16 v[88:91], v[184:187], v[220:223], v[88:91]
	v_mfma_f32_16x16x32_bf16 v[80:83], v[196:199], v[220:223], v[80:83]
	v_mfma_f32_16x16x32_bf16 v[72:75], v[184:187], v[228:231], v[72:75]
	v_mfma_f32_16x16x32_bf16 v[64:67], v[196:199], v[228:231], v[64:67]
	s_barrier
	s_add_i32 s6, s67, s27
	s_mov_b32 m0, s6
	ds_read_b128 v[200:203], v166 offset:16384
	ds_read_b128 v[204:207], v166 offset:17408
	ds_read_b128 v[208:211], v166 offset:18432
	ds_read_b128 v[212:215], v166 offset:19456
	ds_read_b128 v[216:219], v166 offset:20480
	global_load_lds_dwordx4 v132, s[58:59]
	s_add_i32 m0, s6, 0x2000
	s_add_u32 s6, s58, 0x40000
	s_addc_u32 s7, s59, 0
	s_add_i32 s73, s68, s27
	global_load_lds_dwordx4 v128, s[58:59]
	s_mov_b32 m0, s73
	s_nop 0
	global_load_lds_dwordx4 v132, s[6:7]
	s_add_i32 m0, s73, 0x2000
	ds_read_b128 v[228:231], v166 offset:23552
	global_load_lds_dwordx4 v128, s[6:7]
	s_mov_b32 m0, s30
	ds_read_b128 v[224:227], v166 offset:22528
	global_load_lds_dwordx4 v134, s[60:61]
	s_mov_b32 m0, s31
	ds_read_b128 v[220:223], v166 offset:21504
	global_load_lds_dwordx4 v130, s[60:61]
	s_waitcnt vmcnt(8)
	s_waitcnt lgkmcnt(0)
	s_barrier
	s_waitcnt lgkmcnt(0)
	v_mfma_f32_16x16x32_bf16 v[60:63], v[144:147], v[200:203], v[60:63]
	v_mfma_f32_16x16x32_bf16 v[52:55], v[172:175], v[200:203], v[52:55]
	v_mfma_f32_16x16x32_bf16 v[44:47], v[144:147], v[208:211], v[44:47]
	v_mfma_f32_16x16x32_bf16 v[36:39], v[172:175], v[208:211], v[36:39]
	v_mfma_f32_16x16x32_bf16 v[28:31], v[144:147], v[216:219], v[28:31]
	v_mfma_f32_16x16x32_bf16 v[20:23], v[172:175], v[216:219], v[20:23]
	v_mfma_f32_16x16x32_bf16 v[12:15], v[144:147], v[224:227], v[12:15]
	v_mfma_f32_16x16x32_bf16 v[4:7], v[172:175], v[224:227], v[4:7]
	v_mfma_f32_16x16x32_bf16 v[60:63], v[168:171], v[204:207], v[60:63]
	v_mfma_f32_16x16x32_bf16 v[52:55], v[176:179], v[204:207], v[52:55]
	v_mfma_f32_16x16x32_bf16 v[44:47], v[168:171], v[212:215], v[44:47]
	v_mfma_f32_16x16x32_bf16 v[36:39], v[176:179], v[212:215], v[36:39]
	v_mfma_f32_16x16x32_bf16 v[28:31], v[168:171], v[220:223], v[28:31]
	v_mfma_f32_16x16x32_bf16 v[20:23], v[176:179], v[220:223], v[20:23]
	v_mfma_f32_16x16x32_bf16 v[12:15], v[168:171], v[228:231], v[12:15]
	v_mfma_f32_16x16x32_bf16 v[4:7], v[176:179], v[228:231], v[4:7]
	v_mfma_f32_16x16x32_bf16 v[56:59], v[180:183], v[200:203], v[56:59]
	v_mfma_f32_16x16x32_bf16 v[48:51], v[188:191], v[200:203], v[48:51]
	v_mfma_f32_16x16x32_bf16 v[40:43], v[180:183], v[208:211], v[40:43]
	v_mfma_f32_16x16x32_bf16 v[32:35], v[188:191], v[208:211], v[32:35]
	v_mfma_f32_16x16x32_bf16 v[24:27], v[180:183], v[216:219], v[24:27]
	v_mfma_f32_16x16x32_bf16 v[16:19], v[188:191], v[216:219], v[16:19]
	v_mfma_f32_16x16x32_bf16 v[8:11], v[180:183], v[224:227], v[8:11]
	v_mfma_f32_16x16x32_bf16 v[0:3], v[188:191], v[224:227], v[0:3]
	v_mfma_f32_16x16x32_bf16 v[56:59], v[184:187], v[204:207], v[56:59]
	v_mfma_f32_16x16x32_bf16 v[48:51], v[196:199], v[204:207], v[48:51]
	v_mfma_f32_16x16x32_bf16 v[40:43], v[184:187], v[212:215], v[40:43]
	v_mfma_f32_16x16x32_bf16 v[32:35], v[196:199], v[212:215], v[32:35]
	v_mfma_f32_16x16x32_bf16 v[24:27], v[184:187], v[220:223], v[24:27]
	v_mfma_f32_16x16x32_bf16 v[16:19], v[196:199], v[220:223], v[16:19]
	v_mfma_f32_16x16x32_bf16 v[8:11], v[184:187], v[228:231], v[8:11]
	v_mfma_f32_16x16x32_bf16 v[0:3], v[196:199], v[228:231], v[0:3]
	s_barrier
; #define PG8_STAGE(bufoff, gbase, voff) do { _Pragma("unroll") for (int _i = 0; _i < 2; ++_i) \
;         __builtin_amdgcn_global_load_lds((const unsigned*)((const char*)(gbase) + (voff)[_i]), (PG8_LAS unsigned*)(lds + (bufoff) + ldsw + _i * 8192), 16, 0, 0); } while (0)
; #define PG8_LDA(dst, b, h) do { _Pragma("unroll") for (int m = 0; m < 4; ++m) _Pragma("unroll") for (int k = 0; k < 2; ++k) dst[m][k] = *(const PG8_LAS bf16x8*)(lds + PG8_SA(b, h) + aoff + m * 2048 + k * 1024); } while (0)
; #define PG8_LDB(dst, b, h) do { _Pragma("unroll") for (int n = 0; n < 2; ++n) _Pragma("unroll") for (int k = 0; k < 2; ++k) dst[n][k] = *(const PG8_LAS bf16x8*)(lds + PG8_SB(b, h) + boff + n * 2048 + k * 1024); } while (0)
; #define PG8_MMA(ai, bj, At, Bt) do { __builtin_amdgcn_s_setprio(1); _Pragma("unroll") for (int m = 0; m < 4; ++m) _Pragma("unroll") for (int n = 0; n < 2; ++n) _Pragma("unroll") for (int k = 0; k < 2; ++k) \
;         acc[ai][bj][m][n] = __builtin_amdgcn_mfma_f32_16x16x32_bf16(Bt[n][k], At[m][k], acc[ai][bj][m][n], 0, 0, 0); __builtin_amdgcn_s_setprio(0); } while (0)
; #define PG8_WAIT_V(n) asm volatile("s_waitcnt vmcnt(" #n ")" ::: "memory")
; #define PG8_WAIT_L(n) asm volatile("s_waitcnt lgkmcnt(" #n ")" ::: "memory")
; #define PG8_BAR __builtin_amdgcn_s_barrier()
; #define PG8_SCHED __builtin_amdgcn_sched_barrier(0)
; template <class Epi, class Sched, bool ALIGN_EPI = false, bool SP2 = false>
; __device__ __forceinline__ void gemm_phase(PG8_LAS unsigned char* lds, const Gemm g, const Sched& S, const Epi& E) {
;     ...
;             PG8_LDB(B0, 1, 0); PG8_LDB(B1, 1, 1); PG8_SCHED; PG8_LDA(At, 1, 0); PG8_STAGE(PG8_SA(0, 1), a2 + hstep, voffA);
;             PG8_WAIT_V(8); PG8_WAIT_L(0); PG8_BAR; PG8_MMA(0, 0, At, B0); PG8_MMA(0, 1, At, B1); PG8_BAR; PG8_SCHED;
;             PG8_LDA(At, 1, 1); PG8_STAGE(PG8_SB(1, 0), b3, voffB); PG8_STAGE(PG8_SB(1, 1), b3 + hstep, voffB); PG8_STAGE(PG8_SA(1, 0), a3, voffA);
;             PG8_WAIT_V(8); PG8_WAIT_L(0); PG8_BAR; PG8_MMA(1, 0, At, B0); PG8_MMA(1, 1, At, B1); PG8_BAR; PG8_SCHED;
	s_add_i32 s73, 0, 0x18000
	v_add_u32_e32 v167, s73, v156
	s_add_i32 s79, 0, 0x1c000
	ds_read_b128 v[144:147], v167
	ds_read_b128 v[168:171], v167 offset:1024
	ds_read_b128 v[172:175], v167 offset:2048
	ds_read_b128 v[176:179], v167 offset:3072
	v_add_u32_e32 v167, s79, v156
	ds_read_b128 v[180:183], v167
	ds_read_b128 v[184:187], v167 offset:1024
	ds_read_b128 v[188:191], v167 offset:2048
	ds_read_b128 v[196:199], v167 offset:3072
	s_add_u32 s6, s60, 0x40000
	s_addc_u32 s7, s61, 0
	s_mov_b32 m0, s42
	ds_read_b128 v[200:203], v166 offset:32768
	ds_read_b128 v[204:207], v166 offset:33792
	ds_read_b128 v[208:211], v166 offset:34816
	ds_read_b128 v[212:215], v166 offset:35840
	ds_read_b128 v[216:219], v166 offset:36864
	ds_read_b128 v[220:223], v166 offset:37888
	ds_read_b128 v[224:227], v166 offset:38912
	global_load_lds_dwordx4 v134, s[6:7]
	s_mov_b32 m0, s43
	ds_read_b128 v[228:231], v166 offset:39936
	global_load_lds_dwordx4 v130, s[6:7]
	s_waitcnt vmcnt(8)
	s_waitcnt lgkmcnt(0)
	s_barrier
	s_waitcnt lgkmcnt(0)
	v_mfma_f32_16x16x32_bf16 v[124:127], v[144:147], v[200:203], v[124:127]
	v_mfma_f32_16x16x32_bf16 v[116:119], v[172:175], v[200:203], v[116:119]
	v_mfma_f32_16x16x32_bf16 v[108:111], v[144:147], v[208:211], v[108:111]
	v_mfma_f32_16x16x32_bf16 v[100:103], v[172:175], v[208:211], v[100:103]
	v_mfma_f32_16x16x32_bf16 v[92:95], v[144:147], v[216:219], v[92:95]
	v_mfma_f32_16x16x32_bf16 v[84:87], v[172:175], v[216:219], v[84:87]
	v_mfma_f32_16x16x32_bf16 v[76:79], v[144:147], v[224:227], v[76:79]
	v_mfma_f32_16x16x32_bf16 v[68:71], v[172:175], v[224:227], v[68:71]
	v_mfma_f32_16x16x32_bf16 v[124:127], v[168:171], v[204:207], v[124:127]
	v_mfma_f32_16x16x32_bf16 v[116:119], v[176:179], v[204:207], v[116:119]
	v_mfma_f32_16x16x32_bf16 v[108:111], v[168:171], v[212:215], v[108:111]
	v_mfma_f32_16x16x32_bf16 v[100:103], v[176:179], v[212:215], v[100:103]
	v_mfma_f32_16x16x32_bf16 v[92:95], v[168:171], v[220:223], v[92:95]
	v_mfma_f32_16x16x32_bf16 v[84:87], v[176:179], v[220:223], v[84:87]
	v_mfma_f32_16x16x32_bf16 v[76:79], v[168:171], v[228:231], v[76:79]
	v_mfma_f32_16x16x32_bf16 v[68:71], v[176:179], v[228:231], v[68:71]
	v_mfma_f32_16x16x32_bf16 v[120:123], v[180:183], v[200:203], v[120:123]
	v_mfma_f32_16x16x32_bf16 v[112:115], v[188:191], v[200:203], v[112:115]
	v_mfma_f32_16x16x32_bf16 v[104:107], v[180:183], v[208:211], v[104:107]
	v_mfma_f32_16x16x32_bf16 v[96:99], v[188:191], v[208:211], v[96:99]
	v_mfma_f32_16x16x32_bf16 v[88:91], v[180:183], v[216:219], v[88:91]
	v_mfma_f32_16x16x32_bf16 v[80:83], v[188:191], v[216:219], v[80:83]
	v_mfma_f32_16x16x32_bf16 v[72:75], v[180:183], v[224:227], v[72:75]
	v_mfma_f32_16x16x32_bf16 v[64:67], v[188:191], v[224:227], v[64:67]
	v_mfma_f32_16x16x32_bf16 v[120:123], v[184:187], v[204:207], v[120:123]
	v_mfma_f32_16x16x32_bf16 v[112:115], v[196:199], v[204:207], v[112:115]
	v_mfma_f32_16x16x32_bf16 v[104:107], v[184:187], v[212:215], v[104:107]
	v_mfma_f32_16x16x32_bf16 v[96:99], v[196:199], v[212:215], v[96:99]
	v_mfma_f32_16x16x32_bf16 v[88:91], v[184:187], v[220:223], v[88:91]
	v_mfma_f32_16x16x32_bf16 v[80:83], v[196:199], v[220:223], v[80:83]
	v_mfma_f32_16x16x32_bf16 v[72:75], v[184:187], v[228:231], v[72:75]
	v_mfma_f32_16x16x32_bf16 v[64:67], v[196:199], v[228:231], v[64:67]
	s_barrier
	s_add_i32 s6, s73, s27
	s_add_u32 s98, s58, 0x80
	s_addc_u32 s99, s59, 0
	s_add_u32 s100, s60, 0x80
	s_addc_u32 s101, s61, 0
	s_mov_b32 m0, s6
	ds_read_b128 v[200:203], v166 offset:49152
	ds_read_b128 v[204:207], v166 offset:50176
	ds_read_b128 v[208:211], v166 offset:51200
	ds_read_b128 v[212:215], v166 offset:52224
	global_load_lds_dwordx4 v132, s[98:99]
	s_add_i32 m0, s6, 0x2000
	s_add_u32 s6, s58, 0x40080
	s_addc_u32 s7, s59, 0
	s_add_i32 s58, s79, s27
	global_load_lds_dwordx4 v128, s[98:99]
	s_mov_b32 m0, s58
	ds_read_b128 v[228:231], v166 offset:56320
	global_load_lds_dwordx4 v132, s[6:7]
	s_add_i32 m0, s58, 0x2000
	ds_read_b128 v[224:227], v166 offset:55296
	global_load_lds_dwordx4 v128, s[6:7]
	s_mov_b32 m0, s44
	ds_read_b128 v[220:223], v166 offset:54272
	global_load_lds_dwordx4 v134, s[100:101]
	s_mov_b32 m0, s45
	ds_read_b128 v[216:219], v166 offset:53248
	global_load_lds_dwordx4 v130, s[100:101]
	s_waitcnt vmcnt(8)
	s_waitcnt lgkmcnt(0)
	s_barrier
	s_waitcnt lgkmcnt(0)
	v_mfma_f32_16x16x32_bf16 v[60:63], v[144:147], v[200:203], v[60:63]
	v_mfma_f32_16x16x32_bf16 v[52:55], v[172:175], v[200:203], v[52:55]
	v_mfma_f32_16x16x32_bf16 v[44:47], v[144:147], v[208:211], v[44:47]
	v_mfma_f32_16x16x32_bf16 v[36:39], v[172:175], v[208:211], v[36:39]
	v_mfma_f32_16x16x32_bf16 v[28:31], v[144:147], v[216:219], v[28:31]
	v_mfma_f32_16x16x32_bf16 v[20:23], v[172:175], v[216:219], v[20:23]
	v_mfma_f32_16x16x32_bf16 v[12:15], v[144:147], v[224:227], v[12:15]
	v_mfma_f32_16x16x32_bf16 v[4:7], v[172:175], v[224:227], v[4:7]
	v_mfma_f32_16x16x32_bf16 v[60:63], v[168:171], v[204:207], v[60:63]
	v_mfma_f32_16x16x32_bf16 v[52:55], v[176:179], v[204:207], v[52:55]
	v_mfma_f32_16x16x32_bf16 v[44:47], v[168:171], v[212:215], v[44:47]
	v_mfma_f32_16x16x32_bf16 v[36:39], v[176:179], v[212:215], v[36:39]
	v_mfma_f32_16x16x32_bf16 v[28:31], v[168:171], v[220:223], v[28:31]
	v_mfma_f32_16x16x32_bf16 v[20:23], v[176:179], v[220:223], v[20:23]
	v_mfma_f32_16x16x32_bf16 v[12:15], v[168:171], v[228:231], v[12:15]
	v_mfma_f32_16x16x32_bf16 v[4:7], v[176:179], v[228:231], v[4:7]
	v_mfma_f32_16x16x32_bf16 v[56:59], v[180:183], v[200:203], v[56:59]
	v_mfma_f32_16x16x32_bf16 v[48:51], v[188:191], v[200:203], v[48:51]
	v_mfma_f32_16x16x32_bf16 v[40:43], v[180:183], v[208:211], v[40:43]
	v_mfma_f32_16x16x32_bf16 v[32:35], v[188:191], v[208:211], v[32:35]
	v_mfma_f32_16x16x32_bf16 v[24:27], v[180:183], v[216:219], v[24:27]
	v_mfma_f32_16x16x32_bf16 v[16:19], v[188:191], v[216:219], v[16:19]
	v_mfma_f32_16x16x32_bf16 v[8:11], v[180:183], v[224:227], v[8:11]
	v_mfma_f32_16x16x32_bf16 v[0:3], v[188:191], v[224:227], v[0:3]
	v_mfma_f32_16x16x32_bf16 v[56:59], v[184:187], v[204:207], v[56:59]
	v_mfma_f32_16x16x32_bf16 v[48:51], v[196:199], v[204:207], v[48:51]
	v_mfma_f32_16x16x32_bf16 v[40:43], v[184:187], v[212:215], v[40:43]
	v_mfma_f32_16x16x32_bf16 v[32:35], v[196:199], v[212:215], v[32:35]
	v_mfma_f32_16x16x32_bf16 v[24:27], v[184:187], v[220:223], v[24:27]
	v_mfma_f32_16x16x32_bf16 v[16:19], v[196:199], v[220:223], v[16:19]
	v_mfma_f32_16x16x32_bf16 v[8:11], v[184:187], v[228:231], v[8:11]
	v_mfma_f32_16x16x32_bf16 v[0:3], v[196:199], v[228:231], v[0:3]
	s_barrier
	s_add_i32 s72, s72, 2
	s_add_u32 s56, s56, 0x100
	s_addc_u32 s57, s57, 0
	s_add_u32 s78, s78, 0x100
	s_addc_u32 s33, s33, 0
	s_cmp_gt_u32 s72, 13
	s_cbranch_scc0 .LBB0_901
	s_and_b64 vcc, exec, s[38:39]
	s_cbranch_vccz .LBB0_904
	s_barrier

; #define PG8_STAGE(bufoff, gbase, voff) do { _Pragma("unroll") for (int _i = 0; _i < 2; ++_i) \
;         __builtin_amdgcn_global_load_lds((const unsigned*)((const char*)(gbase) + (voff)[_i]), (PG8_LAS unsigned*)(lds + (bufoff) + ldsw + _i * 8192), 16, 0, 0); } while (0)
; #define PG8_LDA(dst, b, h) do { _Pragma("unroll") for (int m = 0; m < 4; ++m) _Pragma("unroll") for (int k = 0; k < 2; ++k) dst[m][k] = *(const PG8_LAS bf16x8*)(lds + PG8_SA(b, h) + aoff + m * 2048 + k * 1024); } while (0)
; #define PG8_LDB(dst, b, h) do { _Pragma("unroll") for (int n = 0; n < 2; ++n) _Pragma("unroll") for (int k = 0; k < 2; ++k) dst[n][k] = *(const PG8_LAS bf16x8*)(lds + PG8_SB(b, h) + boff + n * 2048 + k * 1024); } while (0)
; #define PG8_MMA(ai, bj, At, Bt) do { __builtin_amdgcn_s_setprio(1); _Pragma("unroll") for (int m = 0; m < 4; ++m) _Pragma("unroll") for (int n = 0; n < 2; ++n) _Pragma("unroll") for (int k = 0; k < 2; ++k) \
;         acc[ai][bj][m][n] = __builtin_amdgcn_mfma_f32_16x16x32_bf16(Bt[n][k], At[m][k], acc[ai][bj][m][n], 0, 0, 0); __builtin_amdgcn_s_setprio(0); } while (0)
; #define PG8_WAIT_V(n) asm volatile("s_waitcnt vmcnt(" #n ")" ::: "memory")
; #define PG8_WAIT_L(n) asm volatile("s_waitcnt lgkmcnt(" #n ")" ::: "memory")
; #define PG8_BAR __builtin_amdgcn_s_barrier()
; #define PG8_SCHED __builtin_amdgcn_sched_barrier(0)
; template <class Epi, class Sched, bool ALIGN_EPI = false, bool SP2 = false>
; __device__ __forceinline__ void gemm_phase(PG8_LAS unsigned char* lds, const Gemm g, const Sched& S, const Epi& E) {
;     ...
;             const char* a1 = cA + (size_t)(t + 1) * kstep;
;             const char* a2 = last ? nA : cA + (size_t)(t + 2) * kstep; const char* b2 = last ? nB : cB + (size_t)(t + 2) * kstep;
;             const char* a3 = a2 + kstep; const char* b3 = b2 + kstep;
;     ...
;             PG8_LDB(B0, 0, 0); PG8_LDB(B1, 0, 1); PG8_SCHED; PG8_LDA(At, 0, 0); PG8_STAGE(PG8_SA(1, 1), a1 + hstep, voffA);
;             PG8_WAIT_V(8); PG8_WAIT_L(0); PG8_BAR; PG8_MMA(0, 0, At, B0); PG8_MMA(0, 1, At, B1); PG8_BAR; PG8_SCHED;
;             PG8_LDA(At, 0, 1); PG8_STAGE(PG8_SB(0, 0), b2, voffB); PG8_STAGE(PG8_SB(0, 1), b2 + hstep, voffB); PG8_STAGE(PG8_SA(0, 0), a2, voffA);
;             PG8_WAIT_V(8); PG8_WAIT_L(0); PG8_BAR; PG8_MMA(1, 0, At, B0); PG8_MMA(1, 1, At, B1); PG8_BAR; PG8_SCHED;
.LBB0_1014:
	ds_read_b128 v[144:147], v158
	ds_read_b128 v[168:171], v158 offset:1024
	ds_read_b128 v[172:175], v158 offset:2048
	ds_read_b128 v[176:179], v158 offset:3072
	ds_read_b128 v[180:183], v159
	ds_read_b128 v[184:187], v159 offset:1024
	ds_read_b128 v[188:191], v159 offset:2048
	ds_read_b128 v[196:199], v159 offset:3072
	s_add_u32 s58, s56, 0x100
	s_addc_u32 s59, s57, 0
	s_cmp_eq_u32 s72, 40
	s_cselect_b32 s79, s51, s59
	s_cselect_b32 s78, s50, s58
	s_cselect_b32 s61, s55, s80
	s_cselect_b32 s60, s54, s33
	s_add_i32 m0, s45, 0xc000
	ds_read_b128 v[200:203], v163
	ds_read_b128 v[204:207], v163 offset:1024
	ds_read_b128 v[208:211], v163 offset:2048
	ds_read_b128 v[212:215], v163 offset:3072
	ds_read_b128 v[216:219], v163 offset:4096
	ds_read_b128 v[220:223], v163 offset:5120
	ds_read_b128 v[224:227], v163 offset:6144
	global_load_lds_dwordx4 v136, s[56:57]
	s_add_i32 m0, s45, 0xe000
	ds_read_b128 v[228:231], v163 offset:7168
	global_load_lds_dwordx4 v138, s[56:57]
	s_waitcnt vmcnt(8)
	s_waitcnt lgkmcnt(0)
	s_barrier
	s_waitcnt lgkmcnt(0)
	v_mfma_f32_16x16x32_bf16 v[124:127], v[144:147], v[200:203], v[124:127]
	v_mfma_f32_16x16x32_bf16 v[120:123], v[172:175], v[200:203], v[120:123]
	v_mfma_f32_16x16x32_bf16 v[108:111], v[144:147], v[208:211], v[108:111]
	v_mfma_f32_16x16x32_bf16 v[104:107], v[172:175], v[208:211], v[104:107]
	v_mfma_f32_16x16x32_bf16 v[92:95], v[144:147], v[216:219], v[92:95]
	v_mfma_f32_16x16x32_bf16 v[88:91], v[172:175], v[216:219], v[88:91]
	v_mfma_f32_16x16x32_bf16 v[76:79], v[144:147], v[224:227], v[76:79]
	v_mfma_f32_16x16x32_bf16 v[72:75], v[172:175], v[224:227], v[72:75]
	v_mfma_f32_16x16x32_bf16 v[124:127], v[168:171], v[204:207], v[124:127]
	v_mfma_f32_16x16x32_bf16 v[120:123], v[176:179], v[204:207], v[120:123]
	v_mfma_f32_16x16x32_bf16 v[108:111], v[168:171], v[212:215], v[108:111]
	v_mfma_f32_16x16x32_bf16 v[104:107], v[176:179], v[212:215], v[104:107]
	v_mfma_f32_16x16x32_bf16 v[92:95], v[168:171], v[220:223], v[92:95]
	v_mfma_f32_16x16x32_bf16 v[88:91], v[176:179], v[220:223], v[88:91]
	v_mfma_f32_16x16x32_bf16 v[76:79], v[168:171], v[228:231], v[76:79]
	v_mfma_f32_16x16x32_bf16 v[72:75], v[176:179], v[228:231], v[72:75]
	v_mfma_f32_16x16x32_bf16 v[116:119], v[180:183], v[200:203], v[116:119]
	v_mfma_f32_16x16x32_bf16 v[112:115], v[188:191], v[200:203], v[112:115]
	v_mfma_f32_16x16x32_bf16 v[100:103], v[180:183], v[208:211], v[100:103]
	v_mfma_f32_16x16x32_bf16 v[96:99], v[188:191], v[208:211], v[96:99]
	v_mfma_f32_16x16x32_bf16 v[84:87], v[180:183], v[216:219], v[84:87]
	v_mfma_f32_16x16x32_bf16 v[80:83], v[188:191], v[216:219], v[80:83]
	v_mfma_f32_16x16x32_bf16 v[68:71], v[180:183], v[224:227], v[68:71]
	v_mfma_f32_16x16x32_bf16 v[64:67], v[188:191], v[224:227], v[64:67]
	v_mfma_f32_16x16x32_bf16 v[116:119], v[184:187], v[204:207], v[116:119]
	v_mfma_f32_16x16x32_bf16 v[112:115], v[196:199], v[204:207], v[112:115]
	v_mfma_f32_16x16x32_bf16 v[100:103], v[184:187], v[212:215], v[100:103]
	v_mfma_f32_16x16x32_bf16 v[96:99], v[196:199], v[212:215], v[96:99]
	v_mfma_f32_16x16x32_bf16 v[84:87], v[184:187], v[220:223], v[84:87]
	v_mfma_f32_16x16x32_bf16 v[80:83], v[196:199], v[220:223], v[80:83]
	v_mfma_f32_16x16x32_bf16 v[68:71], v[184:187], v[228:231], v[68:71]
	v_mfma_f32_16x16x32_bf16 v[64:67], v[196:199], v[228:231], v[64:67]
	s_barrier
	s_add_i32 s6, s26, s44
	s_mov_b32 m0, s6
	ds_read_b128 v[200:203], v163 offset:16384
	ds_read_b128 v[204:207], v163 offset:17408
	ds_read_b128 v[208:211], v163 offset:18432
	ds_read_b128 v[212:215], v163 offset:19456
	ds_read_b128 v[216:219], v163 offset:20480
	global_load_lds_dwordx4 v130, s[60:61]
	s_add_i32 m0, s6, 0x2000
	s_add_u32 s6, s60, 0xb0000
	s_addc_u32 s7, s61, 0
	s_add_i32 s56, s74, s44
	global_load_lds_dwordx4 v134, s[60:61]
	s_mov_b32 m0, s56
	s_nop 0
	global_load_lds_dwordx4 v130, s[6:7]
	s_add_i32 m0, s56, 0x2000
	ds_read_b128 v[228:231], v163 offset:23552
	global_load_lds_dwordx4 v134, s[6:7]
	s_mov_b32 m0, s45
	ds_read_b128 v[224:227], v163 offset:22528
	global_load_lds_dwordx4 v128, s[78:79]
	s_mov_b32 m0, s67
	ds_read_b128 v[220:223], v163 offset:21504
	global_load_lds_dwordx4 v132, s[78:79]
	s_waitcnt vmcnt(8)
	s_waitcnt lgkmcnt(0)
	s_barrier
	s_waitcnt lgkmcnt(0)
	v_mfma_f32_16x16x32_bf16 v[60:63], v[144:147], v[200:203], v[60:63]
	v_mfma_f32_16x16x32_bf16 v[56:59], v[172:175], v[200:203], v[56:59]
	v_mfma_f32_16x16x32_bf16 v[44:47], v[144:147], v[208:211], v[44:47]
	v_mfma_f32_16x16x32_bf16 v[40:43], v[172:175], v[208:211], v[40:43]
	v_mfma_f32_16x16x32_bf16 v[28:31], v[144:147], v[216:219], v[28:31]
	v_mfma_f32_16x16x32_bf16 v[24:27], v[172:175], v[216:219], v[24:27]
	v_mfma_f32_16x16x32_bf16 v[12:15], v[144:147], v[224:227], v[12:15]
	v_mfma_f32_16x16x32_bf16 v[8:11], v[172:175], v[224:227], v[8:11]
	v_mfma_f32_16x16x32_bf16 v[60:63], v[168:171], v[204:207], v[60:63]
	v_mfma_f32_16x16x32_bf16 v[56:59], v[176:179], v[204:207], v[56:59]
	v_mfma_f32_16x16x32_bf16 v[44:47], v[168:171], v[212:215], v[44:47]
	v_mfma_f32_16x16x32_bf16 v[40:43], v[176:179], v[212:215], v[40:43]
	v_mfma_f32_16x16x32_bf16 v[28:31], v[168:171], v[220:223], v[28:31]
	v_mfma_f32_16x16x32_bf16 v[24:27], v[176:179], v[220:223], v[24:27]
	v_mfma_f32_16x16x32_bf16 v[12:15], v[168:171], v[228:231], v[12:15]
	v_mfma_f32_16x16x32_bf16 v[8:11], v[176:179], v[228:231], v[8:11]
	v_mfma_f32_16x16x32_bf16 v[52:55], v[180:183], v[200:203], v[52:55]
	v_mfma_f32_16x16x32_bf16 v[48:51], v[188:191], v[200:203], v[48:51]
	v_mfma_f32_16x16x32_bf16 v[36:39], v[180:183], v[208:211], v[36:39]
	v_mfma_f32_16x16x32_bf16 v[32:35], v[188:191], v[208:211], v[32:35]
	v_mfma_f32_16x16x32_bf16 v[20:23], v[180:183], v[216:219], v[20:23]
	v_mfma_f32_16x16x32_bf16 v[16:19], v[188:191], v[216:219], v[16:19]
	v_mfma_f32_16x16x32_bf16 v[4:7], v[180:183], v[224:227], v[4:7]
	v_mfma_f32_16x16x32_bf16 v[0:3], v[188:191], v[224:227], v[0:3]
	v_mfma_f32_16x16x32_bf16 v[52:55], v[184:187], v[204:207], v[52:55]
	v_mfma_f32_16x16x32_bf16 v[48:51], v[196:199], v[204:207], v[48:51]
	v_mfma_f32_16x16x32_bf16 v[36:39], v[184:187], v[212:215], v[36:39]
	v_mfma_f32_16x16x32_bf16 v[32:35], v[196:199], v[212:215], v[32:35]
	v_mfma_f32_16x16x32_bf16 v[20:23], v[184:187], v[220:223], v[20:23]
	v_mfma_f32_16x16x32_bf16 v[16:19], v[196:199], v[220:223], v[16:19]
	v_mfma_f32_16x16x32_bf16 v[4:7], v[184:187], v[228:231], v[4:7]
	v_mfma_f32_16x16x32_bf16 v[0:3], v[196:199], v[228:231], v[0:3]
	s_barrier
; #define PG8_STAGE(bufoff, gbase, voff) do { _Pragma("unroll") for (int _i = 0; _i < 2; ++_i) \
;         __builtin_amdgcn_global_load_lds((const unsigned*)((const char*)(gbase) + (voff)[_i]), (PG8_LAS unsigned*)(lds + (bufoff) + ldsw + _i * 8192), 16, 0, 0); } while (0)
; #define PG8_LDA(dst, b, h) do { _Pragma("unroll") for (int m = 0; m < 4; ++m) _Pragma("unroll") for (int k = 0; k < 2; ++k) dst[m][k] = *(const PG8_LAS bf16x8*)(lds + PG8_SA(b, h) + aoff + m * 2048 + k * 1024); } while (0)
; #define PG8_LDB(dst, b, h) do { _Pragma("unroll") for (int n = 0; n < 2; ++n) _Pragma("unroll") for (int k = 0; k < 2; ++k) dst[n][k] = *(const PG8_LAS bf16x8*)(lds + PG8_SB(b, h) + boff + n * 2048 + k * 1024); } while (0)
; #define PG8_MMA(ai, bj, At, Bt) do { __builtin_amdgcn_s_setprio(1); _Pragma("unroll") for (int m = 0; m < 4; ++m) _Pragma("unroll") for (int n = 0; n < 2; ++n) _Pragma("unroll") for (int k = 0; k < 2; ++k) \
;         acc[ai][bj][m][n] = __builtin_amdgcn_mfma_f32_16x16x32_bf16(Bt[n][k], At[m][k], acc[ai][bj][m][n], 0, 0, 0); __builtin_amdgcn_s_setprio(0); } while (0)
; #define PG8_WAIT_V(n) asm volatile("s_waitcnt vmcnt(" #n ")" ::: "memory")
; #define PG8_WAIT_L(n) asm volatile("s_waitcnt lgkmcnt(" #n ")" ::: "memory")
; #define PG8_BAR __builtin_amdgcn_s_barrier()
; #define PG8_SCHED __builtin_amdgcn_sched_barrier(0)
; template <class Epi, class Sched, bool ALIGN_EPI = false, bool SP2 = false>
; __device__ __forceinline__ void gemm_phase(PG8_LAS unsigned char* lds, const Gemm g, const Sched& S, const Epi& E) {
;     ...
;             PG8_LDB(B0, 1, 0); PG8_LDB(B1, 1, 1); PG8_SCHED; PG8_LDA(At, 1, 0); PG8_STAGE(PG8_SA(0, 1), a2 + hstep, voffA);
;             PG8_WAIT_V(8); PG8_WAIT_L(0); PG8_BAR; PG8_MMA(0, 0, At, B0); PG8_MMA(0, 1, At, B1); PG8_BAR; PG8_SCHED;
;             PG8_LDA(At, 1, 1); PG8_STAGE(PG8_SB(1, 0), b3, voffB); PG8_STAGE(PG8_SB(1, 1), b3 + hstep, voffB); PG8_STAGE(PG8_SA(1, 0), a3, voffA);
;             PG8_WAIT_V(8); PG8_WAIT_L(0); PG8_BAR; PG8_MMA(1, 0, At, B0); PG8_MMA(1, 1, At, B1); PG8_BAR; PG8_SCHED;
	s_add_i32 s56, 0, 0x18000
	v_add_u32_e32 v167, s56, v156
	s_add_i32 s57, 0, 0x1c000
	ds_read_b128 v[144:147], v167
	ds_read_b128 v[168:171], v167 offset:1024
	ds_read_b128 v[172:175], v167 offset:2048
	ds_read_b128 v[176:179], v167 offset:3072
	v_add_u32_e32 v167, s57, v156
	ds_read_b128 v[180:183], v167
	ds_read_b128 v[184:187], v167 offset:1024
	ds_read_b128 v[188:191], v167 offset:2048
	ds_read_b128 v[196:199], v167 offset:3072
	s_add_u32 s6, s78, 0xb0000
	s_addc_u32 s7, s79, 0
	s_mov_b32 m0, s76
	ds_read_b128 v[200:203], v163 offset:32768
	ds_read_b128 v[204:207], v163 offset:33792
	ds_read_b128 v[208:211], v163 offset:34816
	ds_read_b128 v[212:215], v163 offset:35840
	ds_read_b128 v[216:219], v163 offset:36864
	ds_read_b128 v[220:223], v163 offset:37888
	ds_read_b128 v[224:227], v163 offset:38912
	global_load_lds_dwordx4 v128, s[6:7]
	s_mov_b32 m0, s77
	ds_read_b128 v[228:231], v163 offset:39936
	global_load_lds_dwordx4 v132, s[6:7]
	s_waitcnt vmcnt(8)
	s_waitcnt lgkmcnt(0)
	s_barrier
	s_waitcnt lgkmcnt(0)
	v_mfma_f32_16x16x32_bf16 v[124:127], v[144:147], v[200:203], v[124:127]
	v_mfma_f32_16x16x32_bf16 v[120:123], v[172:175], v[200:203], v[120:123]
	v_mfma_f32_16x16x32_bf16 v[108:111], v[144:147], v[208:211], v[108:111]
	v_mfma_f32_16x16x32_bf16 v[104:107], v[172:175], v[208:211], v[104:107]
	v_mfma_f32_16x16x32_bf16 v[92:95], v[144:147], v[216:219], v[92:95]
	v_mfma_f32_16x16x32_bf16 v[88:91], v[172:175], v[216:219], v[88:91]
	v_mfma_f32_16x16x32_bf16 v[76:79], v[144:147], v[224:227], v[76:79]
	v_mfma_f32_16x16x32_bf16 v[72:75], v[172:175], v[224:227], v[72:75]
	v_mfma_f32_16x16x32_bf16 v[124:127], v[168:171], v[204:207], v[124:127]
	v_mfma_f32_16x16x32_bf16 v[120:123], v[176:179], v[204:207], v[120:123]
	v_mfma_f32_16x16x32_bf16 v[108:111], v[168:171], v[212:215], v[108:111]
	v_mfma_f32_16x16x32_bf16 v[104:107], v[176:179], v[212:215], v[104:107]
	v_mfma_f32_16x16x32_bf16 v[92:95], v[168:171], v[220:223], v[92:95]
	v_mfma_f32_16x16x32_bf16 v[88:91], v[176:179], v[220:223], v[88:91]
	v_mfma_f32_16x16x32_bf16 v[76:79], v[168:171], v[228:231], v[76:79]
	v_mfma_f32_16x16x32_bf16 v[72:75], v[176:179], v[228:231], v[72:75]
	v_mfma_f32_16x16x32_bf16 v[116:119], v[180:183], v[200:203], v[116:119]
	v_mfma_f32_16x16x32_bf16 v[112:115], v[188:191], v[200:203], v[112:115]
	v_mfma_f32_16x16x32_bf16 v[100:103], v[180:183], v[208:211], v[100:103]
	v_mfma_f32_16x16x32_bf16 v[96:99], v[188:191], v[208:211], v[96:99]
	v_mfma_f32_16x16x32_bf16 v[84:87], v[180:183], v[216:219], v[84:87]
	v_mfma_f32_16x16x32_bf16 v[80:83], v[188:191], v[216:219], v[80:83]
	v_mfma_f32_16x16x32_bf16 v[68:71], v[180:183], v[224:227], v[68:71]
	v_mfma_f32_16x16x32_bf16 v[64:67], v[188:191], v[224:227], v[64:67]
	v_mfma_f32_16x16x32_bf16 v[116:119], v[184:187], v[204:207], v[116:119]
	v_mfma_f32_16x16x32_bf16 v[112:115], v[196:199], v[204:207], v[112:115]
	v_mfma_f32_16x16x32_bf16 v[100:103], v[184:187], v[212:215], v[100:103]
	v_mfma_f32_16x16x32_bf16 v[96:99], v[196:199], v[212:215], v[96:99]
	v_mfma_f32_16x16x32_bf16 v[84:87], v[184:187], v[220:223], v[84:87]
	v_mfma_f32_16x16x32_bf16 v[80:83], v[196:199], v[220:223], v[80:83]
	v_mfma_f32_16x16x32_bf16 v[68:71], v[184:187], v[228:231], v[68:71]
	v_mfma_f32_16x16x32_bf16 v[64:67], v[196:199], v[228:231], v[64:67]
	s_barrier
	s_add_i32 s6, s56, s44
	s_add_u32 s98, s60, 0x80
	s_addc_u32 s99, s61, 0
	s_add_u32 s100, s78, 0x80
	s_addc_u32 s101, s79, 0
	s_mov_b32 m0, s6
	ds_read_b128 v[200:203], v163 offset:49152
	ds_read_b128 v[204:207], v163 offset:50176
	ds_read_b128 v[208:211], v163 offset:51200
	ds_read_b128 v[212:215], v163 offset:52224
	global_load_lds_dwordx4 v130, s[98:99]
	s_add_i32 m0, s6, 0x2000
	s_add_u32 s6, s60, 0xb0080
	s_addc_u32 s7, s61, 0
	s_add_i32 s56, s57, s44
	global_load_lds_dwordx4 v134, s[98:99]
	s_mov_b32 m0, s56
	ds_read_b128 v[228:231], v163 offset:56320
	global_load_lds_dwordx4 v130, s[6:7]
	s_add_i32 m0, s56, 0x2000
	ds_read_b128 v[224:227], v163 offset:55296
	global_load_lds_dwordx4 v134, s[6:7]
	s_mov_b32 m0, s31
	ds_read_b128 v[220:223], v163 offset:54272
	global_load_lds_dwordx4 v128, s[100:101]
	s_mov_b32 m0, s4
	ds_read_b128 v[216:219], v163 offset:53248
	global_load_lds_dwordx4 v132, s[100:101]
	s_waitcnt vmcnt(8)
	s_waitcnt lgkmcnt(0)
	s_barrier
	s_waitcnt lgkmcnt(0)
	v_mfma_f32_16x16x32_bf16 v[60:63], v[144:147], v[200:203], v[60:63]
	v_mfma_f32_16x16x32_bf16 v[56:59], v[172:175], v[200:203], v[56:59]
	v_mfma_f32_16x16x32_bf16 v[44:47], v[144:147], v[208:211], v[44:47]
	v_mfma_f32_16x16x32_bf16 v[40:43], v[172:175], v[208:211], v[40:43]
	v_mfma_f32_16x16x32_bf16 v[28:31], v[144:147], v[216:219], v[28:31]
	v_mfma_f32_16x16x32_bf16 v[24:27], v[172:175], v[216:219], v[24:27]
	v_mfma_f32_16x16x32_bf16 v[12:15], v[144:147], v[224:227], v[12:15]
	v_mfma_f32_16x16x32_bf16 v[8:11], v[172:175], v[224:227], v[8:11]
	v_mfma_f32_16x16x32_bf16 v[60:63], v[168:171], v[204:207], v[60:63]
	v_mfma_f32_16x16x32_bf16 v[56:59], v[176:179], v[204:207], v[56:59]
	v_mfma_f32_16x16x32_bf16 v[44:47], v[168:171], v[212:215], v[44:47]
	v_mfma_f32_16x16x32_bf16 v[40:43], v[176:179], v[212:215], v[40:43]
	v_mfma_f32_16x16x32_bf16 v[28:31], v[168:171], v[220:223], v[28:31]
	v_mfma_f32_16x16x32_bf16 v[24:27], v[176:179], v[220:223], v[24:27]
	v_mfma_f32_16x16x32_bf16 v[12:15], v[168:171], v[228:231], v[12:15]
	v_mfma_f32_16x16x32_bf16 v[8:11], v[176:179], v[228:231], v[8:11]
	v_mfma_f32_16x16x32_bf16 v[52:55], v[180:183], v[200:203], v[52:55]
	v_mfma_f32_16x16x32_bf16 v[48:51], v[188:191], v[200:203], v[48:51]
	v_mfma_f32_16x16x32_bf16 v[36:39], v[180:183], v[208:211], v[36:39]
	v_mfma_f32_16x16x32_bf16 v[32:35], v[188:191], v[208:211], v[32:35]
	v_mfma_f32_16x16x32_bf16 v[20:23], v[180:183], v[216:219], v[20:23]
	v_mfma_f32_16x16x32_bf16 v[16:19], v[188:191], v[216:219], v[16:19]
	v_mfma_f32_16x16x32_bf16 v[4:7], v[180:183], v[224:227], v[4:7]
	v_mfma_f32_16x16x32_bf16 v[0:3], v[188:191], v[224:227], v[0:3]
	v_mfma_f32_16x16x32_bf16 v[52:55], v[184:187], v[204:207], v[52:55]
	v_mfma_f32_16x16x32_bf16 v[48:51], v[196:199], v[204:207], v[48:51]
	v_mfma_f32_16x16x32_bf16 v[36:39], v[184:187], v[212:215], v[36:39]
	v_mfma_f32_16x16x32_bf16 v[32:35], v[196:199], v[212:215], v[32:35]
	v_mfma_f32_16x16x32_bf16 v[20:23], v[184:187], v[220:223], v[20:23]
	v_mfma_f32_16x16x32_bf16 v[16:19], v[196:199], v[220:223], v[16:19]
	v_mfma_f32_16x16x32_bf16 v[4:7], v[184:187], v[228:231], v[4:7]
	v_mfma_f32_16x16x32_bf16 v[0:3], v[196:199], v[228:231], v[0:3]
	s_barrier
	s_add_i32 s72, s72, 2
	s_add_u32 s33, s33, 0x100
	s_addc_u32 s80, s80, 0
	s_cmp_gt_u32 s72, 41
	s_mov_b64 s[56:57], s[58:59]
	s_cbranch_scc0 .LBB0_1014
	s_and_b64 vcc, exec, s[52:53]
	s_cbranch_vccz .LBB0_1017
	s_barrier

; #define PG8_STAGE(bufoff, gbase, voff) do { _Pragma("unroll") for (int _i = 0; _i < 2; ++_i) \
;         __builtin_amdgcn_global_load_lds((const unsigned*)((const char*)(gbase) + (voff)[_i]), (PG8_LAS unsigned*)(lds + (bufoff) + ldsw + _i * 8192), 16, 0, 0); } while (0)
; #define PG8_LDA(dst, b, h) do { _Pragma("unroll") for (int m = 0; m < 4; ++m) _Pragma("unroll") for (int k = 0; k < 2; ++k) dst[m][k] = *(const PG8_LAS bf16x8*)(lds + PG8_SA(b, h) + aoff + m * 2048 + k * 1024); } while (0)
; #define PG8_LDB(dst, b, h) do { _Pragma("unroll") for (int n = 0; n < 2; ++n) _Pragma("unroll") for (int k = 0; k < 2; ++k) dst[n][k] = *(const PG8_LAS bf16x8*)(lds + PG8_SB(b, h) + boff + n * 2048 + k * 1024); } while (0)
; #define PG8_MMA(ai, bj, At, Bt) do { __builtin_amdgcn_s_setprio(1); _Pragma("unroll") for (int m = 0; m < 4; ++m) _Pragma("unroll") for (int n = 0; n < 2; ++n) _Pragma("unroll") for (int k = 0; k < 2; ++k) \
;         acc[ai][bj][m][n] = __builtin_amdgcn_mfma_f32_16x16x32_bf16(Bt[n][k], At[m][k], acc[ai][bj][m][n], 0, 0, 0); __builtin_amdgcn_s_setprio(0); } while (0)
; #define PG8_WAIT_V(n) asm volatile("s_waitcnt vmcnt(" #n ")" ::: "memory")
; #define PG8_WAIT_L(n) asm volatile("s_waitcnt lgkmcnt(" #n ")" ::: "memory")
; #define PG8_BAR __builtin_amdgcn_s_barrier()
; #define PG8_SCHED __builtin_amdgcn_sched_barrier(0)
; template <class Epi, class Sched, bool ALIGN_EPI = false, bool SP2 = false>
; __device__ __forceinline__ void gemm_phase(PG8_LAS unsigned char* lds, const Gemm g, const Sched& S, const Epi& E) {
;     ...
;             const char* a1 = cA + (size_t)(t + 1) * kstep;
;             const char* a2 = last ? nA : cA + (size_t)(t + 2) * kstep; const char* b2 = last ? nB : cB + (size_t)(t + 2) * kstep;
;             const char* a3 = a2 + kstep; const char* b3 = b2 + kstep;
;     ...
;             PG8_LDB(B0, 0, 0); PG8_LDB(B1, 0, 1); PG8_SCHED; PG8_LDA(At, 0, 0); PG8_STAGE(PG8_SA(1, 1), a1 + hstep, voffA);
;             PG8_WAIT_V(8); PG8_WAIT_L(0); PG8_BAR; PG8_MMA(0, 0, At, B0); PG8_MMA(0, 1, At, B1); PG8_BAR; PG8_SCHED;
;             PG8_LDA(At, 0, 1); PG8_STAGE(PG8_SB(0, 0), b2, voffB); PG8_STAGE(PG8_SB(0, 1), b2 + hstep, voffB); PG8_STAGE(PG8_SA(0, 0), a2, voffA);
;             PG8_WAIT_V(8); PG8_WAIT_L(0); PG8_BAR; PG8_MMA(1, 0, At, B0); PG8_MMA(1, 1, At, B1); PG8_BAR; PG8_SCHED;
.LBB0_1392:
	ds_read_b128 v[144:147], v157
	ds_read_b128 v[166:169], v157 offset:1024
	ds_read_b128 v[170:173], v157 offset:2048
	ds_read_b128 v[174:177], v157 offset:3072
	ds_read_b128 v[178:181], v158
	ds_read_b128 v[182:185], v158 offset:1024
	ds_read_b128 v[186:189], v158 offset:2048
	ds_read_b128 v[196:199], v158 offset:3072
	s_add_u32 s6, s58, 0xfffc0080
	s_addc_u32 s7, s59, -1
	s_cmp_eq_u32 s72, 12
	s_cselect_b32 s79, s51, s7
	s_cselect_b32 s78, s75, s6
	s_cselect_b32 s61, s49, s33
	s_cselect_b32 s60, s76, s77
	v_lshl_add_u64 v[190:191], s[58:59], 0, v[136:137]
	s_add_i32 m0, s30, 0xc000
	ds_read_b128 v[200:203], v159
	ds_read_b128 v[204:207], v159 offset:1024
	ds_read_b128 v[208:211], v159 offset:2048
	ds_read_b128 v[212:215], v159 offset:3072
	ds_read_b128 v[216:219], v159 offset:4096
	ds_read_b128 v[220:223], v159 offset:5120
	ds_read_b128 v[224:227], v159 offset:6144
	global_load_lds_dwordx4 v[190:191], off
	v_lshl_add_u64 v[190:191], s[58:59], 0, v[138:139]
	s_add_i32 m0, s30, 0xe000
	ds_read_b128 v[228:231], v159 offset:7168
	global_load_lds_dwordx4 v[190:191], off
	s_waitcnt vmcnt(8)
	s_waitcnt lgkmcnt(0)
	s_barrier
	s_waitcnt lgkmcnt(0)
	v_mfma_f32_16x16x32_bf16 v[124:127], v[144:147], v[200:203], v[124:127]
	v_mfma_f32_16x16x32_bf16 v[120:123], v[170:173], v[200:203], v[120:123]
	v_mfma_f32_16x16x32_bf16 v[112:115], v[144:147], v[208:211], v[112:115]
	v_mfma_f32_16x16x32_bf16 v[104:107], v[170:173], v[208:211], v[104:107]
	v_mfma_f32_16x16x32_bf16 v[96:99], v[144:147], v[216:219], v[96:99]
	v_mfma_f32_16x16x32_bf16 v[88:91], v[170:173], v[216:219], v[88:91]
	v_mfma_f32_16x16x32_bf16 v[80:83], v[144:147], v[224:227], v[80:83]
	v_mfma_f32_16x16x32_bf16 v[72:75], v[170:173], v[224:227], v[72:75]
	v_mfma_f32_16x16x32_bf16 v[124:127], v[166:169], v[204:207], v[124:127]
	v_mfma_f32_16x16x32_bf16 v[120:123], v[174:177], v[204:207], v[120:123]
	v_mfma_f32_16x16x32_bf16 v[112:115], v[166:169], v[212:215], v[112:115]
	v_mfma_f32_16x16x32_bf16 v[104:107], v[174:177], v[212:215], v[104:107]
	v_mfma_f32_16x16x32_bf16 v[96:99], v[166:169], v[220:223], v[96:99]
	v_mfma_f32_16x16x32_bf16 v[88:91], v[174:177], v[220:223], v[88:91]
	v_mfma_f32_16x16x32_bf16 v[80:83], v[166:169], v[228:231], v[80:83]
	v_mfma_f32_16x16x32_bf16 v[72:75], v[174:177], v[228:231], v[72:75]
	v_mfma_f32_16x16x32_bf16 v[116:119], v[178:181], v[200:203], v[116:119]
	v_mfma_f32_16x16x32_bf16 v[108:111], v[186:189], v[200:203], v[108:111]
	v_mfma_f32_16x16x32_bf16 v[100:103], v[178:181], v[208:211], v[100:103]
	v_mfma_f32_16x16x32_bf16 v[92:95], v[186:189], v[208:211], v[92:95]
	v_mfma_f32_16x16x32_bf16 v[84:87], v[178:181], v[216:219], v[84:87]
	v_mfma_f32_16x16x32_bf16 v[76:79], v[186:189], v[216:219], v[76:79]
	v_mfma_f32_16x16x32_bf16 v[68:71], v[178:181], v[224:227], v[68:71]
	v_mfma_f32_16x16x32_bf16 v[64:67], v[186:189], v[224:227], v[64:67]
	v_mfma_f32_16x16x32_bf16 v[116:119], v[182:185], v[204:207], v[116:119]
	v_mfma_f32_16x16x32_bf16 v[108:111], v[196:199], v[204:207], v[108:111]
	v_mfma_f32_16x16x32_bf16 v[100:103], v[182:185], v[212:215], v[100:103]
	v_mfma_f32_16x16x32_bf16 v[92:95], v[196:199], v[212:215], v[92:95]
	v_mfma_f32_16x16x32_bf16 v[84:87], v[182:185], v[220:223], v[84:87]
	v_mfma_f32_16x16x32_bf16 v[76:79], v[196:199], v[220:223], v[76:79]
	v_mfma_f32_16x16x32_bf16 v[68:71], v[182:185], v[228:231], v[68:71]
	v_mfma_f32_16x16x32_bf16 v[64:67], v[196:199], v[228:231], v[64:67]
	s_barrier
	s_add_i32 s6, s57, s27
	v_lshl_add_u64 v[190:191], s[60:61], 0, v[130:131]
	s_mov_b32 m0, s6
	ds_read_b128 v[200:203], v159 offset:16384
	ds_read_b128 v[204:207], v159 offset:17408
	ds_read_b128 v[208:211], v159 offset:18432
	ds_read_b128 v[212:215], v159 offset:19456
	ds_read_b128 v[216:219], v159 offset:20480
	global_load_lds_dwordx4 v[190:191], off
	s_add_i32 m0, s6, 0x2000
	s_add_u32 s6, s60, 0x40000
	v_lshl_add_u64 v[232:233], s[60:61], 0, v[134:135]
	s_addc_u32 s7, s61, 0
	s_add_i32 s73, s67, s27
	global_load_lds_dwordx4 v[232:233], off
	s_mov_b32 m0, s73
	v_lshl_add_u64 v[236:237], s[78:79], 0, v[132:133]
	global_load_lds_dwordx4 v130, s[6:7]
	s_add_i32 m0, s73, 0x2000
	ds_read_b128 v[228:231], v159 offset:23552
	global_load_lds_dwordx4 v134, s[6:7]
	v_lshl_add_u64 v[234:235], s[78:79], 0, v[128:129]
	s_mov_b32 m0, s30
	ds_read_b128 v[224:227], v159 offset:22528
	global_load_lds_dwordx4 v[234:235], off
	s_mov_b32 m0, s31
	ds_read_b128 v[220:223], v159 offset:21504
	global_load_lds_dwordx4 v[236:237], off
	s_waitcnt vmcnt(8)
	s_waitcnt lgkmcnt(0)
	s_barrier
	s_waitcnt lgkmcnt(0)
	v_mfma_f32_16x16x32_bf16 v[60:63], v[144:147], v[200:203], v[60:63]
	v_mfma_f32_16x16x32_bf16 v[56:59], v[170:173], v[200:203], v[56:59]
	v_mfma_f32_16x16x32_bf16 v[52:55], v[144:147], v[208:211], v[52:55]
	v_mfma_f32_16x16x32_bf16 v[40:43], v[170:173], v[208:211], v[40:43]
	v_mfma_f32_16x16x32_bf16 v[36:39], v[144:147], v[216:219], v[36:39]
	v_mfma_f32_16x16x32_bf16 v[24:27], v[170:173], v[216:219], v[24:27]
	v_mfma_f32_16x16x32_bf16 v[20:23], v[144:147], v[224:227], v[20:23]
	v_mfma_f32_16x16x32_bf16 v[8:11], v[170:173], v[224:227], v[8:11]
	v_mfma_f32_16x16x32_bf16 v[60:63], v[166:169], v[204:207], v[60:63]
	v_mfma_f32_16x16x32_bf16 v[56:59], v[174:177], v[204:207], v[56:59]
	v_mfma_f32_16x16x32_bf16 v[52:55], v[166:169], v[212:215], v[52:55]
	v_mfma_f32_16x16x32_bf16 v[40:43], v[174:177], v[212:215], v[40:43]
	v_mfma_f32_16x16x32_bf16 v[36:39], v[166:169], v[220:223], v[36:39]
	v_mfma_f32_16x16x32_bf16 v[24:27], v[174:177], v[220:223], v[24:27]
	v_mfma_f32_16x16x32_bf16 v[20:23], v[166:169], v[228:231], v[20:23]
	v_mfma_f32_16x16x32_bf16 v[8:11], v[174:177], v[228:231], v[8:11]
	v_mfma_f32_16x16x32_bf16 v[48:51], v[178:181], v[200:203], v[48:51]
	v_mfma_f32_16x16x32_bf16 v[44:47], v[186:189], v[200:203], v[44:47]
	v_mfma_f32_16x16x32_bf16 v[32:35], v[178:181], v[208:211], v[32:35]
	v_mfma_f32_16x16x32_bf16 v[28:31], v[186:189], v[208:211], v[28:31]
	v_mfma_f32_16x16x32_bf16 v[16:19], v[178:181], v[216:219], v[16:19]
	v_mfma_f32_16x16x32_bf16 v[12:15], v[186:189], v[216:219], v[12:15]
	v_mfma_f32_16x16x32_bf16 v[4:7], v[178:181], v[224:227], v[4:7]
	v_mfma_f32_16x16x32_bf16 v[0:3], v[186:189], v[224:227], v[0:3]
	v_mfma_f32_16x16x32_bf16 v[48:51], v[182:185], v[204:207], v[48:51]
	v_mfma_f32_16x16x32_bf16 v[44:47], v[196:199], v[204:207], v[44:47]
	v_mfma_f32_16x16x32_bf16 v[32:35], v[182:185], v[212:215], v[32:35]
	v_mfma_f32_16x16x32_bf16 v[28:31], v[196:199], v[212:215], v[28:31]
	v_mfma_f32_16x16x32_bf16 v[16:19], v[182:185], v[220:223], v[16:19]
	v_mfma_f32_16x16x32_bf16 v[12:15], v[196:199], v[220:223], v[12:15]
	v_mfma_f32_16x16x32_bf16 v[4:7], v[182:185], v[228:231], v[4:7]
	v_mfma_f32_16x16x32_bf16 v[0:3], v[196:199], v[228:231], v[0:3]
	s_barrier
; #define PG8_STAGE(bufoff, gbase, voff) do { _Pragma("unroll") for (int _i = 0; _i < 2; ++_i) \
;         __builtin_amdgcn_global_load_lds((const unsigned*)((const char*)(gbase) + (voff)[_i]), (PG8_LAS unsigned*)(lds + (bufoff) + ldsw + _i * 8192), 16, 0, 0); } while (0)
; #define PG8_LDA(dst, b, h) do { _Pragma("unroll") for (int m = 0; m < 4; ++m) _Pragma("unroll") for (int k = 0; k < 2; ++k) dst[m][k] = *(const PG8_LAS bf16x8*)(lds + PG8_SA(b, h) + aoff + m * 2048 + k * 1024); } while (0)
; #define PG8_LDB(dst, b, h) do { _Pragma("unroll") for (int n = 0; n < 2; ++n) _Pragma("unroll") for (int k = 0; k < 2; ++k) dst[n][k] = *(const PG8_LAS bf16x8*)(lds + PG8_SB(b, h) + boff + n * 2048 + k * 1024); } while (0)
; #define PG8_MMA(ai, bj, At, Bt) do { __builtin_amdgcn_s_setprio(1); _Pragma("unroll") for (int m = 0; m < 4; ++m) _Pragma("unroll") for (int n = 0; n < 2; ++n) _Pragma("unroll") for (int k = 0; k < 2; ++k) \
;         acc[ai][bj][m][n] = __builtin_amdgcn_mfma_f32_16x16x32_bf16(Bt[n][k], At[m][k], acc[ai][bj][m][n], 0, 0, 0); __builtin_amdgcn_s_setprio(0); } while (0)
; #define PG8_WAIT_V(n) asm volatile("s_waitcnt vmcnt(" #n ")" ::: "memory")
; #define PG8_WAIT_L(n) asm volatile("s_waitcnt lgkmcnt(" #n ")" ::: "memory")
; #define PG8_BAR __builtin_amdgcn_s_barrier()
; #define PG8_SCHED __builtin_amdgcn_sched_barrier(0)
; template <class Epi, class Sched, bool ALIGN_EPI = false, bool SP2 = false>
; __device__ __forceinline__ void gemm_phase(PG8_LAS unsigned char* lds, const Gemm g, const Sched& S, const Epi& E) {
;     ...
;             PG8_LDB(B0, 1, 0); PG8_LDB(B1, 1, 1); PG8_SCHED; PG8_LDA(At, 1, 0); PG8_STAGE(PG8_SA(0, 1), a2 + hstep, voffA);
;             PG8_WAIT_V(8); PG8_WAIT_L(0); PG8_BAR; PG8_MMA(0, 0, At, B0); PG8_MMA(0, 1, At, B1); PG8_BAR; PG8_SCHED;
;             PG8_LDA(At, 1, 1); PG8_STAGE(PG8_SB(1, 0), b3, voffB); PG8_STAGE(PG8_SB(1, 1), b3 + hstep, voffB); PG8_STAGE(PG8_SA(1, 0), a3, voffA);
;             PG8_WAIT_V(8); PG8_WAIT_L(0); PG8_BAR; PG8_MMA(1, 0, At, B0); PG8_MMA(1, 1, At, B1); PG8_BAR; PG8_SCHED;
	s_add_i32 s73, 0, 0x18000
	v_add_u32_e32 v163, s73, v149
	s_add_i32 s80, 0, 0x1c000
	ds_read_b128 v[144:147], v163
	ds_read_b128 v[166:169], v163 offset:1024
	ds_read_b128 v[170:173], v163 offset:2048
	ds_read_b128 v[174:177], v163 offset:3072
	v_add_u32_e32 v163, s80, v149
	ds_read_b128 v[178:181], v163
	ds_read_b128 v[182:185], v163 offset:1024
	ds_read_b128 v[186:189], v163 offset:2048
	ds_read_b128 v[196:199], v163 offset:3072
	s_add_u32 s6, s78, 0x40000
	s_addc_u32 s7, s79, 0
	s_mov_b32 m0, s42
	ds_read_b128 v[200:203], v159 offset:32768
	ds_read_b128 v[204:207], v159 offset:33792
	ds_read_b128 v[208:211], v159 offset:34816
	ds_read_b128 v[212:215], v159 offset:35840
	ds_read_b128 v[216:219], v159 offset:36864
	ds_read_b128 v[220:223], v159 offset:37888
	ds_read_b128 v[224:227], v159 offset:38912
	global_load_lds_dwordx4 v128, s[6:7]
	s_mov_b32 m0, s43
	ds_read_b128 v[228:231], v159 offset:39936
	global_load_lds_dwordx4 v132, s[6:7]
	s_waitcnt vmcnt(8)
	s_waitcnt lgkmcnt(0)
	s_barrier
	s_waitcnt lgkmcnt(0)
	v_mfma_f32_16x16x32_bf16 v[124:127], v[144:147], v[200:203], v[124:127]
	v_mfma_f32_16x16x32_bf16 v[120:123], v[170:173], v[200:203], v[120:123]
	v_mfma_f32_16x16x32_bf16 v[112:115], v[144:147], v[208:211], v[112:115]
	v_mfma_f32_16x16x32_bf16 v[104:107], v[170:173], v[208:211], v[104:107]
	v_mfma_f32_16x16x32_bf16 v[96:99], v[144:147], v[216:219], v[96:99]
	v_mfma_f32_16x16x32_bf16 v[88:91], v[170:173], v[216:219], v[88:91]
	v_mfma_f32_16x16x32_bf16 v[80:83], v[144:147], v[224:227], v[80:83]
	v_mfma_f32_16x16x32_bf16 v[72:75], v[170:173], v[224:227], v[72:75]
	v_mfma_f32_16x16x32_bf16 v[124:127], v[166:169], v[204:207], v[124:127]
	v_mfma_f32_16x16x32_bf16 v[120:123], v[174:177], v[204:207], v[120:123]
	v_mfma_f32_16x16x32_bf16 v[112:115], v[166:169], v[212:215], v[112:115]
	v_mfma_f32_16x16x32_bf16 v[104:107], v[174:177], v[212:215], v[104:107]
	v_mfma_f32_16x16x32_bf16 v[96:99], v[166:169], v[220:223], v[96:99]
	v_mfma_f32_16x16x32_bf16 v[88:91], v[174:177], v[220:223], v[88:91]
	v_mfma_f32_16x16x32_bf16 v[80:83], v[166:169], v[228:231], v[80:83]
	v_mfma_f32_16x16x32_bf16 v[72:75], v[174:177], v[228:231], v[72:75]
	v_mfma_f32_16x16x32_bf16 v[116:119], v[178:181], v[200:203], v[116:119]
	v_mfma_f32_16x16x32_bf16 v[108:111], v[186:189], v[200:203], v[108:111]
	v_mfma_f32_16x16x32_bf16 v[100:103], v[178:181], v[208:211], v[100:103]
	v_mfma_f32_16x16x32_bf16 v[92:95], v[186:189], v[208:211], v[92:95]
	v_mfma_f32_16x16x32_bf16 v[84:87], v[178:181], v[216:219], v[84:87]
	v_mfma_f32_16x16x32_bf16 v[76:79], v[186:189], v[216:219], v[76:79]
	v_mfma_f32_16x16x32_bf16 v[68:71], v[178:181], v[224:227], v[68:71]
	v_mfma_f32_16x16x32_bf16 v[64:67], v[186:189], v[224:227], v[64:67]
	v_mfma_f32_16x16x32_bf16 v[116:119], v[182:185], v[204:207], v[116:119]
	v_mfma_f32_16x16x32_bf16 v[108:111], v[196:199], v[204:207], v[108:111]
	v_mfma_f32_16x16x32_bf16 v[100:103], v[182:185], v[212:215], v[100:103]
	v_mfma_f32_16x16x32_bf16 v[92:95], v[196:199], v[212:215], v[92:95]
	v_mfma_f32_16x16x32_bf16 v[84:87], v[182:185], v[220:223], v[84:87]
	v_mfma_f32_16x16x32_bf16 v[76:79], v[196:199], v[220:223], v[76:79]
	v_mfma_f32_16x16x32_bf16 v[68:71], v[182:185], v[228:231], v[68:71]
	v_mfma_f32_16x16x32_bf16 v[64:67], v[196:199], v[228:231], v[64:67]
	s_barrier
	s_add_i32 s6, s73, s27
	v_lshl_add_u64 v[190:191], v[190:191], 0, s[38:39]
	s_mov_b32 m0, s6
	ds_read_b128 v[200:203], v159 offset:49152
	ds_read_b128 v[204:207], v159 offset:50176
	ds_read_b128 v[208:211], v159 offset:51200
	ds_read_b128 v[212:215], v159 offset:52224
	global_load_lds_dwordx4 v[190:191], off
	s_add_i32 m0, s6, 0x2000
	s_add_u32 s6, s60, 0x40080
	v_lshl_add_u64 v[190:191], v[232:233], 0, s[38:39]
	s_addc_u32 s7, s61, 0
	s_add_i32 s60, s80, s27
	global_load_lds_dwordx4 v[190:191], off
	v_lshl_add_u64 v[190:191], s[6:7], 0, v[130:131]
	s_mov_b32 m0, s60
	ds_read_b128 v[228:231], v159 offset:56320
	global_load_lds_dwordx4 v[190:191], off
	v_lshl_add_u64 v[190:191], s[6:7], 0, v[134:135]
	s_add_i32 m0, s60, 0x2000
	ds_read_b128 v[224:227], v159 offset:55296
	global_load_lds_dwordx4 v[190:191], off
	v_lshl_add_u64 v[190:191], v[234:235], 0, s[38:39]
	s_mov_b32 m0, s44
	ds_read_b128 v[220:223], v159 offset:54272
	global_load_lds_dwordx4 v[190:191], off
	v_lshl_add_u64 v[190:191], v[236:237], 0, s[38:39]
	s_mov_b32 m0, s45
	ds_read_b128 v[216:219], v159 offset:53248
	global_load_lds_dwordx4 v[190:191], off
	s_waitcnt vmcnt(8)
	s_waitcnt lgkmcnt(0)
	s_barrier
	s_waitcnt lgkmcnt(0)
	v_mfma_f32_16x16x32_bf16 v[60:63], v[144:147], v[200:203], v[60:63]
	v_mfma_f32_16x16x32_bf16 v[56:59], v[170:173], v[200:203], v[56:59]
	v_mfma_f32_16x16x32_bf16 v[52:55], v[144:147], v[208:211], v[52:55]
	v_mfma_f32_16x16x32_bf16 v[40:43], v[170:173], v[208:211], v[40:43]
	v_mfma_f32_16x16x32_bf16 v[36:39], v[144:147], v[216:219], v[36:39]
	v_mfma_f32_16x16x32_bf16 v[24:27], v[170:173], v[216:219], v[24:27]
	v_mfma_f32_16x16x32_bf16 v[20:23], v[144:147], v[224:227], v[20:23]
	v_mfma_f32_16x16x32_bf16 v[8:11], v[170:173], v[224:227], v[8:11]
	v_mfma_f32_16x16x32_bf16 v[60:63], v[166:169], v[204:207], v[60:63]
	v_mfma_f32_16x16x32_bf16 v[56:59], v[174:177], v[204:207], v[56:59]
	v_mfma_f32_16x16x32_bf16 v[52:55], v[166:169], v[212:215], v[52:55]
	v_mfma_f32_16x16x32_bf16 v[40:43], v[174:177], v[212:215], v[40:43]
	v_mfma_f32_16x16x32_bf16 v[36:39], v[166:169], v[220:223], v[36:39]
	v_mfma_f32_16x16x32_bf16 v[24:27], v[174:177], v[220:223], v[24:27]
	v_mfma_f32_16x16x32_bf16 v[20:23], v[166:169], v[228:231], v[20:23]
	v_mfma_f32_16x16x32_bf16 v[8:11], v[174:177], v[228:231], v[8:11]
	v_mfma_f32_16x16x32_bf16 v[48:51], v[178:181], v[200:203], v[48:51]
	v_mfma_f32_16x16x32_bf16 v[44:47], v[186:189], v[200:203], v[44:47]
	v_mfma_f32_16x16x32_bf16 v[32:35], v[178:181], v[208:211], v[32:35]
	v_mfma_f32_16x16x32_bf16 v[28:31], v[186:189], v[208:211], v[28:31]
	v_mfma_f32_16x16x32_bf16 v[16:19], v[178:181], v[216:219], v[16:19]
	v_mfma_f32_16x16x32_bf16 v[12:15], v[186:189], v[216:219], v[12:15]
	v_mfma_f32_16x16x32_bf16 v[4:7], v[178:181], v[224:227], v[4:7]
	v_mfma_f32_16x16x32_bf16 v[0:3], v[186:189], v[224:227], v[0:3]
	v_mfma_f32_16x16x32_bf16 v[48:51], v[182:185], v[204:207], v[48:51]
	v_mfma_f32_16x16x32_bf16 v[44:47], v[196:199], v[204:207], v[44:47]
	v_mfma_f32_16x16x32_bf16 v[32:35], v[182:185], v[212:215], v[32:35]
	v_mfma_f32_16x16x32_bf16 v[28:31], v[196:199], v[212:215], v[28:31]
	v_mfma_f32_16x16x32_bf16 v[16:19], v[182:185], v[220:223], v[16:19]
	v_mfma_f32_16x16x32_bf16 v[12:15], v[196:199], v[220:223], v[12:15]
	v_mfma_f32_16x16x32_bf16 v[4:7], v[182:185], v[228:231], v[4:7]
	v_mfma_f32_16x16x32_bf16 v[0:3], v[196:199], v[228:231], v[0:3]
	s_barrier
	s_add_i32 s72, s72, 2
	s_add_u32 s58, s58, 0x100
	s_addc_u32 s59, s59, 0
	s_add_u32 s77, s77, 0x100
	s_addc_u32 s33, s33, 0
	s_cmp_gt_u32 s72, 13
	s_cbranch_scc0 .LBB0_1392
	s_and_b64 vcc, exec, s[40:41]
	s_cbranch_vccz .LBB0_1395
	s_barrier

; #define PG8_STAGE(bufoff, gbase, voff) do { _Pragma("unroll") for (int _i = 0; _i < 2; ++_i) \
;         __builtin_amdgcn_global_load_lds((const unsigned*)((const char*)(gbase) + (voff)[_i]), (PG8_LAS unsigned*)(lds + (bufoff) + ldsw + _i * 8192), 16, 0, 0); } while (0)
; #define PG8_LDA(dst, b, h) do { _Pragma("unroll") for (int m = 0; m < 4; ++m) _Pragma("unroll") for (int k = 0; k < 2; ++k) dst[m][k] = *(const PG8_LAS bf16x8*)(lds + PG8_SA(b, h) + aoff + m * 2048 + k * 1024); } while (0)
; #define PG8_LDB(dst, b, h) do { _Pragma("unroll") for (int n = 0; n < 2; ++n) _Pragma("unroll") for (int k = 0; k < 2; ++k) dst[n][k] = *(const PG8_LAS bf16x8*)(lds + PG8_SB(b, h) + boff + n * 2048 + k * 1024); } while (0)
; #define PG8_MMA(ai, bj, At, Bt) do { __builtin_amdgcn_s_setprio(1); _Pragma("unroll") for (int m = 0; m < 4; ++m) _Pragma("unroll") for (int n = 0; n < 2; ++n) _Pragma("unroll") for (int k = 0; k < 2; ++k) \
;         acc[ai][bj][m][n] = __builtin_amdgcn_mfma_f32_16x16x32_bf16(Bt[n][k], At[m][k], acc[ai][bj][m][n], 0, 0, 0); __builtin_amdgcn_s_setprio(0); } while (0)
; #define PG8_WAIT_V(n) asm volatile("s_waitcnt vmcnt(" #n ")" ::: "memory")
; #define PG8_WAIT_L(n) asm volatile("s_waitcnt lgkmcnt(" #n ")" ::: "memory")
; #define PG8_BAR __builtin_amdgcn_s_barrier()
; #define PG8_SCHED __builtin_amdgcn_sched_barrier(0)
; template <class Epi, class Sched, bool ALIGN_EPI = false, bool SP2 = false>
; __device__ __forceinline__ void gemm_phase(PG8_LAS unsigned char* lds, const Gemm g, const Sched& S, const Epi& E) {
;     ...
;             const char* a1 = cA + (size_t)(t + 1) * kstep;
;             const char* a2 = last ? nA : cA + (size_t)(t + 2) * kstep; const char* b2 = last ? nB : cB + (size_t)(t + 2) * kstep;
;             const char* a3 = a2 + kstep; const char* b3 = b2 + kstep;
;     ...
;             PG8_LDB(B0, 0, 0); PG8_LDB(B1, 0, 1); PG8_SCHED; PG8_LDA(At, 0, 0); PG8_STAGE(PG8_SA(1, 1), a1 + hstep, voffA);
;             PG8_WAIT_V(8); PG8_WAIT_L(0); PG8_BAR; PG8_MMA(0, 0, At, B0); PG8_MMA(0, 1, At, B1); PG8_BAR; PG8_SCHED;
;             PG8_LDA(At, 0, 1); PG8_STAGE(PG8_SB(0, 0), b2, voffB); PG8_STAGE(PG8_SB(0, 1), b2 + hstep, voffB); PG8_STAGE(PG8_SA(0, 0), a2, voffA);
;             PG8_WAIT_V(8); PG8_WAIT_L(0); PG8_BAR; PG8_MMA(1, 0, At, B0); PG8_MMA(1, 1, At, B1); PG8_BAR; PG8_SCHED;
.LBB0_1617:
	ds_read_b128 v[32:35], v191
	ds_read_b128 v[36:39], v191 offset:1024
	ds_read_b128 v[48:51], v191 offset:2048
	ds_read_b128 v[52:55], v191 offset:3072
	ds_read_b128 v[128:131], v195
	ds_read_b128 v[148:151], v195 offset:1024
	ds_read_b128 v[152:155], v195 offset:2048
	ds_read_b128 v[180:183], v195 offset:3072
	s_add_u32 s6, s56, 0xfffc0080
	s_addc_u32 s7, s57, -1
	s_cmp_eq_u32 s69, 12
	s_cselect_b32 s61, s26, s7
	s_cselect_b32 s60, s29, s6
	s_cselect_b32 s59, s49, s33
	s_cselect_b32 s58, s51, s68
	s_add_i32 m0, s78, 0xc000
	ds_read_b128 v[184:187], v198
	ds_read_b128 v[200:203], v198 offset:1024
	ds_read_b128 v[204:207], v198 offset:2048
	ds_read_b128 v[208:211], v198 offset:3072
	ds_read_b128 v[212:215], v198 offset:4096
	ds_read_b128 v[216:219], v198 offset:5120
	ds_read_b128 v[220:223], v198 offset:6144
	global_load_lds_dwordx4 v172, s[56:57]
	s_add_i32 m0, s78, 0xe000
	ds_read_b128 v[224:227], v198 offset:7168
	global_load_lds_dwordx4 v174, s[56:57]
	s_waitcnt vmcnt(8)
	s_waitcnt lgkmcnt(0)
	s_barrier
	s_waitcnt lgkmcnt(0)
	v_mfma_f32_16x16x32_bf16 v[144:147], v[32:35], v[184:187], v[144:147]
	v_mfma_f32_16x16x32_bf16 v[140:143], v[48:51], v[184:187], v[140:143]
	v_mfma_f32_16x16x32_bf16 v[124:127], v[32:35], v[204:207], v[124:127]
	v_mfma_f32_16x16x32_bf16 v[120:123], v[48:51], v[204:207], v[120:123]
	v_mfma_f32_16x16x32_bf16 v[108:111], v[32:35], v[212:215], v[108:111]
	v_mfma_f32_16x16x32_bf16 v[104:107], v[48:51], v[212:215], v[104:107]
	v_mfma_f32_16x16x32_bf16 v[92:95], v[32:35], v[220:223], v[92:95]
	v_mfma_f32_16x16x32_bf16 v[88:91], v[48:51], v[220:223], v[88:91]
	v_mfma_f32_16x16x32_bf16 v[144:147], v[36:39], v[200:203], v[144:147]
	v_mfma_f32_16x16x32_bf16 v[140:143], v[52:55], v[200:203], v[140:143]
	v_mfma_f32_16x16x32_bf16 v[124:127], v[36:39], v[208:211], v[124:127]
	v_mfma_f32_16x16x32_bf16 v[120:123], v[52:55], v[208:211], v[120:123]
	v_mfma_f32_16x16x32_bf16 v[108:111], v[36:39], v[216:219], v[108:111]
	v_mfma_f32_16x16x32_bf16 v[104:107], v[52:55], v[216:219], v[104:107]
	v_mfma_f32_16x16x32_bf16 v[92:95], v[36:39], v[224:227], v[92:95]
	v_mfma_f32_16x16x32_bf16 v[88:91], v[52:55], v[224:227], v[88:91]
	v_mfma_f32_16x16x32_bf16 v[136:139], v[128:131], v[184:187], v[136:139]
	v_mfma_f32_16x16x32_bf16 v[132:135], v[152:155], v[184:187], v[132:135]
	v_mfma_f32_16x16x32_bf16 v[116:119], v[128:131], v[204:207], v[116:119]
	v_mfma_f32_16x16x32_bf16 v[112:115], v[152:155], v[204:207], v[112:115]
	v_mfma_f32_16x16x32_bf16 v[100:103], v[128:131], v[212:215], v[100:103]
	v_mfma_f32_16x16x32_bf16 v[96:99], v[152:155], v[212:215], v[96:99]
	v_mfma_f32_16x16x32_bf16 v[84:87], v[128:131], v[220:223], v[84:87]
	v_mfma_f32_16x16x32_bf16 v[80:83], v[152:155], v[220:223], v[80:83]
	v_mfma_f32_16x16x32_bf16 v[136:139], v[148:151], v[200:203], v[136:139]
	v_mfma_f32_16x16x32_bf16 v[132:135], v[180:183], v[200:203], v[132:135]
	v_mfma_f32_16x16x32_bf16 v[116:119], v[148:151], v[208:211], v[116:119]
	v_mfma_f32_16x16x32_bf16 v[112:115], v[180:183], v[208:211], v[112:115]
	v_mfma_f32_16x16x32_bf16 v[100:103], v[148:151], v[216:219], v[100:103]
	v_mfma_f32_16x16x32_bf16 v[96:99], v[180:183], v[216:219], v[96:99]
	v_mfma_f32_16x16x32_bf16 v[84:87], v[148:151], v[224:227], v[84:87]
	v_mfma_f32_16x16x32_bf16 v[80:83], v[180:183], v[224:227], v[80:83]
	s_barrier
	s_add_i32 s6, s43, s67
	s_mov_b32 m0, s6
	ds_read_b128 v[184:187], v198 offset:16384
	ds_read_b128 v[200:203], v198 offset:17408
	ds_read_b128 v[204:207], v198 offset:18432
	ds_read_b128 v[208:211], v198 offset:19456
	ds_read_b128 v[212:215], v198 offset:20480
	global_load_lds_dwordx4 v158, s[58:59]
	s_add_i32 m0, s6, 0x2000
	s_add_u32 s6, s58, 0x40000
	s_addc_u32 s7, s59, 0
	s_add_i32 s72, s76, s67
	global_load_lds_dwordx4 v170, s[58:59]
	s_mov_b32 m0, s72
	s_nop 0
	global_load_lds_dwordx4 v158, s[6:7]
	s_add_i32 m0, s72, 0x2000
	ds_read_b128 v[224:227], v198 offset:23552
	global_load_lds_dwordx4 v170, s[6:7]
	s_mov_b32 m0, s78
	ds_read_b128 v[220:223], v198 offset:22528
	global_load_lds_dwordx4 v156, s[60:61]
	s_mov_b32 m0, s79
	ds_read_b128 v[216:219], v198 offset:21504
	global_load_lds_dwordx4 v164, s[60:61]
	s_waitcnt vmcnt(8)
	s_waitcnt lgkmcnt(0)
	s_barrier
	s_waitcnt lgkmcnt(0)
	v_mfma_f32_16x16x32_bf16 v[76:79], v[32:35], v[184:187], v[76:79]
	v_mfma_f32_16x16x32_bf16 v[72:75], v[48:51], v[184:187], v[72:75]
	v_mfma_f32_16x16x32_bf16 v[60:63], v[32:35], v[204:207], v[60:63]
	v_mfma_f32_16x16x32_bf16 v[56:59], v[48:51], v[204:207], v[56:59]
	v_mfma_f32_16x16x32_bf16 v[28:31], v[32:35], v[212:215], v[28:31]
	v_mfma_f32_16x16x32_bf16 v[24:27], v[48:51], v[212:215], v[24:27]
	v_mfma_f32_16x16x32_bf16 v[12:15], v[32:35], v[220:223], v[12:15]
	v_mfma_f32_16x16x32_bf16 v[8:11], v[48:51], v[220:223], v[8:11]
	v_mfma_f32_16x16x32_bf16 v[76:79], v[36:39], v[200:203], v[76:79]
	v_mfma_f32_16x16x32_bf16 v[72:75], v[52:55], v[200:203], v[72:75]
	v_mfma_f32_16x16x32_bf16 v[60:63], v[36:39], v[208:211], v[60:63]
	v_mfma_f32_16x16x32_bf16 v[56:59], v[52:55], v[208:211], v[56:59]
	v_mfma_f32_16x16x32_bf16 v[28:31], v[36:39], v[216:219], v[28:31]
	v_mfma_f32_16x16x32_bf16 v[24:27], v[52:55], v[216:219], v[24:27]
	v_mfma_f32_16x16x32_bf16 v[12:15], v[36:39], v[224:227], v[12:15]
	v_mfma_f32_16x16x32_bf16 v[8:11], v[52:55], v[224:227], v[8:11]
	v_mfma_f32_16x16x32_bf16 v[44:47], v[128:131], v[204:207], v[44:47]
	v_mfma_f32_16x16x32_bf16 v[40:43], v[152:155], v[204:207], v[40:43]
	v_mfma_f32_16x16x32_bf16 v[20:23], v[128:131], v[212:215], v[20:23]
	v_mfma_f32_16x16x32_bf16 v[16:19], v[152:155], v[212:215], v[16:19]
	v_mfma_f32_16x16x32_bf16 v[4:7], v[128:131], v[220:223], v[4:7]
	v_mfma_f32_16x16x32_bf16 v[0:3], v[152:155], v[220:223], v[0:3]
	v_mfma_f32_16x16x32_bf16 v[32:35], v[128:131], v[184:187], v[68:71]
	v_mfma_f32_16x16x32_bf16 v[36:39], v[152:155], v[184:187], v[64:67]
	v_mfma_f32_16x16x32_bf16 v[44:47], v[148:151], v[208:211], v[44:47]
	v_mfma_f32_16x16x32_bf16 v[40:43], v[180:183], v[208:211], v[40:43]
	v_mfma_f32_16x16x32_bf16 v[20:23], v[148:151], v[216:219], v[20:23]
	v_mfma_f32_16x16x32_bf16 v[16:19], v[180:183], v[216:219], v[16:19]
	v_mfma_f32_16x16x32_bf16 v[4:7], v[148:151], v[224:227], v[4:7]
	v_mfma_f32_16x16x32_bf16 v[0:3], v[180:183], v[224:227], v[0:3]
	v_mfma_f32_16x16x32_bf16 v[32:35], v[148:151], v[200:203], v[32:35]
	v_mfma_f32_16x16x32_bf16 v[36:39], v[180:183], v[200:203], v[36:39]
	s_barrier
; #define PG8_STAGE(bufoff, gbase, voff) do { _Pragma("unroll") for (int _i = 0; _i < 2; ++_i) \
;         __builtin_amdgcn_global_load_lds((const unsigned*)((const char*)(gbase) + (voff)[_i]), (PG8_LAS unsigned*)(lds + (bufoff) + ldsw + _i * 8192), 16, 0, 0); } while (0)
; #define PG8_LDA(dst, b, h) do { _Pragma("unroll") for (int m = 0; m < 4; ++m) _Pragma("unroll") for (int k = 0; k < 2; ++k) dst[m][k] = *(const PG8_LAS bf16x8*)(lds + PG8_SA(b, h) + aoff + m * 2048 + k * 1024); } while (0)
; #define PG8_LDB(dst, b, h) do { _Pragma("unroll") for (int n = 0; n < 2; ++n) _Pragma("unroll") for (int k = 0; k < 2; ++k) dst[n][k] = *(const PG8_LAS bf16x8*)(lds + PG8_SB(b, h) + boff + n * 2048 + k * 1024); } while (0)
; #define PG8_MMA(ai, bj, At, Bt) do { __builtin_amdgcn_s_setprio(1); _Pragma("unroll") for (int m = 0; m < 4; ++m) _Pragma("unroll") for (int n = 0; n < 2; ++n) _Pragma("unroll") for (int k = 0; k < 2; ++k) \
;         acc[ai][bj][m][n] = __builtin_amdgcn_mfma_f32_16x16x32_bf16(Bt[n][k], At[m][k], acc[ai][bj][m][n], 0, 0, 0); __builtin_amdgcn_s_setprio(0); } while (0)
; #define PG8_WAIT_V(n) asm volatile("s_waitcnt vmcnt(" #n ")" ::: "memory")
; #define PG8_WAIT_L(n) asm volatile("s_waitcnt lgkmcnt(" #n ")" ::: "memory")
; #define PG8_BAR __builtin_amdgcn_s_barrier()
; #define PG8_SCHED __builtin_amdgcn_sched_barrier(0)
; template <class Epi, class Sched, bool ALIGN_EPI = false, bool SP2 = false>
; __device__ __forceinline__ void gemm_phase(PG8_LAS unsigned char* lds, const Gemm g, const Sched& S, const Epi& E) {
;     ...
;             PG8_LDB(B0, 1, 0); PG8_LDB(B1, 1, 1); PG8_SCHED; PG8_LDA(At, 1, 0); PG8_STAGE(PG8_SA(0, 1), a2 + hstep, voffA);
;             PG8_WAIT_V(8); PG8_WAIT_L(0); PG8_BAR; PG8_MMA(0, 0, At, B0); PG8_MMA(0, 1, At, B1); PG8_BAR; PG8_SCHED;
;             PG8_LDA(At, 1, 1); PG8_STAGE(PG8_SB(1, 0), b3, voffB); PG8_STAGE(PG8_SB(1, 1), b3 + hstep, voffB); PG8_STAGE(PG8_SA(1, 0), a3, voffA);
;             PG8_WAIT_V(8); PG8_WAIT_L(0); PG8_BAR; PG8_MMA(1, 0, At, B0); PG8_MMA(1, 1, At, B1); PG8_BAR; PG8_SCHED;
	s_add_i32 s72, 0, 0x18000
	s_add_i32 s73, 0, 0x1c000
	v_add_u32_e32 v68, s72, v169
	v_add_u32_e32 v180, s73, v169
	ds_read_b128 v[48:51], v68
	ds_read_b128 v[52:55], v68 offset:1024
	ds_read_b128 v[64:67], v68 offset:2048
	ds_read_b128 v[68:71], v68 offset:3072
	ds_read_b128 v[128:131], v180
	ds_read_b128 v[148:151], v180 offset:1024
	ds_read_b128 v[152:155], v180 offset:2048
	ds_read_b128 v[180:183], v180 offset:3072
	s_add_u32 s6, s60, 0x40000
	s_addc_u32 s7, s61, 0
	s_mov_b32 m0, s80
	ds_read_b128 v[184:187], v198 offset:32768
	ds_read_b128 v[200:203], v198 offset:33792
	ds_read_b128 v[204:207], v198 offset:34816
	ds_read_b128 v[208:211], v198 offset:35840
	ds_read_b128 v[212:215], v198 offset:36864
	ds_read_b128 v[216:219], v198 offset:37888
	ds_read_b128 v[220:223], v198 offset:38912
	global_load_lds_dwordx4 v156, s[6:7]
	s_mov_b32 m0, s81
	ds_read_b128 v[224:227], v198 offset:39936
	global_load_lds_dwordx4 v164, s[6:7]
	s_waitcnt vmcnt(8)
	s_waitcnt lgkmcnt(0)
	s_barrier
	s_waitcnt lgkmcnt(0)
	v_mfma_f32_16x16x32_bf16 v[144:147], v[48:51], v[184:187], v[144:147]
	v_mfma_f32_16x16x32_bf16 v[140:143], v[64:67], v[184:187], v[140:143]
	v_mfma_f32_16x16x32_bf16 v[124:127], v[48:51], v[204:207], v[124:127]
	v_mfma_f32_16x16x32_bf16 v[120:123], v[64:67], v[204:207], v[120:123]
	v_mfma_f32_16x16x32_bf16 v[108:111], v[48:51], v[212:215], v[108:111]
	v_mfma_f32_16x16x32_bf16 v[104:107], v[64:67], v[212:215], v[104:107]
	v_mfma_f32_16x16x32_bf16 v[92:95], v[48:51], v[220:223], v[92:95]
	v_mfma_f32_16x16x32_bf16 v[88:91], v[64:67], v[220:223], v[88:91]
	v_mfma_f32_16x16x32_bf16 v[144:147], v[52:55], v[200:203], v[144:147]
	v_mfma_f32_16x16x32_bf16 v[140:143], v[68:71], v[200:203], v[140:143]
	v_mfma_f32_16x16x32_bf16 v[124:127], v[52:55], v[208:211], v[124:127]
	v_mfma_f32_16x16x32_bf16 v[120:123], v[68:71], v[208:211], v[120:123]
	v_mfma_f32_16x16x32_bf16 v[108:111], v[52:55], v[216:219], v[108:111]
	v_mfma_f32_16x16x32_bf16 v[104:107], v[68:71], v[216:219], v[104:107]
	v_mfma_f32_16x16x32_bf16 v[92:95], v[52:55], v[224:227], v[92:95]
	v_mfma_f32_16x16x32_bf16 v[88:91], v[68:71], v[224:227], v[88:91]
	v_mfma_f32_16x16x32_bf16 v[136:139], v[128:131], v[184:187], v[136:139]
	v_mfma_f32_16x16x32_bf16 v[132:135], v[152:155], v[184:187], v[132:135]
	v_mfma_f32_16x16x32_bf16 v[116:119], v[128:131], v[204:207], v[116:119]
	v_mfma_f32_16x16x32_bf16 v[112:115], v[152:155], v[204:207], v[112:115]
	v_mfma_f32_16x16x32_bf16 v[100:103], v[128:131], v[212:215], v[100:103]
	v_mfma_f32_16x16x32_bf16 v[96:99], v[152:155], v[212:215], v[96:99]
	v_mfma_f32_16x16x32_bf16 v[84:87], v[128:131], v[220:223], v[84:87]
	v_mfma_f32_16x16x32_bf16 v[80:83], v[152:155], v[220:223], v[80:83]
	v_mfma_f32_16x16x32_bf16 v[136:139], v[148:151], v[200:203], v[136:139]
	v_mfma_f32_16x16x32_bf16 v[132:135], v[180:183], v[200:203], v[132:135]
	v_mfma_f32_16x16x32_bf16 v[116:119], v[148:151], v[208:211], v[116:119]
	v_mfma_f32_16x16x32_bf16 v[112:115], v[180:183], v[208:211], v[112:115]
	v_mfma_f32_16x16x32_bf16 v[100:103], v[148:151], v[216:219], v[100:103]
	v_mfma_f32_16x16x32_bf16 v[96:99], v[180:183], v[216:219], v[96:99]
	v_mfma_f32_16x16x32_bf16 v[84:87], v[148:151], v[224:227], v[84:87]
	v_mfma_f32_16x16x32_bf16 v[80:83], v[180:183], v[224:227], v[80:83]
	s_barrier
	s_add_i32 s6, s72, s67
	s_add_u32 s98, s58, 0x80
	s_addc_u32 s99, s59, 0
	s_add_u32 s100, s60, 0x80
	s_addc_u32 s101, s61, 0
	s_mov_b32 m0, s6
	ds_read_b128 v[184:187], v198 offset:49152
	ds_read_b128 v[200:203], v198 offset:50176
	ds_read_b128 v[204:207], v198 offset:51200
	ds_read_b128 v[208:211], v198 offset:52224
	global_load_lds_dwordx4 v158, s[98:99]
	s_add_i32 m0, s6, 0x2000
	s_add_u32 s6, s58, 0x40080
	s_addc_u32 s7, s59, 0
	s_add_i32 s58, s73, s67
	global_load_lds_dwordx4 v170, s[98:99]
	s_mov_b32 m0, s58
	ds_read_b128 v[224:227], v198 offset:56320
	global_load_lds_dwordx4 v158, s[6:7]
	s_add_i32 m0, s58, 0x2000
	ds_read_b128 v[220:223], v198 offset:55296
	global_load_lds_dwordx4 v170, s[6:7]
	s_mov_b32 m0, s45
	ds_read_b128 v[216:219], v198 offset:54272
	global_load_lds_dwordx4 v156, s[100:101]
	s_mov_b32 m0, s42
	ds_read_b128 v[212:215], v198 offset:53248
	global_load_lds_dwordx4 v164, s[100:101]
	s_waitcnt vmcnt(8)
	s_waitcnt lgkmcnt(0)
	s_barrier
	s_waitcnt lgkmcnt(0)
	v_mfma_f32_16x16x32_bf16 v[76:79], v[48:51], v[184:187], v[76:79]
	v_mfma_f32_16x16x32_bf16 v[72:75], v[64:67], v[184:187], v[72:75]
	v_mfma_f32_16x16x32_bf16 v[60:63], v[48:51], v[204:207], v[60:63]
	v_mfma_f32_16x16x32_bf16 v[56:59], v[64:67], v[204:207], v[56:59]
	v_mfma_f32_16x16x32_bf16 v[28:31], v[48:51], v[212:215], v[28:31]
	v_mfma_f32_16x16x32_bf16 v[24:27], v[64:67], v[212:215], v[24:27]
	v_mfma_f32_16x16x32_bf16 v[12:15], v[48:51], v[220:223], v[12:15]
	v_mfma_f32_16x16x32_bf16 v[8:11], v[64:67], v[220:223], v[8:11]
	v_mfma_f32_16x16x32_bf16 v[76:79], v[52:55], v[200:203], v[76:79]
	v_mfma_f32_16x16x32_bf16 v[72:75], v[68:71], v[200:203], v[72:75]
	v_mfma_f32_16x16x32_bf16 v[60:63], v[52:55], v[208:211], v[60:63]
	v_mfma_f32_16x16x32_bf16 v[56:59], v[68:71], v[208:211], v[56:59]
	v_mfma_f32_16x16x32_bf16 v[28:31], v[52:55], v[216:219], v[28:31]
	v_mfma_f32_16x16x32_bf16 v[24:27], v[68:71], v[216:219], v[24:27]
	v_mfma_f32_16x16x32_bf16 v[12:15], v[52:55], v[224:227], v[12:15]
	v_mfma_f32_16x16x32_bf16 v[8:11], v[68:71], v[224:227], v[8:11]
	v_mfma_f32_16x16x32_bf16 v[32:35], v[128:131], v[184:187], v[32:35]
	v_mfma_f32_16x16x32_bf16 v[68:71], v[148:151], v[200:203], v[32:35]
	v_mfma_f32_16x16x32_bf16 v[32:35], v[152:155], v[184:187], v[36:39]
	v_mfma_f32_16x16x32_bf16 v[64:67], v[180:183], v[200:203], v[32:35]
	v_mfma_f32_16x16x32_bf16 v[32:35], v[128:131], v[204:207], v[44:47]
	v_mfma_f32_16x16x32_bf16 v[44:47], v[148:151], v[208:211], v[32:35]
	v_mfma_f32_16x16x32_bf16 v[32:35], v[152:155], v[204:207], v[40:43]
	v_mfma_f32_16x16x32_bf16 v[20:23], v[128:131], v[212:215], v[20:23]
	v_mfma_f32_16x16x32_bf16 v[16:19], v[152:155], v[212:215], v[16:19]
	v_mfma_f32_16x16x32_bf16 v[4:7], v[128:131], v[220:223], v[4:7]
	v_mfma_f32_16x16x32_bf16 v[0:3], v[152:155], v[220:223], v[0:3]
	v_mfma_f32_16x16x32_bf16 v[40:43], v[180:183], v[208:211], v[32:35]
	v_mfma_f32_16x16x32_bf16 v[20:23], v[148:151], v[216:219], v[20:23]
	v_mfma_f32_16x16x32_bf16 v[16:19], v[180:183], v[216:219], v[16:19]
	v_mfma_f32_16x16x32_bf16 v[4:7], v[148:151], v[224:227], v[4:7]
	v_mfma_f32_16x16x32_bf16 v[0:3], v[180:183], v[224:227], v[0:3]
	s_barrier
	s_add_i32 s69, s69, 2
	s_add_u32 s56, s56, 0x100
	s_addc_u32 s57, s57, 0
	s_add_u32 s68, s68, 0x100
	s_addc_u32 s33, s33, 0
	s_cmp_gt_u32 s69, 13
	s_cbranch_scc0 .LBB0_1617
	v_readlane_b32 s68, v243, 59
	s_and_b64 vcc, exec, s[40:41]
	v_readlane_b32 s69, v243, 60
	s_cbranch_vccz .LBB0_1620
	s_barrier

; #define PG8_STAGE(bufoff, gbase, voff) do { _Pragma("unroll") for (int _i = 0; _i < 2; ++_i) \
;         __builtin_amdgcn_global_load_lds((const unsigned*)((const char*)(gbase) + (voff)[_i]), (PG8_LAS unsigned*)(lds + (bufoff) + ldsw + _i * 8192), 16, 0, 0); } while (0)
; #define PG8_LDA(dst, b, h) do { _Pragma("unroll") for (int m = 0; m < 4; ++m) _Pragma("unroll") for (int k = 0; k < 2; ++k) dst[m][k] = *(const PG8_LAS bf16x8*)(lds + PG8_SA(b, h) + aoff + m * 2048 + k * 1024); } while (0)
; #define PG8_LDB(dst, b, h) do { _Pragma("unroll") for (int n = 0; n < 2; ++n) _Pragma("unroll") for (int k = 0; k < 2; ++k) dst[n][k] = *(const PG8_LAS bf16x8*)(lds + PG8_SB(b, h) + boff + n * 2048 + k * 1024); } while (0)
; #define PG8_MMA(ai, bj, At, Bt) do { __builtin_amdgcn_s_setprio(1); _Pragma("unroll") for (int m = 0; m < 4; ++m) _Pragma("unroll") for (int n = 0; n < 2; ++n) _Pragma("unroll") for (int k = 0; k < 2; ++k) \
;         acc[ai][bj][m][n] = __builtin_amdgcn_mfma_f32_16x16x32_bf16(Bt[n][k], At[m][k], acc[ai][bj][m][n], 0, 0, 0); __builtin_amdgcn_s_setprio(0); } while (0)
; #define PG8_WAIT_V(n) asm volatile("s_waitcnt vmcnt(" #n ")" ::: "memory")
; #define PG8_WAIT_L(n) asm volatile("s_waitcnt lgkmcnt(" #n ")" ::: "memory")
; #define PG8_BAR __builtin_amdgcn_s_barrier()
; #define PG8_SCHED __builtin_amdgcn_sched_barrier(0)
; template <class Epi, class Sched, bool ALIGN_EPI = false, bool SP2 = false>
; __device__ __forceinline__ void gemm_phase(PG8_LAS unsigned char* lds, const Gemm g, const Sched& S, const Epi& E) {
;     ...
;             const char* a1 = cA + (size_t)(t + 1) * kstep;
;             const char* a2 = last ? nA : cA + (size_t)(t + 2) * kstep; const char* b2 = last ? nB : cB + (size_t)(t + 2) * kstep;
;             const char* a3 = a2 + kstep; const char* b3 = b2 + kstep;
;     ...
;             PG8_LDB(B0, 0, 0); PG8_LDB(B1, 0, 1); PG8_SCHED; PG8_LDA(At, 0, 0); PG8_STAGE(PG8_SA(1, 1), a1 + hstep, voffA);
;             PG8_WAIT_V(8); PG8_WAIT_L(0); PG8_BAR; PG8_MMA(0, 0, At, B0); PG8_MMA(0, 1, At, B1); PG8_BAR; PG8_SCHED;
;             PG8_LDA(At, 0, 1); PG8_STAGE(PG8_SB(0, 0), b2, voffB); PG8_STAGE(PG8_SB(0, 1), b2 + hstep, voffB); PG8_STAGE(PG8_SA(0, 0), a2, voffA);
;             PG8_WAIT_V(8); PG8_WAIT_L(0); PG8_BAR; PG8_MMA(1, 0, At, B0); PG8_MMA(1, 1, At, B1); PG8_BAR; PG8_SCHED;
.LBB0_1698:
	ds_read_b128 v[144:147], v153
	ds_read_b128 v[170:173], v153 offset:1024
	ds_read_b128 v[174:177], v153 offset:2048
	ds_read_b128 v[178:181], v153 offset:3072
	ds_read_b128 v[182:185], v154
	ds_read_b128 v[186:189], v154 offset:1024
	ds_read_b128 v[198:201], v154 offset:2048
	ds_read_b128 v[202:205], v154 offset:3072
	s_add_u32 s6, s60, 0xfffc0080
	s_addc_u32 s7, s61, -1
	s_cmp_eq_u32 s72, 12
	s_cselect_b32 s81, s29, s7
	s_cselect_b32 s80, s55, s6
	s_cselect_b32 s79, s53, s33
	s_cselect_b32 s78, s68, s69
	s_add_i32 m0, s43, 0xc000
	ds_read_b128 v[206:209], v155
	ds_read_b128 v[210:213], v155 offset:1024
	ds_read_b128 v[214:217], v155 offset:2048
	ds_read_b128 v[218:221], v155 offset:3072
	ds_read_b128 v[222:225], v155 offset:4096
	ds_read_b128 v[226:229], v155 offset:5120
	ds_read_b128 v[230:233], v155 offset:6144
	global_load_lds_dwordx4 v136, s[60:61]
	s_add_i32 m0, s43, 0xe000
	ds_read_b128 v[234:237], v155 offset:7168
	global_load_lds_dwordx4 v138, s[60:61]
	s_waitcnt vmcnt(8)
	s_waitcnt lgkmcnt(0)
	s_barrier
	s_waitcnt lgkmcnt(0)
	v_mfma_f32_16x16x32_bf16 v[124:127], v[144:147], v[206:209], v[124:127]
	v_mfma_f32_16x16x32_bf16 v[120:123], v[174:177], v[206:209], v[120:123]
	v_mfma_f32_16x16x32_bf16 v[108:111], v[144:147], v[214:217], v[108:111]
	v_mfma_f32_16x16x32_bf16 v[104:107], v[174:177], v[214:217], v[104:107]
	v_mfma_f32_16x16x32_bf16 v[92:95], v[144:147], v[222:225], v[92:95]
	v_mfma_f32_16x16x32_bf16 v[88:91], v[174:177], v[222:225], v[88:91]
	v_mfma_f32_16x16x32_bf16 v[76:79], v[144:147], v[230:233], v[76:79]
	v_mfma_f32_16x16x32_bf16 v[72:75], v[174:177], v[230:233], v[72:75]
	v_mfma_f32_16x16x32_bf16 v[124:127], v[170:173], v[210:213], v[124:127]
	v_mfma_f32_16x16x32_bf16 v[120:123], v[178:181], v[210:213], v[120:123]
	v_mfma_f32_16x16x32_bf16 v[108:111], v[170:173], v[218:221], v[108:111]
	v_mfma_f32_16x16x32_bf16 v[104:107], v[178:181], v[218:221], v[104:107]
	v_mfma_f32_16x16x32_bf16 v[92:95], v[170:173], v[226:229], v[92:95]
	v_mfma_f32_16x16x32_bf16 v[88:91], v[178:181], v[226:229], v[88:91]
	v_mfma_f32_16x16x32_bf16 v[76:79], v[170:173], v[234:237], v[76:79]
	v_mfma_f32_16x16x32_bf16 v[72:75], v[178:181], v[234:237], v[72:75]
	v_mfma_f32_16x16x32_bf16 v[116:119], v[182:185], v[206:209], v[116:119]
	v_mfma_f32_16x16x32_bf16 v[112:115], v[198:201], v[206:209], v[112:115]
	v_mfma_f32_16x16x32_bf16 v[100:103], v[182:185], v[214:217], v[100:103]
	v_mfma_f32_16x16x32_bf16 v[96:99], v[198:201], v[214:217], v[96:99]
	v_mfma_f32_16x16x32_bf16 v[84:87], v[182:185], v[222:225], v[84:87]
	v_mfma_f32_16x16x32_bf16 v[80:83], v[198:201], v[222:225], v[80:83]
	v_mfma_f32_16x16x32_bf16 v[68:71], v[182:185], v[230:233], v[68:71]
	v_mfma_f32_16x16x32_bf16 v[64:67], v[198:201], v[230:233], v[64:67]
	v_mfma_f32_16x16x32_bf16 v[116:119], v[186:189], v[210:213], v[116:119]
	v_mfma_f32_16x16x32_bf16 v[112:115], v[202:205], v[210:213], v[112:115]
	v_mfma_f32_16x16x32_bf16 v[100:103], v[186:189], v[218:221], v[100:103]
	v_mfma_f32_16x16x32_bf16 v[96:99], v[202:205], v[218:221], v[96:99]
	v_mfma_f32_16x16x32_bf16 v[84:87], v[186:189], v[226:229], v[84:87]
	v_mfma_f32_16x16x32_bf16 v[80:83], v[202:205], v[226:229], v[80:83]
	v_mfma_f32_16x16x32_bf16 v[68:71], v[186:189], v[234:237], v[68:71]
	v_mfma_f32_16x16x32_bf16 v[64:67], v[202:205], v[234:237], v[64:67]
	s_barrier
	s_add_i32 s6, s26, s42
	s_mov_b32 m0, s6
	ds_read_b128 v[206:209], v155 offset:16384
	ds_read_b128 v[210:213], v155 offset:17408
	ds_read_b128 v[214:217], v155 offset:18432
	ds_read_b128 v[218:221], v155 offset:19456
	ds_read_b128 v[222:225], v155 offset:20480
	global_load_lds_dwordx4 v130, s[78:79]
	s_add_i32 m0, s6, 0x2000
	s_add_u32 s6, s78, 0x40000
	s_addc_u32 s7, s79, 0
	s_add_i32 s73, s74, s42
	global_load_lds_dwordx4 v134, s[78:79]
	s_mov_b32 m0, s73
	s_nop 0
	global_load_lds_dwordx4 v130, s[6:7]
	s_add_i32 m0, s73, 0x2000
	ds_read_b128 v[234:237], v155 offset:23552
	global_load_lds_dwordx4 v134, s[6:7]
	s_mov_b32 m0, s43
	ds_read_b128 v[230:233], v155 offset:22528
	global_load_lds_dwordx4 v128, s[80:81]
	s_mov_b32 m0, s44
	ds_read_b128 v[226:229], v155 offset:21504
	global_load_lds_dwordx4 v132, s[80:81]
	s_waitcnt vmcnt(8)
	s_waitcnt lgkmcnt(0)
	s_barrier
	s_waitcnt lgkmcnt(0)
	v_mfma_f32_16x16x32_bf16 v[60:63], v[144:147], v[206:209], v[60:63]
	v_mfma_f32_16x16x32_bf16 v[56:59], v[174:177], v[206:209], v[56:59]
	v_mfma_f32_16x16x32_bf16 v[44:47], v[144:147], v[214:217], v[44:47]
	v_mfma_f32_16x16x32_bf16 v[40:43], v[174:177], v[214:217], v[40:43]
	v_mfma_f32_16x16x32_bf16 v[28:31], v[144:147], v[222:225], v[28:31]
	v_mfma_f32_16x16x32_bf16 v[24:27], v[174:177], v[222:225], v[24:27]
	v_mfma_f32_16x16x32_bf16 v[12:15], v[144:147], v[230:233], v[12:15]
	v_mfma_f32_16x16x32_bf16 v[8:11], v[174:177], v[230:233], v[8:11]
	v_mfma_f32_16x16x32_bf16 v[60:63], v[170:173], v[210:213], v[60:63]
	v_mfma_f32_16x16x32_bf16 v[56:59], v[178:181], v[210:213], v[56:59]
	v_mfma_f32_16x16x32_bf16 v[44:47], v[170:173], v[218:221], v[44:47]
	v_mfma_f32_16x16x32_bf16 v[40:43], v[178:181], v[218:221], v[40:43]
	v_mfma_f32_16x16x32_bf16 v[28:31], v[170:173], v[226:229], v[28:31]
	v_mfma_f32_16x16x32_bf16 v[24:27], v[178:181], v[226:229], v[24:27]
	v_mfma_f32_16x16x32_bf16 v[12:15], v[170:173], v[234:237], v[12:15]
	v_mfma_f32_16x16x32_bf16 v[8:11], v[178:181], v[234:237], v[8:11]
	v_mfma_f32_16x16x32_bf16 v[52:55], v[182:185], v[206:209], v[52:55]
	v_mfma_f32_16x16x32_bf16 v[48:51], v[198:201], v[206:209], v[48:51]
	v_mfma_f32_16x16x32_bf16 v[36:39], v[182:185], v[214:217], v[36:39]
	v_mfma_f32_16x16x32_bf16 v[32:35], v[198:201], v[214:217], v[32:35]
	v_mfma_f32_16x16x32_bf16 v[20:23], v[182:185], v[222:225], v[20:23]
	v_mfma_f32_16x16x32_bf16 v[16:19], v[198:201], v[222:225], v[16:19]
	v_mfma_f32_16x16x32_bf16 v[4:7], v[182:185], v[230:233], v[4:7]
	v_mfma_f32_16x16x32_bf16 v[0:3], v[198:201], v[230:233], v[0:3]
	v_mfma_f32_16x16x32_bf16 v[52:55], v[186:189], v[210:213], v[52:55]
	v_mfma_f32_16x16x32_bf16 v[48:51], v[202:205], v[210:213], v[48:51]
	v_mfma_f32_16x16x32_bf16 v[36:39], v[186:189], v[218:221], v[36:39]
	v_mfma_f32_16x16x32_bf16 v[32:35], v[202:205], v[218:221], v[32:35]
	v_mfma_f32_16x16x32_bf16 v[20:23], v[186:189], v[226:229], v[20:23]
	v_mfma_f32_16x16x32_bf16 v[16:19], v[202:205], v[226:229], v[16:19]
	v_mfma_f32_16x16x32_bf16 v[4:7], v[186:189], v[234:237], v[4:7]
	v_mfma_f32_16x16x32_bf16 v[0:3], v[202:205], v[234:237], v[0:3]
	s_barrier
; #define PG8_STAGE(bufoff, gbase, voff) do { _Pragma("unroll") for (int _i = 0; _i < 2; ++_i) \
;         __builtin_amdgcn_global_load_lds((const unsigned*)((const char*)(gbase) + (voff)[_i]), (PG8_LAS unsigned*)(lds + (bufoff) + ldsw + _i * 8192), 16, 0, 0); } while (0)
; #define PG8_LDA(dst, b, h) do { _Pragma("unroll") for (int m = 0; m < 4; ++m) _Pragma("unroll") for (int k = 0; k < 2; ++k) dst[m][k] = *(const PG8_LAS bf16x8*)(lds + PG8_SA(b, h) + aoff + m * 2048 + k * 1024); } while (0)
; #define PG8_LDB(dst, b, h) do { _Pragma("unroll") for (int n = 0; n < 2; ++n) _Pragma("unroll") for (int k = 0; k < 2; ++k) dst[n][k] = *(const PG8_LAS bf16x8*)(lds + PG8_SB(b, h) + boff + n * 2048 + k * 1024); } while (0)
; #define PG8_MMA(ai, bj, At, Bt) do { __builtin_amdgcn_s_setprio(1); _Pragma("unroll") for (int m = 0; m < 4; ++m) _Pragma("unroll") for (int n = 0; n < 2; ++n) _Pragma("unroll") for (int k = 0; k < 2; ++k) \
;         acc[ai][bj][m][n] = __builtin_amdgcn_mfma_f32_16x16x32_bf16(Bt[n][k], At[m][k], acc[ai][bj][m][n], 0, 0, 0); __builtin_amdgcn_s_setprio(0); } while (0)
; #define PG8_WAIT_V(n) asm volatile("s_waitcnt vmcnt(" #n ")" ::: "memory")
; #define PG8_WAIT_L(n) asm volatile("s_waitcnt lgkmcnt(" #n ")" ::: "memory")
; #define PG8_BAR __builtin_amdgcn_s_barrier()
; #define PG8_SCHED __builtin_amdgcn_sched_barrier(0)
; template <class Epi, class Sched, bool ALIGN_EPI = false, bool SP2 = false>
; __device__ __forceinline__ void gemm_phase(PG8_LAS unsigned char* lds, const Gemm g, const Sched& S, const Epi& E) {
;     ...
;             PG8_LDB(B0, 1, 0); PG8_LDB(B1, 1, 1); PG8_SCHED; PG8_LDA(At, 1, 0); PG8_STAGE(PG8_SA(0, 1), a2 + hstep, voffA);
;             PG8_WAIT_V(8); PG8_WAIT_L(0); PG8_BAR; PG8_MMA(0, 0, At, B0); PG8_MMA(0, 1, At, B1); PG8_BAR; PG8_SCHED;
;             PG8_LDA(At, 1, 1); PG8_STAGE(PG8_SB(1, 0), b3, voffB); PG8_STAGE(PG8_SB(1, 1), b3 + hstep, voffB); PG8_STAGE(PG8_SA(1, 0), a3, voffA);
;             PG8_WAIT_V(8); PG8_WAIT_L(0); PG8_BAR; PG8_MMA(1, 0, At, B0); PG8_MMA(1, 1, At, B1); PG8_BAR; PG8_SCHED;
	s_add_i32 s73, 0, 0x18000
	v_add_u32_e32 v157, s73, v151
	s_add_i32 s82, 0, 0x1c000
	ds_read_b128 v[144:147], v157
	ds_read_b128 v[170:173], v157 offset:1024
	ds_read_b128 v[174:177], v157 offset:2048
	ds_read_b128 v[178:181], v157 offset:3072
	v_add_u32_e32 v157, s82, v151
	ds_read_b128 v[182:185], v157
	ds_read_b128 v[186:189], v157 offset:1024
	ds_read_b128 v[198:201], v157 offset:2048
	ds_read_b128 v[202:205], v157 offset:3072
	s_add_u32 s6, s80, 0x40000
	s_addc_u32 s7, s81, 0
	s_mov_b32 m0, s45
	ds_read_b128 v[206:209], v155 offset:32768
	ds_read_b128 v[210:213], v155 offset:33792
	ds_read_b128 v[214:217], v155 offset:34816
	ds_read_b128 v[218:221], v155 offset:35840
	ds_read_b128 v[222:225], v155 offset:36864
	ds_read_b128 v[226:229], v155 offset:37888
	ds_read_b128 v[230:233], v155 offset:38912
	global_load_lds_dwordx4 v128, s[6:7]
	s_mov_b32 m0, s67
	ds_read_b128 v[234:237], v155 offset:39936
	global_load_lds_dwordx4 v132, s[6:7]
	s_waitcnt vmcnt(8)
	s_waitcnt lgkmcnt(0)
	s_barrier
	s_waitcnt lgkmcnt(0)
	v_mfma_f32_16x16x32_bf16 v[124:127], v[144:147], v[206:209], v[124:127]
	v_mfma_f32_16x16x32_bf16 v[120:123], v[174:177], v[206:209], v[120:123]
	v_mfma_f32_16x16x32_bf16 v[108:111], v[144:147], v[214:217], v[108:111]
	v_mfma_f32_16x16x32_bf16 v[104:107], v[174:177], v[214:217], v[104:107]
	v_mfma_f32_16x16x32_bf16 v[92:95], v[144:147], v[222:225], v[92:95]
	v_mfma_f32_16x16x32_bf16 v[88:91], v[174:177], v[222:225], v[88:91]
	v_mfma_f32_16x16x32_bf16 v[76:79], v[144:147], v[230:233], v[76:79]
	v_mfma_f32_16x16x32_bf16 v[72:75], v[174:177], v[230:233], v[72:75]
	v_mfma_f32_16x16x32_bf16 v[124:127], v[170:173], v[210:213], v[124:127]
	v_mfma_f32_16x16x32_bf16 v[120:123], v[178:181], v[210:213], v[120:123]
	v_mfma_f32_16x16x32_bf16 v[108:111], v[170:173], v[218:221], v[108:111]
	v_mfma_f32_16x16x32_bf16 v[104:107], v[178:181], v[218:221], v[104:107]
	v_mfma_f32_16x16x32_bf16 v[92:95], v[170:173], v[226:229], v[92:95]
	v_mfma_f32_16x16x32_bf16 v[88:91], v[178:181], v[226:229], v[88:91]
	v_mfma_f32_16x16x32_bf16 v[76:79], v[170:173], v[234:237], v[76:79]
	v_mfma_f32_16x16x32_bf16 v[72:75], v[178:181], v[234:237], v[72:75]
	v_mfma_f32_16x16x32_bf16 v[116:119], v[182:185], v[206:209], v[116:119]
	v_mfma_f32_16x16x32_bf16 v[112:115], v[198:201], v[206:209], v[112:115]
	v_mfma_f32_16x16x32_bf16 v[100:103], v[182:185], v[214:217], v[100:103]
	v_mfma_f32_16x16x32_bf16 v[96:99], v[198:201], v[214:217], v[96:99]
	v_mfma_f32_16x16x32_bf16 v[84:87], v[182:185], v[222:225], v[84:87]
	v_mfma_f32_16x16x32_bf16 v[80:83], v[198:201], v[222:225], v[80:83]
	v_mfma_f32_16x16x32_bf16 v[68:71], v[182:185], v[230:233], v[68:71]
	v_mfma_f32_16x16x32_bf16 v[64:67], v[198:201], v[230:233], v[64:67]
	v_mfma_f32_16x16x32_bf16 v[116:119], v[186:189], v[210:213], v[116:119]
	v_mfma_f32_16x16x32_bf16 v[112:115], v[202:205], v[210:213], v[112:115]
	v_mfma_f32_16x16x32_bf16 v[100:103], v[186:189], v[218:221], v[100:103]
	v_mfma_f32_16x16x32_bf16 v[96:99], v[202:205], v[218:221], v[96:99]
	v_mfma_f32_16x16x32_bf16 v[84:87], v[186:189], v[226:229], v[84:87]
	v_mfma_f32_16x16x32_bf16 v[80:83], v[202:205], v[226:229], v[80:83]
	v_mfma_f32_16x16x32_bf16 v[68:71], v[186:189], v[234:237], v[68:71]
	v_mfma_f32_16x16x32_bf16 v[64:67], v[202:205], v[234:237], v[64:67]
	s_barrier
	s_add_i32 s6, s73, s42
	s_add_u32 s98, s78, 0x80
	s_addc_u32 s99, s79, 0
	s_add_u32 s100, s80, 0x80
	s_addc_u32 s101, s81, 0
	s_mov_b32 m0, s6
	ds_read_b128 v[206:209], v155 offset:49152
	ds_read_b128 v[210:213], v155 offset:50176
	ds_read_b128 v[214:217], v155 offset:51200
	ds_read_b128 v[218:221], v155 offset:52224
	global_load_lds_dwordx4 v130, s[98:99]
	s_add_i32 m0, s6, 0x2000
	s_add_u32 s6, s78, 0x40080
	s_addc_u32 s7, s79, 0
	s_add_i32 s73, s82, s42
	global_load_lds_dwordx4 v134, s[98:99]
	s_mov_b32 m0, s73
	ds_read_b128 v[234:237], v155 offset:56320
	global_load_lds_dwordx4 v130, s[6:7]
	s_add_i32 m0, s73, 0x2000
	ds_read_b128 v[230:233], v155 offset:55296
	global_load_lds_dwordx4 v134, s[6:7]
	s_mov_b32 m0, s4
	ds_read_b128 v[226:229], v155 offset:54272
	global_load_lds_dwordx4 v128, s[100:101]
	s_mov_b32 m0, s77
	ds_read_b128 v[222:225], v155 offset:53248
	global_load_lds_dwordx4 v132, s[100:101]
	s_waitcnt vmcnt(8)
	s_waitcnt lgkmcnt(0)
	s_barrier
	s_waitcnt lgkmcnt(0)
	v_mfma_f32_16x16x32_bf16 v[60:63], v[144:147], v[206:209], v[60:63]
	v_mfma_f32_16x16x32_bf16 v[56:59], v[174:177], v[206:209], v[56:59]
	v_mfma_f32_16x16x32_bf16 v[44:47], v[144:147], v[214:217], v[44:47]
	v_mfma_f32_16x16x32_bf16 v[40:43], v[174:177], v[214:217], v[40:43]
	v_mfma_f32_16x16x32_bf16 v[28:31], v[144:147], v[222:225], v[28:31]
	v_mfma_f32_16x16x32_bf16 v[24:27], v[174:177], v[222:225], v[24:27]
	v_mfma_f32_16x16x32_bf16 v[12:15], v[144:147], v[230:233], v[12:15]
	v_mfma_f32_16x16x32_bf16 v[8:11], v[174:177], v[230:233], v[8:11]
	v_mfma_f32_16x16x32_bf16 v[60:63], v[170:173], v[210:213], v[60:63]
	v_mfma_f32_16x16x32_bf16 v[56:59], v[178:181], v[210:213], v[56:59]
	v_mfma_f32_16x16x32_bf16 v[44:47], v[170:173], v[218:221], v[44:47]
	v_mfma_f32_16x16x32_bf16 v[40:43], v[178:181], v[218:221], v[40:43]
	v_mfma_f32_16x16x32_bf16 v[28:31], v[170:173], v[226:229], v[28:31]
	v_mfma_f32_16x16x32_bf16 v[24:27], v[178:181], v[226:229], v[24:27]
	v_mfma_f32_16x16x32_bf16 v[12:15], v[170:173], v[234:237], v[12:15]
	v_mfma_f32_16x16x32_bf16 v[8:11], v[178:181], v[234:237], v[8:11]
	v_mfma_f32_16x16x32_bf16 v[52:55], v[182:185], v[206:209], v[52:55]
	v_mfma_f32_16x16x32_bf16 v[48:51], v[198:201], v[206:209], v[48:51]
	v_mfma_f32_16x16x32_bf16 v[36:39], v[182:185], v[214:217], v[36:39]
	v_mfma_f32_16x16x32_bf16 v[32:35], v[198:201], v[214:217], v[32:35]
	v_mfma_f32_16x16x32_bf16 v[20:23], v[182:185], v[222:225], v[20:23]
	v_mfma_f32_16x16x32_bf16 v[16:19], v[198:201], v[222:225], v[16:19]
	v_mfma_f32_16x16x32_bf16 v[4:7], v[182:185], v[230:233], v[4:7]
	v_mfma_f32_16x16x32_bf16 v[0:3], v[198:201], v[230:233], v[0:3]
	v_mfma_f32_16x16x32_bf16 v[52:55], v[186:189], v[210:213], v[52:55]
	v_mfma_f32_16x16x32_bf16 v[48:51], v[202:205], v[210:213], v[48:51]
	v_mfma_f32_16x16x32_bf16 v[36:39], v[186:189], v[218:221], v[36:39]
	v_mfma_f32_16x16x32_bf16 v[32:35], v[202:205], v[218:221], v[32:35]
	v_mfma_f32_16x16x32_bf16 v[20:23], v[186:189], v[226:229], v[20:23]
	v_mfma_f32_16x16x32_bf16 v[16:19], v[202:205], v[226:229], v[16:19]
	v_mfma_f32_16x16x32_bf16 v[4:7], v[186:189], v[234:237], v[4:7]
	v_mfma_f32_16x16x32_bf16 v[0:3], v[202:205], v[234:237], v[0:3]
	s_barrier
	s_add_i32 s72, s72, 2
	s_add_u32 s60, s60, 0x100
	s_addc_u32 s61, s61, 0
	s_add_u32 s69, s69, 0x100
	s_addc_u32 s33, s33, 0
	s_cmp_gt_u32 s72, 13
	s_cbranch_scc0 .LBB0_1698
	s_and_b64 vcc, exec, s[50:51]
	s_cbranch_vccz .LBB0_1701
	s_barrier

; #define PG8_STAGE(bufoff, gbase, voff) do { _Pragma("unroll") for (int _i = 0; _i < 2; ++_i) \
;         __builtin_amdgcn_global_load_lds((const unsigned*)((const char*)(gbase) + (voff)[_i]), (PG8_LAS unsigned*)(lds + (bufoff) + ldsw + _i * 8192), 16, 0, 0); } while (0)
; #define PG8_LDA(dst, b, h) do { _Pragma("unroll") for (int m = 0; m < 4; ++m) _Pragma("unroll") for (int k = 0; k < 2; ++k) dst[m][k] = *(const PG8_LAS bf16x8*)(lds + PG8_SA(b, h) + aoff + m * 2048 + k * 1024); } while (0)
; #define PG8_LDB(dst, b, h) do { _Pragma("unroll") for (int n = 0; n < 2; ++n) _Pragma("unroll") for (int k = 0; k < 2; ++k) dst[n][k] = *(const PG8_LAS bf16x8*)(lds + PG8_SB(b, h) + boff + n * 2048 + k * 1024); } while (0)
; #define PG8_MMA(ai, bj, At, Bt) do { __builtin_amdgcn_s_setprio(1); _Pragma("unroll") for (int m = 0; m < 4; ++m) _Pragma("unroll") for (int n = 0; n < 2; ++n) _Pragma("unroll") for (int k = 0; k < 2; ++k) \
;         acc[ai][bj][m][n] = __builtin_amdgcn_mfma_f32_16x16x32_bf16(Bt[n][k], At[m][k], acc[ai][bj][m][n], 0, 0, 0); __builtin_amdgcn_s_setprio(0); } while (0)
; #define PG8_WAIT_V(n) asm volatile("s_waitcnt vmcnt(" #n ")" ::: "memory")
; #define PG8_WAIT_L(n) asm volatile("s_waitcnt lgkmcnt(" #n ")" ::: "memory")
; #define PG8_BAR __builtin_amdgcn_s_barrier()
; #define PG8_SCHED __builtin_amdgcn_sched_barrier(0)
; template <class Epi, class Sched, bool ALIGN_EPI = false, bool SP2 = false>
; __device__ __forceinline__ void gemm_phase(PG8_LAS unsigned char* lds, const Gemm g, const Sched& S, const Epi& E) {
;     ...
;             const char* a1 = cA + (size_t)(t + 1) * kstep;
;             const char* a2 = last ? nA : cA + (size_t)(t + 2) * kstep; const char* b2 = last ? nB : cB + (size_t)(t + 2) * kstep;
;             const char* a3 = a2 + kstep; const char* b3 = b2 + kstep;
;     ...
;             PG8_LDB(B0, 0, 0); PG8_LDB(B1, 0, 1); PG8_SCHED; PG8_LDA(At, 0, 0); PG8_STAGE(PG8_SA(1, 1), a1 + hstep, voffA);
;             PG8_WAIT_V(8); PG8_WAIT_L(0); PG8_BAR; PG8_MMA(0, 0, At, B0); PG8_MMA(0, 1, At, B1); PG8_BAR; PG8_SCHED;
;             PG8_LDA(At, 0, 1); PG8_STAGE(PG8_SB(0, 0), b2, voffB); PG8_STAGE(PG8_SB(0, 1), b2 + hstep, voffB); PG8_STAGE(PG8_SA(0, 0), a2, voffA);
;             PG8_WAIT_V(8); PG8_WAIT_L(0); PG8_BAR; PG8_MMA(1, 0, At, B0); PG8_MMA(1, 1, At, B1); PG8_BAR; PG8_SCHED;
.LBB0_1822:
	ds_read_b128 v[144:147], v154
	ds_read_b128 v[168:171], v154 offset:1024
	ds_read_b128 v[172:175], v154 offset:2048
	ds_read_b128 v[176:179], v154 offset:3072
	ds_read_b128 v[180:183], v155
	ds_read_b128 v[184:187], v155 offset:1024
	ds_read_b128 v[188:191], v155 offset:2048
	ds_read_b128 v[198:201], v155 offset:3072
	s_add_u32 s6, s50, 0xfffc0080
	s_addc_u32 s7, s51, -1
	s_cmp_eq_u32 s72, 12
	s_cselect_b32 s55, s39, s7
	s_cselect_b32 s54, s69, s6
	s_cselect_b32 s53, s37, s33
	s_cselect_b32 s52, s74, s75
	s_add_i32 m0, s27, 0xc000
	ds_read_b128 v[202:205], v156
	ds_read_b128 v[206:209], v156 offset:1024
	ds_read_b128 v[210:213], v156 offset:2048
	ds_read_b128 v[214:217], v156 offset:3072
	ds_read_b128 v[218:221], v156 offset:4096
	ds_read_b128 v[222:225], v156 offset:5120
	ds_read_b128 v[226:229], v156 offset:6144
	global_load_lds_dwordx4 v136, s[50:51]
	s_add_i32 m0, s27, 0xe000
	ds_read_b128 v[230:233], v156 offset:7168
	global_load_lds_dwordx4 v138, s[50:51]
	s_waitcnt vmcnt(8)
	s_waitcnt lgkmcnt(0)
	s_barrier
	s_waitcnt lgkmcnt(0)
	v_mfma_f32_16x16x32_bf16 v[124:127], v[144:147], v[202:205], v[124:127]
	v_mfma_f32_16x16x32_bf16 v[116:119], v[172:175], v[202:205], v[116:119]
	v_mfma_f32_16x16x32_bf16 v[108:111], v[144:147], v[210:213], v[108:111]
	v_mfma_f32_16x16x32_bf16 v[100:103], v[172:175], v[210:213], v[100:103]
	v_mfma_f32_16x16x32_bf16 v[92:95], v[144:147], v[218:221], v[92:95]
	v_mfma_f32_16x16x32_bf16 v[84:87], v[172:175], v[218:221], v[84:87]
	v_mfma_f32_16x16x32_bf16 v[76:79], v[144:147], v[226:229], v[76:79]
	v_mfma_f32_16x16x32_bf16 v[68:71], v[172:175], v[226:229], v[68:71]
	v_mfma_f32_16x16x32_bf16 v[124:127], v[168:171], v[206:209], v[124:127]
	v_mfma_f32_16x16x32_bf16 v[116:119], v[176:179], v[206:209], v[116:119]
	v_mfma_f32_16x16x32_bf16 v[108:111], v[168:171], v[214:217], v[108:111]
	v_mfma_f32_16x16x32_bf16 v[100:103], v[176:179], v[214:217], v[100:103]
	v_mfma_f32_16x16x32_bf16 v[92:95], v[168:171], v[222:225], v[92:95]
	v_mfma_f32_16x16x32_bf16 v[84:87], v[176:179], v[222:225], v[84:87]
	v_mfma_f32_16x16x32_bf16 v[76:79], v[168:171], v[230:233], v[76:79]
	v_mfma_f32_16x16x32_bf16 v[68:71], v[176:179], v[230:233], v[68:71]
	v_mfma_f32_16x16x32_bf16 v[120:123], v[180:183], v[202:205], v[120:123]
	v_mfma_f32_16x16x32_bf16 v[112:115], v[188:191], v[202:205], v[112:115]
	v_mfma_f32_16x16x32_bf16 v[104:107], v[180:183], v[210:213], v[104:107]
	v_mfma_f32_16x16x32_bf16 v[96:99], v[188:191], v[210:213], v[96:99]
	v_mfma_f32_16x16x32_bf16 v[88:91], v[180:183], v[218:221], v[88:91]
	v_mfma_f32_16x16x32_bf16 v[80:83], v[188:191], v[218:221], v[80:83]
	v_mfma_f32_16x16x32_bf16 v[72:75], v[180:183], v[226:229], v[72:75]
	v_mfma_f32_16x16x32_bf16 v[64:67], v[188:191], v[226:229], v[64:67]
	v_mfma_f32_16x16x32_bf16 v[120:123], v[184:187], v[206:209], v[120:123]
	v_mfma_f32_16x16x32_bf16 v[112:115], v[198:201], v[206:209], v[112:115]
	v_mfma_f32_16x16x32_bf16 v[104:107], v[184:187], v[214:217], v[104:107]
	v_mfma_f32_16x16x32_bf16 v[96:99], v[198:201], v[214:217], v[96:99]
	v_mfma_f32_16x16x32_bf16 v[88:91], v[184:187], v[222:225], v[88:91]
	v_mfma_f32_16x16x32_bf16 v[80:83], v[198:201], v[222:225], v[80:83]
	v_mfma_f32_16x16x32_bf16 v[72:75], v[184:187], v[230:233], v[72:75]
	v_mfma_f32_16x16x32_bf16 v[64:67], v[198:201], v[230:233], v[64:67]
	s_barrier
	s_add_i32 s6, s59, s26
	s_mov_b32 m0, s6
	ds_read_b128 v[202:205], v156 offset:16384
	ds_read_b128 v[206:209], v156 offset:17408
	ds_read_b128 v[210:213], v156 offset:18432
	ds_read_b128 v[214:217], v156 offset:19456
	ds_read_b128 v[218:221], v156 offset:20480
	global_load_lds_dwordx4 v132, s[52:53]
	s_add_i32 m0, s6, 0x2000
	s_add_u32 s6, s52, 0x40000
	s_addc_u32 s7, s53, 0
	s_add_i32 s73, s60, s26
	global_load_lds_dwordx4 v128, s[52:53]
	s_mov_b32 m0, s73
	s_nop 0
	global_load_lds_dwordx4 v132, s[6:7]
	s_add_i32 m0, s73, 0x2000
	ds_read_b128 v[230:233], v156 offset:23552
	global_load_lds_dwordx4 v128, s[6:7]
	s_mov_b32 m0, s27
	ds_read_b128 v[226:229], v156 offset:22528
	global_load_lds_dwordx4 v134, s[54:55]
	s_mov_b32 m0, s42
	ds_read_b128 v[222:225], v156 offset:21504
	global_load_lds_dwordx4 v130, s[54:55]
	s_waitcnt vmcnt(8)
	s_waitcnt lgkmcnt(0)
	s_barrier
	s_waitcnt lgkmcnt(0)
	v_mfma_f32_16x16x32_bf16 v[60:63], v[144:147], v[202:205], v[60:63]
	v_mfma_f32_16x16x32_bf16 v[52:55], v[172:175], v[202:205], v[52:55]
	v_mfma_f32_16x16x32_bf16 v[44:47], v[144:147], v[210:213], v[44:47]
	v_mfma_f32_16x16x32_bf16 v[36:39], v[172:175], v[210:213], v[36:39]
	v_mfma_f32_16x16x32_bf16 v[28:31], v[144:147], v[218:221], v[28:31]
	v_mfma_f32_16x16x32_bf16 v[20:23], v[172:175], v[218:221], v[20:23]
	v_mfma_f32_16x16x32_bf16 v[12:15], v[144:147], v[226:229], v[12:15]
	v_mfma_f32_16x16x32_bf16 v[4:7], v[172:175], v[226:229], v[4:7]
	v_mfma_f32_16x16x32_bf16 v[60:63], v[168:171], v[206:209], v[60:63]
	v_mfma_f32_16x16x32_bf16 v[52:55], v[176:179], v[206:209], v[52:55]
	v_mfma_f32_16x16x32_bf16 v[44:47], v[168:171], v[214:217], v[44:47]
	v_mfma_f32_16x16x32_bf16 v[36:39], v[176:179], v[214:217], v[36:39]
	v_mfma_f32_16x16x32_bf16 v[28:31], v[168:171], v[222:225], v[28:31]
	v_mfma_f32_16x16x32_bf16 v[20:23], v[176:179], v[222:225], v[20:23]
	v_mfma_f32_16x16x32_bf16 v[12:15], v[168:171], v[230:233], v[12:15]
	v_mfma_f32_16x16x32_bf16 v[4:7], v[176:179], v[230:233], v[4:7]
	v_mfma_f32_16x16x32_bf16 v[56:59], v[180:183], v[202:205], v[56:59]
	v_mfma_f32_16x16x32_bf16 v[48:51], v[188:191], v[202:205], v[48:51]
	v_mfma_f32_16x16x32_bf16 v[40:43], v[180:183], v[210:213], v[40:43]
	v_mfma_f32_16x16x32_bf16 v[32:35], v[188:191], v[210:213], v[32:35]
	v_mfma_f32_16x16x32_bf16 v[24:27], v[180:183], v[218:221], v[24:27]
	v_mfma_f32_16x16x32_bf16 v[16:19], v[188:191], v[218:221], v[16:19]
	v_mfma_f32_16x16x32_bf16 v[8:11], v[180:183], v[226:229], v[8:11]
	v_mfma_f32_16x16x32_bf16 v[0:3], v[188:191], v[226:229], v[0:3]
	v_mfma_f32_16x16x32_bf16 v[56:59], v[184:187], v[206:209], v[56:59]
	v_mfma_f32_16x16x32_bf16 v[48:51], v[198:201], v[206:209], v[48:51]
	v_mfma_f32_16x16x32_bf16 v[40:43], v[184:187], v[214:217], v[40:43]
	v_mfma_f32_16x16x32_bf16 v[32:35], v[198:201], v[214:217], v[32:35]
	v_mfma_f32_16x16x32_bf16 v[24:27], v[184:187], v[222:225], v[24:27]
	v_mfma_f32_16x16x32_bf16 v[16:19], v[198:201], v[222:225], v[16:19]
	v_mfma_f32_16x16x32_bf16 v[8:11], v[184:187], v[230:233], v[8:11]
	v_mfma_f32_16x16x32_bf16 v[0:3], v[198:201], v[230:233], v[0:3]
	s_barrier
; #define PG8_STAGE(bufoff, gbase, voff) do { _Pragma("unroll") for (int _i = 0; _i < 2; ++_i) \
;         __builtin_amdgcn_global_load_lds((const unsigned*)((const char*)(gbase) + (voff)[_i]), (PG8_LAS unsigned*)(lds + (bufoff) + ldsw + _i * 8192), 16, 0, 0); } while (0)
; #define PG8_LDA(dst, b, h) do { _Pragma("unroll") for (int m = 0; m < 4; ++m) _Pragma("unroll") for (int k = 0; k < 2; ++k) dst[m][k] = *(const PG8_LAS bf16x8*)(lds + PG8_SA(b, h) + aoff + m * 2048 + k * 1024); } while (0)
; #define PG8_LDB(dst, b, h) do { _Pragma("unroll") for (int n = 0; n < 2; ++n) _Pragma("unroll") for (int k = 0; k < 2; ++k) dst[n][k] = *(const PG8_LAS bf16x8*)(lds + PG8_SB(b, h) + boff + n * 2048 + k * 1024); } while (0)
; #define PG8_MMA(ai, bj, At, Bt) do { __builtin_amdgcn_s_setprio(1); _Pragma("unroll") for (int m = 0; m < 4; ++m) _Pragma("unroll") for (int n = 0; n < 2; ++n) _Pragma("unroll") for (int k = 0; k < 2; ++k) \
;         acc[ai][bj][m][n] = __builtin_amdgcn_mfma_f32_16x16x32_bf16(Bt[n][k], At[m][k], acc[ai][bj][m][n], 0, 0, 0); __builtin_amdgcn_s_setprio(0); } while (0)
; #define PG8_WAIT_V(n) asm volatile("s_waitcnt vmcnt(" #n ")" ::: "memory")
; #define PG8_WAIT_L(n) asm volatile("s_waitcnt lgkmcnt(" #n ")" ::: "memory")
; #define PG8_BAR __builtin_amdgcn_s_barrier()
; #define PG8_SCHED __builtin_amdgcn_sched_barrier(0)
; template <class Epi, class Sched, bool ALIGN_EPI = false, bool SP2 = false>
; __device__ __forceinline__ void gemm_phase(PG8_LAS unsigned char* lds, const Gemm g, const Sched& S, const Epi& E) {
;     ...
;             PG8_LDB(B0, 1, 0); PG8_LDB(B1, 1, 1); PG8_SCHED; PG8_LDA(At, 1, 0); PG8_STAGE(PG8_SA(0, 1), a2 + hstep, voffA);
;             PG8_WAIT_V(8); PG8_WAIT_L(0); PG8_BAR; PG8_MMA(0, 0, At, B0); PG8_MMA(0, 1, At, B1); PG8_BAR; PG8_SCHED;
;             PG8_LDA(At, 1, 1); PG8_STAGE(PG8_SB(1, 0), b3, voffB); PG8_STAGE(PG8_SB(1, 1), b3 + hstep, voffB); PG8_STAGE(PG8_SA(1, 0), a3, voffA);
;             PG8_WAIT_V(8); PG8_WAIT_L(0); PG8_BAR; PG8_MMA(1, 0, At, B0); PG8_MMA(1, 1, At, B1); PG8_BAR; PG8_SCHED;
	s_add_i32 s73, 0, 0x18000
	v_add_u32_e32 v157, s73, v151
	s_add_i32 s76, 0, 0x1c000
	ds_read_b128 v[144:147], v157
	ds_read_b128 v[168:171], v157 offset:1024
	ds_read_b128 v[172:175], v157 offset:2048
	ds_read_b128 v[176:179], v157 offset:3072
	v_add_u32_e32 v157, s76, v151
	ds_read_b128 v[180:183], v157
	ds_read_b128 v[184:187], v157 offset:1024
	ds_read_b128 v[188:191], v157 offset:2048
	ds_read_b128 v[198:201], v157 offset:3072
	s_add_u32 s6, s54, 0x40000
	s_addc_u32 s7, s55, 0
	s_mov_b32 m0, s43
	ds_read_b128 v[202:205], v156 offset:32768
	ds_read_b128 v[206:209], v156 offset:33792
	ds_read_b128 v[210:213], v156 offset:34816
	ds_read_b128 v[214:217], v156 offset:35840
	ds_read_b128 v[218:221], v156 offset:36864
	ds_read_b128 v[222:225], v156 offset:37888
	ds_read_b128 v[226:229], v156 offset:38912
	global_load_lds_dwordx4 v134, s[6:7]
	s_mov_b32 m0, s56
	ds_read_b128 v[230:233], v156 offset:39936
	global_load_lds_dwordx4 v130, s[6:7]
	s_waitcnt vmcnt(8)
	s_waitcnt lgkmcnt(0)
	s_barrier
	s_waitcnt lgkmcnt(0)
	v_mfma_f32_16x16x32_bf16 v[124:127], v[144:147], v[202:205], v[124:127]
	v_mfma_f32_16x16x32_bf16 v[116:119], v[172:175], v[202:205], v[116:119]
	v_mfma_f32_16x16x32_bf16 v[108:111], v[144:147], v[210:213], v[108:111]
	v_mfma_f32_16x16x32_bf16 v[100:103], v[172:175], v[210:213], v[100:103]
	v_mfma_f32_16x16x32_bf16 v[92:95], v[144:147], v[218:221], v[92:95]
	v_mfma_f32_16x16x32_bf16 v[84:87], v[172:175], v[218:221], v[84:87]
	v_mfma_f32_16x16x32_bf16 v[76:79], v[144:147], v[226:229], v[76:79]
	v_mfma_f32_16x16x32_bf16 v[68:71], v[172:175], v[226:229], v[68:71]
	v_mfma_f32_16x16x32_bf16 v[124:127], v[168:171], v[206:209], v[124:127]
	v_mfma_f32_16x16x32_bf16 v[116:119], v[176:179], v[206:209], v[116:119]
	v_mfma_f32_16x16x32_bf16 v[108:111], v[168:171], v[214:217], v[108:111]
	v_mfma_f32_16x16x32_bf16 v[100:103], v[176:179], v[214:217], v[100:103]
	v_mfma_f32_16x16x32_bf16 v[92:95], v[168:171], v[222:225], v[92:95]
	v_mfma_f32_16x16x32_bf16 v[84:87], v[176:179], v[222:225], v[84:87]
	v_mfma_f32_16x16x32_bf16 v[76:79], v[168:171], v[230:233], v[76:79]
	v_mfma_f32_16x16x32_bf16 v[68:71], v[176:179], v[230:233], v[68:71]
	v_mfma_f32_16x16x32_bf16 v[120:123], v[180:183], v[202:205], v[120:123]
	v_mfma_f32_16x16x32_bf16 v[112:115], v[188:191], v[202:205], v[112:115]
	v_mfma_f32_16x16x32_bf16 v[104:107], v[180:183], v[210:213], v[104:107]
	v_mfma_f32_16x16x32_bf16 v[96:99], v[188:191], v[210:213], v[96:99]
	v_mfma_f32_16x16x32_bf16 v[88:91], v[180:183], v[218:221], v[88:91]
	v_mfma_f32_16x16x32_bf16 v[80:83], v[188:191], v[218:221], v[80:83]
	v_mfma_f32_16x16x32_bf16 v[72:75], v[180:183], v[226:229], v[72:75]
	v_mfma_f32_16x16x32_bf16 v[64:67], v[188:191], v[226:229], v[64:67]
	v_mfma_f32_16x16x32_bf16 v[120:123], v[184:187], v[206:209], v[120:123]
	v_mfma_f32_16x16x32_bf16 v[112:115], v[198:201], v[206:209], v[112:115]
	v_mfma_f32_16x16x32_bf16 v[104:107], v[184:187], v[214:217], v[104:107]
	v_mfma_f32_16x16x32_bf16 v[96:99], v[198:201], v[214:217], v[96:99]
	v_mfma_f32_16x16x32_bf16 v[88:91], v[184:187], v[222:225], v[88:91]
	v_mfma_f32_16x16x32_bf16 v[80:83], v[198:201], v[222:225], v[80:83]
	v_mfma_f32_16x16x32_bf16 v[72:75], v[184:187], v[230:233], v[72:75]
	v_mfma_f32_16x16x32_bf16 v[64:67], v[198:201], v[230:233], v[64:67]
	s_barrier
	s_add_i32 s6, s73, s26
	s_add_u32 s98, s52, 0x80
	s_addc_u32 s99, s53, 0
	s_add_u32 s100, s54, 0x80
	s_addc_u32 s101, s55, 0
	s_mov_b32 m0, s6
	ds_read_b128 v[202:205], v156 offset:49152
	ds_read_b128 v[206:209], v156 offset:50176
	ds_read_b128 v[210:213], v156 offset:51200
	ds_read_b128 v[214:217], v156 offset:52224
	global_load_lds_dwordx4 v132, s[98:99]
	s_add_i32 m0, s6, 0x2000
	s_add_u32 s6, s52, 0x40080
	s_addc_u32 s7, s53, 0
	s_add_i32 s52, s76, s26
	global_load_lds_dwordx4 v128, s[98:99]
	s_mov_b32 m0, s52
	ds_read_b128 v[230:233], v156 offset:56320
	global_load_lds_dwordx4 v132, s[6:7]
	s_add_i32 m0, s52, 0x2000
	ds_read_b128 v[226:229], v156 offset:55296
	global_load_lds_dwordx4 v128, s[6:7]
	s_mov_b32 m0, s57
	ds_read_b128 v[222:225], v156 offset:54272
	global_load_lds_dwordx4 v134, s[100:101]
	s_mov_b32 m0, s58
	ds_read_b128 v[218:221], v156 offset:53248
	global_load_lds_dwordx4 v130, s[100:101]
	s_waitcnt vmcnt(8)
	s_waitcnt lgkmcnt(0)
	s_barrier
	s_waitcnt lgkmcnt(0)
	v_mfma_f32_16x16x32_bf16 v[60:63], v[144:147], v[202:205], v[60:63]
	v_mfma_f32_16x16x32_bf16 v[52:55], v[172:175], v[202:205], v[52:55]
	v_mfma_f32_16x16x32_bf16 v[44:47], v[144:147], v[210:213], v[44:47]
	v_mfma_f32_16x16x32_bf16 v[36:39], v[172:175], v[210:213], v[36:39]
	v_mfma_f32_16x16x32_bf16 v[28:31], v[144:147], v[218:221], v[28:31]
	v_mfma_f32_16x16x32_bf16 v[20:23], v[172:175], v[218:221], v[20:23]
	v_mfma_f32_16x16x32_bf16 v[12:15], v[144:147], v[226:229], v[12:15]
	v_mfma_f32_16x16x32_bf16 v[4:7], v[172:175], v[226:229], v[4:7]
	v_mfma_f32_16x16x32_bf16 v[60:63], v[168:171], v[206:209], v[60:63]
	v_mfma_f32_16x16x32_bf16 v[52:55], v[176:179], v[206:209], v[52:55]
	v_mfma_f32_16x16x32_bf16 v[44:47], v[168:171], v[214:217], v[44:47]
	v_mfma_f32_16x16x32_bf16 v[36:39], v[176:179], v[214:217], v[36:39]
	v_mfma_f32_16x16x32_bf16 v[28:31], v[168:171], v[222:225], v[28:31]
	v_mfma_f32_16x16x32_bf16 v[20:23], v[176:179], v[222:225], v[20:23]
	v_mfma_f32_16x16x32_bf16 v[12:15], v[168:171], v[230:233], v[12:15]
	v_mfma_f32_16x16x32_bf16 v[4:7], v[176:179], v[230:233], v[4:7]
	v_mfma_f32_16x16x32_bf16 v[56:59], v[180:183], v[202:205], v[56:59]
	v_mfma_f32_16x16x32_bf16 v[48:51], v[188:191], v[202:205], v[48:51]
	v_mfma_f32_16x16x32_bf16 v[40:43], v[180:183], v[210:213], v[40:43]
	v_mfma_f32_16x16x32_bf16 v[32:35], v[188:191], v[210:213], v[32:35]
	v_mfma_f32_16x16x32_bf16 v[24:27], v[180:183], v[218:221], v[24:27]
	v_mfma_f32_16x16x32_bf16 v[16:19], v[188:191], v[218:221], v[16:19]
	v_mfma_f32_16x16x32_bf16 v[8:11], v[180:183], v[226:229], v[8:11]
	v_mfma_f32_16x16x32_bf16 v[0:3], v[188:191], v[226:229], v[0:3]
	v_mfma_f32_16x16x32_bf16 v[56:59], v[184:187], v[206:209], v[56:59]
	v_mfma_f32_16x16x32_bf16 v[48:51], v[198:201], v[206:209], v[48:51]
	v_mfma_f32_16x16x32_bf16 v[40:43], v[184:187], v[214:217], v[40:43]
	v_mfma_f32_16x16x32_bf16 v[32:35], v[198:201], v[214:217], v[32:35]
	v_mfma_f32_16x16x32_bf16 v[24:27], v[184:187], v[222:225], v[24:27]
	v_mfma_f32_16x16x32_bf16 v[16:19], v[198:201], v[222:225], v[16:19]
	v_mfma_f32_16x16x32_bf16 v[8:11], v[184:187], v[230:233], v[8:11]
	v_mfma_f32_16x16x32_bf16 v[0:3], v[198:201], v[230:233], v[0:3]
	s_barrier
	s_add_i32 s72, s72, 2
	s_add_u32 s50, s50, 0x100
	s_addc_u32 s51, s51, 0
	s_add_u32 s75, s75, 0x100
	s_addc_u32 s33, s33, 0
	s_cmp_gt_u32 s72, 13
	s_cbranch_scc0 .LBB0_1822
	v_readlane_b32 s74, v243, 57
	s_and_b64 vcc, exec, s[34:35]
	v_readlane_b32 s75, v243, 58
	s_cbranch_vccz .LBB0_1825
	s_barrier

; #define PG8_STAGE(bufoff, gbase, voff) do { _Pragma("unroll") for (int _i = 0; _i < 2; ++_i) \
;         __builtin_amdgcn_global_load_lds((const unsigned*)((const char*)(gbase) + (voff)[_i]), (PG8_LAS unsigned*)(lds + (bufoff) + ldsw + _i * 8192), 16, 0, 0); } while (0)
; #define PG8_LDA(dst, b, h) do { _Pragma("unroll") for (int m = 0; m < 4; ++m) _Pragma("unroll") for (int k = 0; k < 2; ++k) dst[m][k] = *(const PG8_LAS bf16x8*)(lds + PG8_SA(b, h) + aoff + m * 2048 + k * 1024); } while (0)
; #define PG8_LDB(dst, b, h) do { _Pragma("unroll") for (int n = 0; n < 2; ++n) _Pragma("unroll") for (int k = 0; k < 2; ++k) dst[n][k] = *(const PG8_LAS bf16x8*)(lds + PG8_SB(b, h) + boff + n * 2048 + k * 1024); } while (0)
; #define PG8_MMA(ai, bj, At, Bt) do { __builtin_amdgcn_s_setprio(1); _Pragma("unroll") for (int m = 0; m < 4; ++m) _Pragma("unroll") for (int n = 0; n < 2; ++n) _Pragma("unroll") for (int k = 0; k < 2; ++k) \
;         acc[ai][bj][m][n] = __builtin_amdgcn_mfma_f32_16x16x32_bf16(Bt[n][k], At[m][k], acc[ai][bj][m][n], 0, 0, 0); __builtin_amdgcn_s_setprio(0); } while (0)
; #define PG8_WAIT_V(n) asm volatile("s_waitcnt vmcnt(" #n ")" ::: "memory")
; #define PG8_WAIT_L(n) asm volatile("s_waitcnt lgkmcnt(" #n ")" ::: "memory")
; #define PG8_BAR __builtin_amdgcn_s_barrier()
; #define PG8_SCHED __builtin_amdgcn_sched_barrier(0)
; template <class Epi, class Sched, bool ALIGN_EPI = false, bool SP2 = false>
; __device__ __forceinline__ void gemm_phase(PG8_LAS unsigned char* lds, const Gemm g, const Sched& S, const Epi& E) {
;     ...
;             const char* a1 = cA + (size_t)(t + 1) * kstep;
;             const char* a2 = last ? nA : cA + (size_t)(t + 2) * kstep; const char* b2 = last ? nB : cB + (size_t)(t + 2) * kstep;
;             const char* a3 = a2 + kstep; const char* b3 = b2 + kstep;
;     ...
;             PG8_LDB(B0, 0, 0); PG8_LDB(B1, 0, 1); PG8_SCHED; PG8_LDA(At, 0, 0); PG8_STAGE(PG8_SA(1, 1), a1 + hstep, voffA);
;             PG8_WAIT_V(8); PG8_WAIT_L(0); PG8_BAR; PG8_MMA(0, 0, At, B0); PG8_MMA(0, 1, At, B1); PG8_BAR; PG8_SCHED;
;             PG8_LDA(At, 0, 1); PG8_STAGE(PG8_SB(0, 0), b2, voffB); PG8_STAGE(PG8_SB(0, 1), b2 + hstep, voffB); PG8_STAGE(PG8_SA(0, 0), a2, voffA);
;             PG8_WAIT_V(8); PG8_WAIT_L(0); PG8_BAR; PG8_MMA(1, 0, At, B0); PG8_MMA(1, 1, At, B1); PG8_BAR; PG8_SCHED;
.LBB0_1935:
	ds_read_b128 v[144:147], v153
	ds_read_b128 v[168:171], v153 offset:1024
	ds_read_b128 v[172:175], v153 offset:2048
	ds_read_b128 v[176:179], v153 offset:3072
	ds_read_b128 v[180:183], v154
	ds_read_b128 v[184:187], v154 offset:1024
	ds_read_b128 v[188:191], v154 offset:2048
	ds_read_b128 v[198:201], v154 offset:3072
	s_add_u32 s50, s48, 0x100
	s_addc_u32 s51, s49, 0
	s_cmp_eq_u32 s72, 40
	s_cselect_b32 s55, s41, s51
	s_cselect_b32 s54, s40, s50
	s_cselect_b32 s53, s47, s77
	s_cselect_b32 s52, s46, s33
	s_add_i32 m0, s58, 0xc000
	ds_read_b128 v[202:205], v155
	ds_read_b128 v[206:209], v155 offset:1024
	ds_read_b128 v[210:213], v155 offset:2048
	ds_read_b128 v[214:217], v155 offset:3072
	ds_read_b128 v[218:221], v155 offset:4096
	ds_read_b128 v[222:225], v155 offset:5120
	ds_read_b128 v[226:229], v155 offset:6144
	global_load_lds_dwordx4 v136, s[48:49]
	s_add_i32 m0, s58, 0xe000
	ds_read_b128 v[230:233], v155 offset:7168
	global_load_lds_dwordx4 v138, s[48:49]
	s_waitcnt vmcnt(8)
	s_waitcnt lgkmcnt(0)
	s_barrier
	s_waitcnt lgkmcnt(0)
	v_mfma_f32_16x16x32_bf16 v[124:127], v[144:147], v[202:205], v[124:127]
	v_mfma_f32_16x16x32_bf16 v[120:123], v[172:175], v[202:205], v[120:123]
	v_mfma_f32_16x16x32_bf16 v[108:111], v[144:147], v[210:213], v[108:111]
	v_mfma_f32_16x16x32_bf16 v[104:107], v[172:175], v[210:213], v[104:107]
	v_mfma_f32_16x16x32_bf16 v[92:95], v[144:147], v[218:221], v[92:95]
	v_mfma_f32_16x16x32_bf16 v[88:91], v[172:175], v[218:221], v[88:91]
	v_mfma_f32_16x16x32_bf16 v[76:79], v[144:147], v[226:229], v[76:79]
	v_mfma_f32_16x16x32_bf16 v[72:75], v[172:175], v[226:229], v[72:75]
	v_mfma_f32_16x16x32_bf16 v[124:127], v[168:171], v[206:209], v[124:127]
	v_mfma_f32_16x16x32_bf16 v[120:123], v[176:179], v[206:209], v[120:123]
	v_mfma_f32_16x16x32_bf16 v[108:111], v[168:171], v[214:217], v[108:111]
	v_mfma_f32_16x16x32_bf16 v[104:107], v[176:179], v[214:217], v[104:107]
	v_mfma_f32_16x16x32_bf16 v[92:95], v[168:171], v[222:225], v[92:95]
	v_mfma_f32_16x16x32_bf16 v[88:91], v[176:179], v[222:225], v[88:91]
	v_mfma_f32_16x16x32_bf16 v[76:79], v[168:171], v[230:233], v[76:79]
	v_mfma_f32_16x16x32_bf16 v[72:75], v[176:179], v[230:233], v[72:75]
	v_mfma_f32_16x16x32_bf16 v[116:119], v[180:183], v[202:205], v[116:119]
	v_mfma_f32_16x16x32_bf16 v[112:115], v[188:191], v[202:205], v[112:115]
	v_mfma_f32_16x16x32_bf16 v[100:103], v[180:183], v[210:213], v[100:103]
	v_mfma_f32_16x16x32_bf16 v[96:99], v[188:191], v[210:213], v[96:99]
	v_mfma_f32_16x16x32_bf16 v[84:87], v[180:183], v[218:221], v[84:87]
	v_mfma_f32_16x16x32_bf16 v[80:83], v[188:191], v[218:221], v[80:83]
	v_mfma_f32_16x16x32_bf16 v[68:71], v[180:183], v[226:229], v[68:71]
	v_mfma_f32_16x16x32_bf16 v[64:67], v[188:191], v[226:229], v[64:67]
	v_mfma_f32_16x16x32_bf16 v[116:119], v[184:187], v[206:209], v[116:119]
	v_mfma_f32_16x16x32_bf16 v[112:115], v[198:201], v[206:209], v[112:115]
	v_mfma_f32_16x16x32_bf16 v[100:103], v[184:187], v[214:217], v[100:103]
	v_mfma_f32_16x16x32_bf16 v[96:99], v[198:201], v[214:217], v[96:99]
	v_mfma_f32_16x16x32_bf16 v[84:87], v[184:187], v[222:225], v[84:87]
	v_mfma_f32_16x16x32_bf16 v[80:83], v[198:201], v[222:225], v[80:83]
	v_mfma_f32_16x16x32_bf16 v[68:71], v[184:187], v[230:233], v[68:71]
	v_mfma_f32_16x16x32_bf16 v[64:67], v[198:201], v[230:233], v[64:67]
	s_barrier
	s_add_i32 s6, s26, s57
	s_mov_b32 m0, s6
	ds_read_b128 v[202:205], v155 offset:16384
	ds_read_b128 v[206:209], v155 offset:17408
	ds_read_b128 v[210:213], v155 offset:18432
	ds_read_b128 v[214:217], v155 offset:19456
	ds_read_b128 v[218:221], v155 offset:20480
	global_load_lds_dwordx4 v130, s[52:53]
	s_add_i32 m0, s6, 0x2000
	s_add_u32 s6, s52, 0xb0000
	s_addc_u32 s7, s53, 0
	s_add_i32 s48, s74, s57
	global_load_lds_dwordx4 v134, s[52:53]
	s_mov_b32 m0, s48
	s_nop 0
	global_load_lds_dwordx4 v130, s[6:7]
	s_add_i32 m0, s48, 0x2000
	ds_read_b128 v[230:233], v155 offset:23552
	global_load_lds_dwordx4 v134, s[6:7]
	s_mov_b32 m0, s58
	ds_read_b128 v[226:229], v155 offset:22528
	global_load_lds_dwordx4 v128, s[54:55]
	s_mov_b32 m0, s59
	ds_read_b128 v[222:225], v155 offset:21504
	global_load_lds_dwordx4 v132, s[54:55]
	s_waitcnt vmcnt(8)
	s_waitcnt lgkmcnt(0)
	s_barrier
	s_waitcnt lgkmcnt(0)
	v_mfma_f32_16x16x32_bf16 v[60:63], v[144:147], v[202:205], v[60:63]
	v_mfma_f32_16x16x32_bf16 v[56:59], v[172:175], v[202:205], v[56:59]
	v_mfma_f32_16x16x32_bf16 v[44:47], v[144:147], v[210:213], v[44:47]
	v_mfma_f32_16x16x32_bf16 v[40:43], v[172:175], v[210:213], v[40:43]
	v_mfma_f32_16x16x32_bf16 v[28:31], v[144:147], v[218:221], v[28:31]
	v_mfma_f32_16x16x32_bf16 v[24:27], v[172:175], v[218:221], v[24:27]
	v_mfma_f32_16x16x32_bf16 v[12:15], v[144:147], v[226:229], v[12:15]
	v_mfma_f32_16x16x32_bf16 v[8:11], v[172:175], v[226:229], v[8:11]
	v_mfma_f32_16x16x32_bf16 v[60:63], v[168:171], v[206:209], v[60:63]
	v_mfma_f32_16x16x32_bf16 v[56:59], v[176:179], v[206:209], v[56:59]
	v_mfma_f32_16x16x32_bf16 v[44:47], v[168:171], v[214:217], v[44:47]
	v_mfma_f32_16x16x32_bf16 v[40:43], v[176:179], v[214:217], v[40:43]
	v_mfma_f32_16x16x32_bf16 v[28:31], v[168:171], v[222:225], v[28:31]
	v_mfma_f32_16x16x32_bf16 v[24:27], v[176:179], v[222:225], v[24:27]
	v_mfma_f32_16x16x32_bf16 v[12:15], v[168:171], v[230:233], v[12:15]
	v_mfma_f32_16x16x32_bf16 v[8:11], v[176:179], v[230:233], v[8:11]
	v_mfma_f32_16x16x32_bf16 v[52:55], v[180:183], v[202:205], v[52:55]
	v_mfma_f32_16x16x32_bf16 v[48:51], v[188:191], v[202:205], v[48:51]
	v_mfma_f32_16x16x32_bf16 v[36:39], v[180:183], v[210:213], v[36:39]
	v_mfma_f32_16x16x32_bf16 v[32:35], v[188:191], v[210:213], v[32:35]
	v_mfma_f32_16x16x32_bf16 v[20:23], v[180:183], v[218:221], v[20:23]
	v_mfma_f32_16x16x32_bf16 v[16:19], v[188:191], v[218:221], v[16:19]
	v_mfma_f32_16x16x32_bf16 v[4:7], v[180:183], v[226:229], v[4:7]
	v_mfma_f32_16x16x32_bf16 v[0:3], v[188:191], v[226:229], v[0:3]
	v_mfma_f32_16x16x32_bf16 v[52:55], v[184:187], v[206:209], v[52:55]
	v_mfma_f32_16x16x32_bf16 v[48:51], v[198:201], v[206:209], v[48:51]
	v_mfma_f32_16x16x32_bf16 v[36:39], v[184:187], v[214:217], v[36:39]
	v_mfma_f32_16x16x32_bf16 v[32:35], v[198:201], v[214:217], v[32:35]
	v_mfma_f32_16x16x32_bf16 v[20:23], v[184:187], v[222:225], v[20:23]
	v_mfma_f32_16x16x32_bf16 v[16:19], v[198:201], v[222:225], v[16:19]
	v_mfma_f32_16x16x32_bf16 v[4:7], v[184:187], v[230:233], v[4:7]
	v_mfma_f32_16x16x32_bf16 v[0:3], v[198:201], v[230:233], v[0:3]
	s_barrier
; #define PG8_STAGE(bufoff, gbase, voff) do { _Pragma("unroll") for (int _i = 0; _i < 2; ++_i) \
;         __builtin_amdgcn_global_load_lds((const unsigned*)((const char*)(gbase) + (voff)[_i]), (PG8_LAS unsigned*)(lds + (bufoff) + ldsw + _i * 8192), 16, 0, 0); } while (0)
; #define PG8_LDA(dst, b, h) do { _Pragma("unroll") for (int m = 0; m < 4; ++m) _Pragma("unroll") for (int k = 0; k < 2; ++k) dst[m][k] = *(const PG8_LAS bf16x8*)(lds + PG8_SA(b, h) + aoff + m * 2048 + k * 1024); } while (0)
; #define PG8_LDB(dst, b, h) do { _Pragma("unroll") for (int n = 0; n < 2; ++n) _Pragma("unroll") for (int k = 0; k < 2; ++k) dst[n][k] = *(const PG8_LAS bf16x8*)(lds + PG8_SB(b, h) + boff + n * 2048 + k * 1024); } while (0)
; #define PG8_MMA(ai, bj, At, Bt) do { __builtin_amdgcn_s_setprio(1); _Pragma("unroll") for (int m = 0; m < 4; ++m) _Pragma("unroll") for (int n = 0; n < 2; ++n) _Pragma("unroll") for (int k = 0; k < 2; ++k) \
;         acc[ai][bj][m][n] = __builtin_amdgcn_mfma_f32_16x16x32_bf16(Bt[n][k], At[m][k], acc[ai][bj][m][n], 0, 0, 0); __builtin_amdgcn_s_setprio(0); } while (0)
; #define PG8_WAIT_V(n) asm volatile("s_waitcnt vmcnt(" #n ")" ::: "memory")
; #define PG8_WAIT_L(n) asm volatile("s_waitcnt lgkmcnt(" #n ")" ::: "memory")
; #define PG8_BAR __builtin_amdgcn_s_barrier()
; #define PG8_SCHED __builtin_amdgcn_sched_barrier(0)
; template <class Epi, class Sched, bool ALIGN_EPI = false, bool SP2 = false>
; __device__ __forceinline__ void gemm_phase(PG8_LAS unsigned char* lds, const Gemm g, const Sched& S, const Epi& E) {
;     ...
;             PG8_LDB(B0, 1, 0); PG8_LDB(B1, 1, 1); PG8_SCHED; PG8_LDA(At, 1, 0); PG8_STAGE(PG8_SA(0, 1), a2 + hstep, voffA);
;             PG8_WAIT_V(8); PG8_WAIT_L(0); PG8_BAR; PG8_MMA(0, 0, At, B0); PG8_MMA(0, 1, At, B1); PG8_BAR; PG8_SCHED;
;             PG8_LDA(At, 1, 1); PG8_STAGE(PG8_SB(1, 0), b3, voffB); PG8_STAGE(PG8_SB(1, 1), b3 + hstep, voffB); PG8_STAGE(PG8_SA(1, 0), a3, voffA);
;             PG8_WAIT_V(8); PG8_WAIT_L(0); PG8_BAR; PG8_MMA(1, 0, At, B0); PG8_MMA(1, 1, At, B1); PG8_BAR; PG8_SCHED;
	s_add_i32 s48, 0, 0x18000
	v_add_u32_e32 v157, s48, v151
	s_add_i32 s49, 0, 0x1c000
	ds_read_b128 v[144:147], v157
	ds_read_b128 v[168:171], v157 offset:1024
	ds_read_b128 v[172:175], v157 offset:2048
	ds_read_b128 v[176:179], v157 offset:3072
	v_add_u32_e32 v157, s49, v151
	ds_read_b128 v[180:183], v157
	ds_read_b128 v[184:187], v157 offset:1024
	ds_read_b128 v[188:191], v157 offset:2048
	ds_read_b128 v[198:201], v157 offset:3072
	s_add_u32 s6, s54, 0xb0000
	s_addc_u32 s7, s55, 0
	s_mov_b32 m0, s60
	ds_read_b128 v[202:205], v155 offset:32768
	ds_read_b128 v[206:209], v155 offset:33792
	ds_read_b128 v[210:213], v155 offset:34816
	ds_read_b128 v[214:217], v155 offset:35840
	ds_read_b128 v[218:221], v155 offset:36864
	ds_read_b128 v[222:225], v155 offset:37888
	ds_read_b128 v[226:229], v155 offset:38912
	global_load_lds_dwordx4 v128, s[6:7]
	s_mov_b32 m0, s61
	ds_read_b128 v[230:233], v155 offset:39936
	global_load_lds_dwordx4 v132, s[6:7]
	s_waitcnt vmcnt(8)
	s_waitcnt lgkmcnt(0)
	s_barrier
	s_waitcnt lgkmcnt(0)
	v_mfma_f32_16x16x32_bf16 v[124:127], v[144:147], v[202:205], v[124:127]
	v_mfma_f32_16x16x32_bf16 v[120:123], v[172:175], v[202:205], v[120:123]
	v_mfma_f32_16x16x32_bf16 v[108:111], v[144:147], v[210:213], v[108:111]
	v_mfma_f32_16x16x32_bf16 v[104:107], v[172:175], v[210:213], v[104:107]
	v_mfma_f32_16x16x32_bf16 v[92:95], v[144:147], v[218:221], v[92:95]
	v_mfma_f32_16x16x32_bf16 v[88:91], v[172:175], v[218:221], v[88:91]
	v_mfma_f32_16x16x32_bf16 v[76:79], v[144:147], v[226:229], v[76:79]
	v_mfma_f32_16x16x32_bf16 v[72:75], v[172:175], v[226:229], v[72:75]
	v_mfma_f32_16x16x32_bf16 v[124:127], v[168:171], v[206:209], v[124:127]
	v_mfma_f32_16x16x32_bf16 v[120:123], v[176:179], v[206:209], v[120:123]
	v_mfma_f32_16x16x32_bf16 v[108:111], v[168:171], v[214:217], v[108:111]
	v_mfma_f32_16x16x32_bf16 v[104:107], v[176:179], v[214:217], v[104:107]
	v_mfma_f32_16x16x32_bf16 v[92:95], v[168:171], v[222:225], v[92:95]
	v_mfma_f32_16x16x32_bf16 v[88:91], v[176:179], v[222:225], v[88:91]
	v_mfma_f32_16x16x32_bf16 v[76:79], v[168:171], v[230:233], v[76:79]
	v_mfma_f32_16x16x32_bf16 v[72:75], v[176:179], v[230:233], v[72:75]
	v_mfma_f32_16x16x32_bf16 v[116:119], v[180:183], v[202:205], v[116:119]
	v_mfma_f32_16x16x32_bf16 v[112:115], v[188:191], v[202:205], v[112:115]
	v_mfma_f32_16x16x32_bf16 v[100:103], v[180:183], v[210:213], v[100:103]
	v_mfma_f32_16x16x32_bf16 v[96:99], v[188:191], v[210:213], v[96:99]
	v_mfma_f32_16x16x32_bf16 v[84:87], v[180:183], v[218:221], v[84:87]
	v_mfma_f32_16x16x32_bf16 v[80:83], v[188:191], v[218:221], v[80:83]
	v_mfma_f32_16x16x32_bf16 v[68:71], v[180:183], v[226:229], v[68:71]
	v_mfma_f32_16x16x32_bf16 v[64:67], v[188:191], v[226:229], v[64:67]
	v_mfma_f32_16x16x32_bf16 v[116:119], v[184:187], v[206:209], v[116:119]
	v_mfma_f32_16x16x32_bf16 v[112:115], v[198:201], v[206:209], v[112:115]
	v_mfma_f32_16x16x32_bf16 v[100:103], v[184:187], v[214:217], v[100:103]
	v_mfma_f32_16x16x32_bf16 v[96:99], v[198:201], v[214:217], v[96:99]
	v_mfma_f32_16x16x32_bf16 v[84:87], v[184:187], v[222:225], v[84:87]
	v_mfma_f32_16x16x32_bf16 v[80:83], v[198:201], v[222:225], v[80:83]
	v_mfma_f32_16x16x32_bf16 v[68:71], v[184:187], v[230:233], v[68:71]
	v_mfma_f32_16x16x32_bf16 v[64:67], v[198:201], v[230:233], v[64:67]
	s_barrier
	s_add_i32 s6, s48, s57
	s_add_u32 s98, s52, 0x80
	s_addc_u32 s99, s53, 0
	s_add_u32 s100, s54, 0x80
	s_addc_u32 s101, s55, 0
	s_mov_b32 m0, s6
	ds_read_b128 v[202:205], v155 offset:49152
	ds_read_b128 v[206:209], v155 offset:50176
	ds_read_b128 v[210:213], v155 offset:51200
	ds_read_b128 v[214:217], v155 offset:52224
	global_load_lds_dwordx4 v130, s[98:99]
	s_add_i32 m0, s6, 0x2000
	s_add_u32 s6, s52, 0xb0080
	s_addc_u32 s7, s53, 0
	s_add_i32 s48, s49, s57
	global_load_lds_dwordx4 v134, s[98:99]
	s_mov_b32 m0, s48
	ds_read_b128 v[230:233], v155 offset:56320
	global_load_lds_dwordx4 v130, s[6:7]
	s_add_i32 m0, s48, 0x2000
	ds_read_b128 v[226:229], v155 offset:55296
	global_load_lds_dwordx4 v134, s[6:7]
	s_mov_b32 m0, s76
	ds_read_b128 v[222:225], v155 offset:54272
	global_load_lds_dwordx4 v128, s[100:101]
	s_mov_b32 m0, s4
	ds_read_b128 v[218:221], v155 offset:53248
	global_load_lds_dwordx4 v132, s[100:101]
	s_waitcnt vmcnt(8)
	s_waitcnt lgkmcnt(0)
	s_barrier
	s_waitcnt lgkmcnt(0)
	v_mfma_f32_16x16x32_bf16 v[60:63], v[144:147], v[202:205], v[60:63]
	v_mfma_f32_16x16x32_bf16 v[56:59], v[172:175], v[202:205], v[56:59]
	v_mfma_f32_16x16x32_bf16 v[44:47], v[144:147], v[210:213], v[44:47]
	v_mfma_f32_16x16x32_bf16 v[40:43], v[172:175], v[210:213], v[40:43]
	v_mfma_f32_16x16x32_bf16 v[28:31], v[144:147], v[218:221], v[28:31]
	v_mfma_f32_16x16x32_bf16 v[24:27], v[172:175], v[218:221], v[24:27]
	v_mfma_f32_16x16x32_bf16 v[12:15], v[144:147], v[226:229], v[12:15]
	v_mfma_f32_16x16x32_bf16 v[8:11], v[172:175], v[226:229], v[8:11]
	v_mfma_f32_16x16x32_bf16 v[60:63], v[168:171], v[206:209], v[60:63]
	v_mfma_f32_16x16x32_bf16 v[56:59], v[176:179], v[206:209], v[56:59]
	v_mfma_f32_16x16x32_bf16 v[44:47], v[168:171], v[214:217], v[44:47]
	v_mfma_f32_16x16x32_bf16 v[40:43], v[176:179], v[214:217], v[40:43]
	v_mfma_f32_16x16x32_bf16 v[28:31], v[168:171], v[222:225], v[28:31]
	v_mfma_f32_16x16x32_bf16 v[24:27], v[176:179], v[222:225], v[24:27]
	v_mfma_f32_16x16x32_bf16 v[12:15], v[168:171], v[230:233], v[12:15]
	v_mfma_f32_16x16x32_bf16 v[8:11], v[176:179], v[230:233], v[8:11]
	v_mfma_f32_16x16x32_bf16 v[52:55], v[180:183], v[202:205], v[52:55]
	v_mfma_f32_16x16x32_bf16 v[48:51], v[188:191], v[202:205], v[48:51]
	v_mfma_f32_16x16x32_bf16 v[36:39], v[180:183], v[210:213], v[36:39]
	v_mfma_f32_16x16x32_bf16 v[32:35], v[188:191], v[210:213], v[32:35]
	v_mfma_f32_16x16x32_bf16 v[20:23], v[180:183], v[218:221], v[20:23]
	v_mfma_f32_16x16x32_bf16 v[16:19], v[188:191], v[218:221], v[16:19]
	v_mfma_f32_16x16x32_bf16 v[4:7], v[180:183], v[226:229], v[4:7]
	v_mfma_f32_16x16x32_bf16 v[0:3], v[188:191], v[226:229], v[0:3]
	v_mfma_f32_16x16x32_bf16 v[52:55], v[184:187], v[206:209], v[52:55]
	v_mfma_f32_16x16x32_bf16 v[48:51], v[198:201], v[206:209], v[48:51]
	v_mfma_f32_16x16x32_bf16 v[36:39], v[184:187], v[214:217], v[36:39]
	v_mfma_f32_16x16x32_bf16 v[32:35], v[198:201], v[214:217], v[32:35]
	v_mfma_f32_16x16x32_bf16 v[20:23], v[184:187], v[222:225], v[20:23]
	v_mfma_f32_16x16x32_bf16 v[16:19], v[198:201], v[222:225], v[16:19]
	v_mfma_f32_16x16x32_bf16 v[4:7], v[184:187], v[230:233], v[4:7]
	v_mfma_f32_16x16x32_bf16 v[0:3], v[198:201], v[230:233], v[0:3]
	s_barrier
	s_add_i32 s72, s72, 2
	s_add_u32 s33, s33, 0x100
	s_addc_u32 s77, s77, 0
	s_cmp_gt_u32 s72, 41
	s_mov_b64 s[48:49], s[50:51]
	s_cbranch_scc0 .LBB0_1935
	s_and_b64 vcc, exec, s[38:39]
	s_cbranch_vccz .LBB0_1938
	s_barrier
